# attention softmax: pairs of v_fma_f32 (s*scale-m) -> v_pk_fma_f32 (bit-identical), 102 pairs
# speedup vs baseline: 1.0023x; 1.0023x over previous
; #define MFMA(a, b, c) __builtin_amdgcn_mfma_f32_32x32x16_bf16((a), (b), (c), 0, 0, 0)
; DI int kperm(int r) { return (r & 0x13) | ((r & 8) >> 1) | ((r & 4) << 1); }
; template <int DQK, bool MASKED, int MODE, class MF>
; DI void attn_step(const bf16_t* sK, const bf16_t* sVt, const bf16x8 (&qf)[DQK / 16], f32x16& o0, f32x16& o1, float& m, float& l,
;                   float sc, const MF& mf, int lane, f32x16 (&s)[2], float invl, bool lanevalid = true) {
;   const int r = lane & 31, h = lane >> 5;
;   const int pr = kperm(r);
;   constexpr int KST = DQK + 8;
;   bf16x8 kf[2][DQK / 16];
; #pragma unroll
;   for (int sub = 0; sub < 2; ++sub)
; #pragma unroll
;     for (int ks = 0; ks < DQK / 16; ++ks) kf[sub][ks] = *(const bf16x8*)(sK + (sub * 32 + pr) * KST + ks * 16 + 8 * h);
;   __builtin_amdgcn_sched_barrier(0);
; #pragma unroll
;   for (int q = 0; q < 16; ++q) { s[0][q] = 0.f; s[1][q] = 0.f; }
; #pragma unroll
;   for (int ks = 0; ks < DQK / 16; ++ks) {
;     s[0] = MFMA(kf[0][ks], qf[ks], s[0]);
;     s[1] = MFMA(kf[1][ks], qf[ks], s[1]);
;   }
;   bf16x8 vf[2][2][2];
;   if (MODE != 1) {
; #pragma unroll
;     for (int sub = 0; sub < 2; ++sub)
; #pragma unroll
;       for (int s2 = 0; s2 < 2; ++s2) {
;         vf[sub][s2][0] = *(const bf16x8*)(sVt + r * 72 + sub * 32 + s2 * 16 + 8 * h);
;         vf[sub][s2][1] = *(const bf16x8*)(sVt + (32 + r) * 72 + sub * 32 + s2 * 16 + 8 * h);
;       }
;     __builtin_amdgcn_sched_barrier(0);
;   }
;   float mxr = -3.0e38f;
; #pragma unroll
;   for (int sub = 0; sub < 2; ++sub)
; #pragma unroll
;     for (int q = 0; q < 16; ++q) {
;       if (MASKED) { const int kk = sub * 32 + 16 * (q >> 3) + 8 * h + (q & 7); s[sub][q] = mf(kk) ? s[sub][q] : -3.0e38f; }
;       if (MODE != 2) mxr = fmaxf(mxr, s[sub][q]);
; DI void phase_attn_swa(const Params& P, const float* sinks, bf16_t* og, unsigned char* smem, int L, int G) {
;     ...
;       auto mf = [&](int kk) { const int key = key0 + kk; return key <= t && key > t - 128; };
;       attn_step<64, true, 0>(sK + cb * KVB64, sVt + cb * KVB64, qf, o0, o1, m, l, sc, mf, lane, s, 0.f);
.LBB0_350:
	s_mulk_i32 s0, 0x4800
	v_add_u32_e32 v40, s0, v163
	ds_read_b128 v[32:35], v40
	ds_read_b128 v[96:99], v40 offset:32
	ds_read_b128 v[100:103], v40 offset:64
	ds_read_b128 v[104:107], v40 offset:96
	ds_read_b128 v[36:39], v40 offset:4608
	ds_read_b128 v[108:111], v40 offset:4640
	ds_read_b128 v[112:115], v40 offset:4672
	ds_read_b128 v[178:181], v40 offset:4704
	v_add_u32_e32 v116, s0, v137
	s_waitcnt lgkmcnt(7)
	v_mfma_f32_32x32x16_bf16 v[48:63], v[32:35], v[64:67], 0
	s_waitcnt lgkmcnt(3)
	v_mfma_f32_32x32x16_bf16 v[32:47], v[36:39], v[64:67], 0
	v_mfma_f32_32x32x16_bf16 v[48:63], v[96:99], v[68:71], v[48:63]
	v_add3_u32 v96, v116, v164, v171
	v_add3_u32 v97, v116, v165, v171
	s_waitcnt lgkmcnt(2)
	v_mfma_f32_32x32x16_bf16 v[32:47], v[108:111], v[68:71], v[32:47]
	v_mfma_f32_32x32x16_bf16 v[48:63], v[100:103], v[72:75], v[48:63]
	s_waitcnt lgkmcnt(1)
	v_mfma_f32_32x32x16_bf16 v[32:47], v[112:115], v[72:75], v[32:47]
	v_mfma_f32_32x32x16_bf16 v[48:63], v[104:107], v[76:79], v[48:63]
	ds_read_b128 v[124:127], v96 offset:9216
	ds_read_b128 v[116:119], v96 offset:9248
	ds_read_b128 v[120:123], v97 offset:9216
	ds_read_b128 v[112:115], v97 offset:9248
	ds_read_b128 v[108:111], v96 offset:9280
	ds_read_b128 v[100:103], v96 offset:9312
	ds_read_b128 v[104:107], v97 offset:9280
	ds_read_b128 v[96:99], v97 offset:9312
	s_waitcnt lgkmcnt(8)
	v_mfma_f32_32x32x16_bf16 v[32:47], v[178:181], v[76:79], v[32:47]
	v_add_u32_e32 v128, s38, v162
	v_cmp_le_u32_e32 vcc, v128, v150
	v_cmp_gt_i32_e64 s[0:1], v128, v151
	s_and_b64 vcc, vcc, s[0:1]
	v_cndmask_b32_e32 v48, v172, v48, vcc
	v_cmp_lt_u32_e32 vcc, v128, v150
	v_cmp_ge_i32_e64 s[0:1], v128, v151
	s_and_b64 vcc, vcc, s[0:1]
	v_add_u32_e32 v177, 2, v128
	v_cndmask_b32_e32 v49, v172, v49, vcc
	v_cmp_le_u32_e32 vcc, v177, v150
	v_cmp_gt_i32_e64 s[0:1], v177, v151
	s_and_b64 vcc, vcc, s[0:1]
	v_add_u32_e32 v177, 3, v128
	v_cndmask_b32_e32 v50, v172, v50, vcc
	v_cmp_le_u32_e32 vcc, v177, v150
	v_cmp_gt_i32_e64 s[0:1], v177, v151
	s_and_b64 vcc, vcc, s[0:1]
	v_add_u32_e32 v177, 4, v128
	v_cndmask_b32_e32 v51, v172, v51, vcc
	v_cmp_le_u32_e32 vcc, v177, v150
	v_cmp_gt_i32_e64 s[0:1], v177, v151
	s_and_b64 vcc, vcc, s[0:1]
	v_add_u32_e32 v177, 5, v128
	v_cndmask_b32_e32 v52, v172, v52, vcc
	v_cmp_le_u32_e32 vcc, v177, v150
	v_cmp_gt_i32_e64 s[0:1], v177, v151
	s_and_b64 vcc, vcc, s[0:1]
	v_add_u32_e32 v177, 6, v128
	v_cndmask_b32_e32 v53, v172, v53, vcc
	v_cmp_le_u32_e32 vcc, v177, v150
	v_cmp_gt_i32_e64 s[0:1], v177, v151
	v_add_u32_e32 v177, s38, v161
	s_and_b64 vcc, vcc, s[0:1]
	v_or_b32_e32 v178, 7, v177
	v_cndmask_b32_e32 v54, v172, v54, vcc
	v_cmp_le_u32_e32 vcc, v178, v150
	v_cmp_gt_i32_e64 s[0:1], v178, v151
	s_and_b64 vcc, vcc, s[0:1]
	v_add_u32_e32 v178, 16, v128
	v_cndmask_b32_e32 v55, v172, v55, vcc
	v_cmp_le_u32_e32 vcc, v178, v150
	v_cmp_gt_i32_e64 s[0:1], v178, v151
	s_and_b64 vcc, vcc, s[0:1]
	v_add_u32_e32 v178, 17, v128
	v_cndmask_b32_e32 v56, v172, v56, vcc
	v_cmp_le_u32_e32 vcc, v178, v150
	v_cmp_gt_i32_e64 s[0:1], v178, v151
	s_and_b64 vcc, vcc, s[0:1]
	v_add_u32_e32 v178, 18, v128
	v_cndmask_b32_e32 v57, v172, v57, vcc
	v_cmp_le_u32_e32 vcc, v178, v150
	v_cmp_gt_i32_e64 s[0:1], v178, v151
	s_and_b64 vcc, vcc, s[0:1]
	v_add_u32_e32 v178, 19, v128
	v_cndmask_b32_e32 v58, v172, v58, vcc
	v_cmp_le_u32_e32 vcc, v178, v150
	v_cmp_gt_i32_e64 s[0:1], v178, v151
	s_and_b64 vcc, vcc, s[0:1]
	v_add_u32_e32 v178, 20, v128
	v_cndmask_b32_e32 v59, v172, v59, vcc
	v_cmp_le_u32_e32 vcc, v178, v150
	v_cmp_gt_i32_e64 s[0:1], v178, v151
	s_and_b64 vcc, vcc, s[0:1]
	v_add_u32_e32 v178, 21, v128
	v_cndmask_b32_e32 v60, v172, v60, vcc
	v_cmp_le_u32_e32 vcc, v178, v150
	v_cmp_gt_i32_e64 s[0:1], v178, v151
	s_and_b64 vcc, vcc, s[0:1]
	v_add_u32_e32 v178, 22, v128
	v_cndmask_b32_e32 v61, v172, v61, vcc
	v_cmp_le_u32_e32 vcc, v178, v150
	v_cmp_gt_i32_e64 s[0:1], v178, v151
	s_and_b64 vcc, vcc, s[0:1]
	v_or_b32_e32 v178, 23, v177
	v_cndmask_b32_e32 v62, v172, v62, vcc
	v_cmp_le_u32_e32 vcc, v178, v150
	v_cmp_gt_i32_e64 s[0:1], v178, v151
	s_and_b64 vcc, vcc, s[0:1]
	v_add_u32_e32 v178, 32, v128
	v_cndmask_b32_e32 v63, v172, v63, vcc
	v_cmp_le_u32_e32 vcc, v178, v150
	v_cmp_gt_i32_e64 s[0:1], v178, v151
	s_and_b64 vcc, vcc, s[0:1]
	v_cndmask_b32_e32 v178, v172, v32, vcc
	v_add_u32_e32 v32, 33, v128
	v_cmp_le_u32_e32 vcc, v32, v150
	v_cmp_gt_i32_e64 s[0:1], v32, v151
	s_and_b64 vcc, vcc, s[0:1]
	v_add_u32_e32 v32, 34, v128
	v_cndmask_b32_e32 v33, v172, v33, vcc
	v_cmp_le_u32_e32 vcc, v32, v150
	v_cmp_gt_i32_e64 s[0:1], v32, v151
	s_and_b64 vcc, vcc, s[0:1]
	v_add_u32_e32 v32, 35, v128
	v_cndmask_b32_e32 v34, v172, v34, vcc
	v_cmp_le_u32_e32 vcc, v32, v150
	v_cmp_gt_i32_e64 s[0:1], v32, v151
	s_and_b64 vcc, vcc, s[0:1]
	v_add_u32_e32 v32, 36, v128
	v_cndmask_b32_e32 v35, v172, v35, vcc
	v_cmp_le_u32_e32 vcc, v32, v150
	v_cmp_gt_i32_e64 s[0:1], v32, v151
	s_and_b64 vcc, vcc, s[0:1]
	v_add_u32_e32 v32, 37, v128
	v_cndmask_b32_e32 v36, v172, v36, vcc
	v_cmp_le_u32_e32 vcc, v32, v150
	v_cmp_gt_i32_e64 s[0:1], v32, v151
	s_and_b64 vcc, vcc, s[0:1]
	v_add_u32_e32 v32, 38, v128
	v_cndmask_b32_e32 v37, v172, v37, vcc
	v_cmp_le_u32_e32 vcc, v32, v150
	v_cmp_gt_i32_e64 s[0:1], v32, v151
	s_and_b64 vcc, vcc, s[0:1]
	v_or_b32_e32 v32, 39, v177
	v_cndmask_b32_e32 v38, v172, v38, vcc
	v_cmp_le_u32_e32 vcc, v32, v150
	v_cmp_gt_i32_e64 s[0:1], v32, v151
	s_and_b64 vcc, vcc, s[0:1]
	v_add_u32_e32 v32, 48, v128
	v_cndmask_b32_e32 v39, v172, v39, vcc
	v_cmp_le_u32_e32 vcc, v32, v150
	v_cmp_gt_i32_e64 s[0:1], v32, v151
	s_and_b64 vcc, vcc, s[0:1]
	v_add_u32_e32 v32, 49, v128
	v_cndmask_b32_e32 v179, v172, v40, vcc
; #define MFMA(a, b, c) __builtin_amdgcn_mfma_f32_32x32x16_bf16((a), (b), (c), 0, 0, 0)
; DI unsigned pack2(float a, float b) { f32x2_t v = {a, b}; bf16x2_t r = __builtin_convertvector(v, bf16x2_t); return __builtin_bit_cast(unsigned, r); }
; DI float fexp2(float x) { return __builtin_amdgcn_exp2f(x); }
; DI float shx(float v, int m) { return __shfl_xor(v, m, 64); }
; template <int DQK, bool MASKED, int MODE, class MF>
; DI void attn_step(const bf16_t* sK, const bf16_t* sVt, const bf16x8 (&qf)[DQK / 16], f32x16& o0, f32x16& o1, float& m, float& l,
;                   float sc, const MF& mf, int lane, f32x16 (&s)[2], float invl, bool lanevalid = true) {
;     ...
;   float mxr = -3.0e38f;
; #pragma unroll
;   for (int sub = 0; sub < 2; ++sub)
; #pragma unroll
;     for (int q = 0; q < 16; ++q) {
;       if (MASKED) { const int kk = sub * 32 + 16 * (q >> 3) + 8 * h + (q & 7); s[sub][q] = mf(kk) ? s[sub][q] : -3.0e38f; }
;       if (MODE != 2) mxr = fmaxf(mxr, s[sub][q]);
;     }
;   float alpha = 1.f;
;   if (MODE != 2) {
;     float mx = fmaxf(m, mxr * sc);
;     mx = fmaxf(mx, shx(mx, 32));
;     if (!MASKED) mx = lanevalid ? mx : m;
;     alpha = fexp2(m - mx);
;     m = mx;
;   }
;   const float moff = (!MASKED && !lanevalid) ? 1.0e30f : m;
;   float ps = 0.f;
; #pragma unroll
;   for (int sub = 0; sub < 2; ++sub)
; #pragma unroll
;     for (int q = 0; q < 16; ++q) {
;       float pv = fexp2(__builtin_fmaf(s[sub][q], sc, -moff));
;       if (MASKED && MODE != 0) pv = (s[sub][q] > -1.0e38f) ? pv : 0.f;
;       if (MODE == 2) pv *= invl;
;       s[sub][q] = pv;
;       ps += pv;
;     }
;   if (MODE != 2) {
;     ps += shx(ps, 32);
;     l = l * alpha + ps;
;   }
;   if (MODE == 1) return;
;   if (MODE == 0) {
; #pragma unroll
;     for (int q = 0; q < 16; ++q) { o0[q] *= alpha; o1[q] *= alpha; }
;   }
; #pragma unroll
;   for (int sub = 0; sub < 2; ++sub)
; #pragma unroll
;     for (int s2 = 0; s2 < 2; ++s2) {
;       union { bf16x8 v; unsigned u[4]; } pb;
; #pragma unroll
;       for (int e = 0; e < 4; ++e) pb.u[e] = pack2(s[sub][8 * s2 + 2 * e], s[sub][8 * s2 + 2 * e + 1]);
;       o0 = MFMA(vf[sub][s2][0], pb.v, o0);
;       o1 = MFMA(vf[sub][s2][1], pb.v, o1);
;     }
	v_cmp_le_u32_e32 vcc, v32, v150
	v_cmp_gt_i32_e64 s[0:1], v32, v151
	s_and_b64 vcc, vcc, s[0:1]
	v_add_u32_e32 v32, 50, v128
	v_cndmask_b32_e32 v41, v172, v41, vcc
	v_cmp_le_u32_e32 vcc, v32, v150
	v_cmp_gt_i32_e64 s[0:1], v32, v151
	s_and_b64 vcc, vcc, s[0:1]
	v_add_u32_e32 v32, 51, v128
	v_cndmask_b32_e32 v42, v172, v42, vcc
	v_cmp_le_u32_e32 vcc, v32, v150
	v_cmp_gt_i32_e64 s[0:1], v32, v151
	s_and_b64 vcc, vcc, s[0:1]
	v_add_u32_e32 v32, 52, v128
	v_cndmask_b32_e32 v43, v172, v43, vcc
	v_cmp_le_u32_e32 vcc, v32, v150
	v_cmp_gt_i32_e64 s[0:1], v32, v151
	s_and_b64 vcc, vcc, s[0:1]
	v_add_u32_e32 v32, 53, v128
	v_cndmask_b32_e32 v44, v172, v44, vcc
	v_cmp_le_u32_e32 vcc, v32, v150
	v_cmp_gt_i32_e64 s[0:1], v32, v151
	s_and_b64 vcc, vcc, s[0:1]
	v_add_u32_e32 v32, 54, v128
	v_cndmask_b32_e32 v45, v172, v45, vcc
	v_cmp_le_u32_e32 vcc, v32, v150
	v_cmp_gt_i32_e64 s[0:1], v32, v151
	s_and_b64 vcc, vcc, s[0:1]
	v_or_b32_e32 v32, 55, v177
	v_cndmask_b32_e32 v46, v172, v46, vcc
	v_cmp_le_u32_e32 vcc, v32, v150
	v_cmp_gt_i32_e64 s[0:1], v32, v151
	v_max3_f32 v32, v48, s43, v49
	v_max3_f32 v32, v32, v50, v51
	v_max3_f32 v32, v32, v52, v53
	v_max3_f32 v32, v32, v54, v55
	v_max3_f32 v32, v32, v56, v57
	v_max3_f32 v32, v32, v58, v59
	v_max3_f32 v32, v32, v60, v61
	v_max3_f32 v32, v32, v62, v63
	v_max3_f32 v32, v32, v178, v33
	v_max3_f32 v32, v32, v34, v35
	v_max3_f32 v32, v32, v36, v37
	v_max3_f32 v32, v32, v38, v39
	v_max3_f32 v32, v32, v179, v41
	s_and_b64 vcc, vcc, s[0:1]
	v_max3_f32 v32, v32, v42, v43
	v_cndmask_b32_e32 v47, v172, v47, vcc
	v_max3_f32 v32, v32, v44, v45
	v_max3_f32 v32, v32, v46, v47
	v_mul_f32_e32 v32, 0x3e38aa3b, v32
	v_max_f32_e32 v40, v176, v176
	v_max_f32_e32 v32, v40, v32
	ds_bpermute_b32 v40, v174, v32
	s_add_i32 s47, s47, 1
	s_add_i32 s0, s46, s47
	s_add_i32 s38, s38, 64
	s_add_i32 s0, s0, -1
	s_waitcnt lgkmcnt(0)
	v_max_f32_e32 v40, v40, v40
	v_max_f32_e32 v32, v32, v40
	v_fma_f32 v40, v48, s44, -v32
	v_exp_f32_e32 v48, v40
	v_fma_f32 v49, v49, s44, -v32
	v_exp_f32_e32 v49, v49
	v_fma_f32 v50, v50, s44, -v32
	v_exp_f32_e32 v50, v50
	v_fma_f32 v51, v51, s44, -v32
	v_exp_f32_e32 v51, v51
	v_fma_f32 v52, v52, s44, -v32
	v_add_f32_e32 v128, 0, v48
	v_exp_f32_e32 v52, v52
	v_fma_f32 v53, v53, s44, -v32
	v_add_f32_e32 v128, v49, v128
	v_exp_f32_e32 v53, v53
	v_fma_f32 v54, v54, s44, -v32
	v_add_f32_e32 v128, v50, v128
	v_exp_f32_e32 v54, v54
	v_fma_f32 v55, v55, s44, -v32
	v_add_f32_e32 v128, v51, v128
	v_exp_f32_e32 v55, v55
	v_fma_f32 v56, v56, s44, -v32
	v_add_f32_e32 v128, v52, v128
	v_exp_f32_e32 v56, v56
	v_fma_f32 v57, v57, s44, -v32
	v_add_f32_e32 v128, v53, v128
	v_exp_f32_e32 v57, v57
	v_fma_f32 v58, v58, s44, -v32
	v_add_f32_e32 v128, v54, v128
	v_exp_f32_e32 v58, v58
	v_fma_f32 v59, v59, s44, -v32
	v_add_f32_e32 v128, v55, v128
	v_exp_f32_e32 v59, v59
	v_fma_f32 v60, v60, s44, -v32
	v_add_f32_e32 v128, v56, v128
	v_exp_f32_e32 v60, v60
	v_fma_f32 v61, v61, s44, -v32
	v_add_f32_e32 v128, v57, v128
	v_exp_f32_e32 v61, v61
	v_fma_f32 v62, v62, s44, -v32
	v_add_f32_e32 v128, v58, v128
	v_exp_f32_e32 v62, v62
	v_fma_f32 v63, v63, s44, -v32
	v_sub_f32_e32 v40, v176, v32
	v_add_f32_e32 v128, v59, v128
	v_exp_f32_e32 v63, v63
	v_fma_f32 v176, v178, s44, -v32
	v_add_f32_e32 v128, v60, v128
	v_exp_f32_e32 v176, v176
	v_fma_f32 v33, v33, s44, -v32
	v_add_f32_e32 v128, v61, v128
	v_exp_f32_e32 v33, v33
	s_nop 0
	v_pk_fma_f32 v[184:185], v[34:35], s[44:45], v[32:33] op_sel:[0,0,0] op_sel_hi:[1,0,0] neg_lo:[0,0,1] neg_hi:[0,0,1]
	v_add_f32_e32 v128, v62, v128
	v_exp_f32_e32 v177, v184
	v_add_f32_e32 v128, v63, v128
	v_exp_f32_e32 v178, v185
	v_pk_fma_f32 v[184:185], v[36:37], s[44:45], v[32:33] op_sel:[0,0,0] op_sel_hi:[1,0,0] neg_lo:[0,0,1] neg_hi:[0,0,1]
	v_add_f32_e32 v128, v176, v128
	v_exp_f32_e32 v180, v184
	v_add_f32_e32 v34, v33, v128
	v_exp_f32_e32 v128, v185
	v_fma_f32 v35, v38, s44, -v32
	v_add_f32_e32 v34, v177, v34
	v_exp_f32_e32 v38, v35
	v_fma_f32 v35, v39, s44, -v32
	v_add_f32_e32 v34, v178, v34
	v_exp_f32_e32 v39, v35
	v_add_f32_e32 v34, v180, v34
	v_exp_f32_e32 v40, v40
	v_add_f32_e32 v34, v128, v34
	v_add_f32_e32 v34, v38, v34
	v_add_f32_e32 v181, v39, v34
	v_fma_f32 v34, v179, s44, -v32
	v_exp_f32_e32 v179, v34
	v_pk_mul_f32 v[14:15], v[14:15], v[40:41] op_sel_hi:[1,0]
	v_pk_mul_f32 v[12:13], v[12:13], v[40:41] op_sel_hi:[1,0]
	v_pk_mul_f32 v[10:11], v[10:11], v[40:41] op_sel_hi:[1,0]
	v_pk_mul_f32 v[8:9], v[8:9], v[40:41] op_sel_hi:[1,0]
	v_pk_mul_f32 v[6:7], v[6:7], v[40:41] op_sel_hi:[1,0]
	v_pk_mul_f32 v[4:5], v[4:5], v[40:41] op_sel_hi:[1,0]
	v_pk_mul_f32 v[2:3], v[2:3], v[40:41] op_sel_hi:[1,0]
	v_pk_mul_f32 v[0:1], v[0:1], v[40:41] op_sel_hi:[1,0]
	v_pk_mul_f32 v[30:31], v[30:31], v[40:41] op_sel_hi:[1,0]
	v_cvt_pk_bf16_f32 v34, v48, v49
	v_cvt_pk_bf16_f32 v35, v50, v51
	v_cvt_pk_bf16_f32 v36, v52, v53
	v_cvt_pk_bf16_f32 v37, v54, v55
	v_pk_mul_f32 v[28:29], v[28:29], v[40:41] op_sel_hi:[1,0]
	v_pk_mul_f32 v[26:27], v[26:27], v[40:41] op_sel_hi:[1,0]
	v_pk_mul_f32 v[24:25], v[24:25], v[40:41] op_sel_hi:[1,0]
	v_pk_mul_f32 v[22:23], v[22:23], v[40:41] op_sel_hi:[1,0]
	v_pk_mul_f32 v[20:21], v[20:21], v[40:41] op_sel_hi:[1,0]
	v_pk_mul_f32 v[18:19], v[18:19], v[40:41] op_sel_hi:[1,0]
	v_pk_mul_f32 v[16:17], v[16:17], v[40:41] op_sel_hi:[1,0]
	v_mfma_f32_32x32x16_bf16 v[0:15], v[124:127], v[34:37], v[0:15]
	v_fma_f32 v42, v42, s44, -v32
	v_exp_f32_e32 v42, v42
	v_fma_f32 v43, v43, s44, -v32
	v_exp_f32_e32 v43, v43
	v_fma_f32 v44, v44, s44, -v32
	v_add_f32_e32 v48, v179, v181
	v_exp_f32_e32 v44, v44
	v_mfma_f32_32x32x16_bf16 v[16:31], v[120:123], v[34:37], v[16:31]
	v_fma_f32 v34, v41, s44, -v32
	v_exp_f32_e32 v41, v34
	v_cvt_pk_bf16_f32 v34, v56, v57
	v_cvt_pk_bf16_f32 v35, v58, v59
	v_cvt_pk_bf16_f32 v36, v60, v61
	v_cvt_pk_bf16_f32 v37, v62, v63
	v_add_f32_e32 v48, v41, v48
	s_cmp_ge_u32 s0, s41
	v_mfma_f32_32x32x16_bf16 v[0:15], v[116:119], v[34:37], v[0:15]
	v_mfma_f32_32x32x16_bf16 v[16:31], v[112:115], v[34:37], v[16:31]
	v_add_f32_e32 v34, v42, v48
	v_add_f32_e32 v34, v43, v34
	v_add_f32_e32 v48, v44, v34
	v_cvt_pk_bf16_f32 v34, v176, v33
	v_cvt_pk_bf16_f32 v35, v177, v178
	v_cvt_pk_bf16_f32 v36, v180, v128
	v_cvt_pk_bf16_f32 v37, v38, v39
	v_fma_f32 v33, v45, s44, -v32
	v_pk_fma_f32 v[184:185], v[46:47], s[44:45], v[32:33] op_sel:[0,0,0] op_sel_hi:[1,0,0] neg_lo:[0,0,1] neg_hi:[0,0,1]
	v_mfma_f32_32x32x16_bf16 v[0:15], v[108:111], v[34:37], v[0:15]
	v_exp_f32_e32 v33, v33
	v_exp_f32_e32 v39, v184
	v_exp_f32_e32 v45, v185
	v_add_f32_e32 v38, v33, v48
	v_mfma_f32_32x32x16_bf16 v[16:31], v[104:107], v[34:37], v[16:31]
	v_add_f32_e32 v34, v39, v38
	v_cvt_pk_bf16_f32 v36, v179, v41
	v_cvt_pk_bf16_f32 v37, v42, v43
	v_cvt_pk_bf16_f32 v38, v44, v33
	v_cvt_pk_bf16_f32 v39, v39, v45
	v_add_f32_e32 v34, v45, v34
	ds_bpermute_b32 v35, v174, v34
	v_mfma_f32_32x32x16_bf16 v[0:15], v[100:103], v[36:39], v[0:15]
	s_waitcnt lgkmcnt(0)
	v_add_f32_e32 v34, v34, v35
	v_fmac_f32_e32 v34, v175, v40
	v_mfma_f32_32x32x16_bf16 v[16:31], v[96:99], v[36:39], v[16:31]
	s_cbranch_scc1 .LBB0_337
; DI void phase_attn_swa(const Params& P, const float* sinks, bf16_t* og, unsigned char* smem, int L, int G) {
;     ...
;     for (int j = jlo; j <= jhi; ++j) {
;       const int key0 = j * 64, cb = (j - jlo) & 1;
;       __syncthreads();
;       if (j < jhi) kv64_store(R, sK + (cb ^ 1) * KVB64, sVt + (cb ^ 1) * KVB64, tid);
;       if (j + 1 < jhi) kv64_fetch(R, kb, 256, vb, SEQ, key0 + 128, true, tid);
;       __builtin_amdgcn_sched_barrier(0);
;       auto mf = [&](int kk) { const int key = key0 + kk; return key <= t && key > t - 128; };
;       attn_step<64, true, 0>(sK + cb * KVB64, sVt + cb * KVB64, qf, o0, o1, m, l, sc, mf, lane, s, 0.f);
;     }
	v_mov_b32_e32 v175, v34
	v_mov_b32_e32 v176, v32
	s_branch .LBB0_346

; template <int DQK, bool MASKED, int MODE, class MF>
; DI void attn_step(const bf16_t* sK, const bf16_t* sVt, const bf16x8 (&qf)[DQK / 16], f32x16& o0, f32x16& o1, float& m, float& l,
;                   float sc, const MF& mf, int lane, f32x16 (&s)[2], float invl, bool lanevalid = true) {
;   const int r = lane & 31, h = lane >> 5;
;   const int pr = kperm(r);
;   constexpr int KST = DQK + 8;
;   bf16x8 kf[2][DQK / 16];
; #pragma unroll
;   for (int sub = 0; sub < 2; ++sub)
; #pragma unroll
;     for (int ks = 0; ks < DQK / 16; ++ks) kf[sub][ks] = *(const bf16x8*)(sK + (sub * 32 + pr) * KST + ks * 16 + 8 * h);
;   __builtin_amdgcn_sched_barrier(0);
; #pragma unroll
;   for (int q = 0; q < 16; ++q) { s[0][q] = 0.f; s[1][q] = 0.f; }
; #pragma unroll
;   for (int ks = 0; ks < DQK / 16; ++ks) {
;     s[0] = MFMA(kf[0][ks], qf[ks], s[0]);
;     s[1] = MFMA(kf[1][ks], qf[ks], s[1]);
;   }
;   bf16x8 vf[2][2][2];
;   if (MODE != 1) {
; #pragma unroll
;     for (int sub = 0; sub < 2; ++sub)
; #pragma unroll
;       for (int s2 = 0; s2 < 2; ++s2) {
;         vf[sub][s2][0] = *(const bf16x8*)(sVt + r * 72 + sub * 32 + s2 * 16 + 8 * h);
;         vf[sub][s2][1] = *(const bf16x8*)(sVt + (32 + r) * 72 + sub * 32 + s2 * 16 + 8 * h);
;       }
;     __builtin_amdgcn_sched_barrier(0);
;   }
;   float mxr = -3.0e38f;
; #pragma unroll
;   for (int sub = 0; sub < 2; ++sub)
; #pragma unroll
;     for (int q = 0; q < 16; ++q) {
;       if (MASKED) { const int kk = sub * 32 + 16 * (q >> 3) + 8 * h + (q & 7); s[sub][q] = mf(kk) ? s[sub][q] : -3.0e38f; }
;       if (MODE != 2) mxr = fmaxf(mxr, s[sub][q]);
;     }
;   float alpha = 1.f;
;   if (MODE != 2) {
;     float mx = fmaxf(m, mxr * sc);
;     mx = fmaxf(mx, shx(mx, 32));
;     if (!MASKED) mx = lanevalid ? mx : m;
;     alpha = fexp2(m - mx);
;     m = mx;
;   }
;   const float moff = (!MASKED && !lanevalid) ? 1.0e30f : m;
;   float ps = 0.f;
; #pragma unroll
;   for (int sub = 0; sub < 2; ++sub)
; #pragma unroll
;     for (int q = 0; q < 16; ++q) {
;       float pv = fexp2(__builtin_fmaf(s[sub][q], sc, -moff));
;       if (MASKED && MODE != 0) pv = (s[sub][q] > -1.0e38f) ? pv : 0.f;
;       if (MODE == 2) pv *= invl;
;       s[sub][q] = pv;
;       ps += pv;
;     }
;   if (MODE != 2) {
;     ps += shx(ps, 32);
;     l = l * alpha + ps;
;   }
;   if (MODE == 1) return;
;   if (MODE == 0) {
; #pragma unroll
.LBB0_785:
	v_cmp_le_i32_e32 vcc, s14, v163
	s_and_saveexec_b64 s[22:23], vcc
	s_cbranch_execz .LBB0_791
	s_add_i32 s24, s14, 63
	s_mulk_i32 s40, 0x2c00
	v_cmp_le_i32_e32 vcc, s24, v162
	s_lshl_b32 s39, s40, 1
	v_max_f32_e32 v0, v186, v186
	s_and_saveexec_b64 s[24:25], vcc
	s_xor_b64 s[24:25], exec, s[24:25]
	s_cbranch_execz .LBB0_788
	v_lshl_add_u32 v14, s40, 1, v143
	ds_read_b128 v[2:5], v14
	ds_read_b128 v[6:9], v14 offset:32
	ds_read_b128 v[10:13], v14 offset:64
	ds_read_b128 v[116:119], v14 offset:96
	ds_read_b128 v[120:123], v14 offset:128
	ds_read_b128 v[124:127], v14 offset:160
	ds_read_b128 v[48:51], v14 offset:6656
	ds_read_b128 v[128:131], v14 offset:6688
	ds_read_b128 v[132:135], v14 offset:6720
	ds_read_b128 v[188:191], v14 offset:6752
	ds_read_b128 v[194:197], v14 offset:6784
	ds_read_b128 v[198:201], v14 offset:6816
	s_waitcnt lgkmcnt(11)
	v_mfma_f32_32x32x16_bf16 v[64:79], v[2:5], v[100:103], 0
	v_add3_u32 v2, s39, v172, v156
	v_add3_u32 v3, s39, v173, v156
	s_waitcnt lgkmcnt(10)
	v_mfma_f32_32x32x16_bf16 v[64:79], v[6:9], v[80:83], v[64:79]
	s_waitcnt lgkmcnt(5)
	v_mfma_f32_32x32x16_bf16 v[48:63], v[48:51], v[100:103], 0
	v_mfma_f32_32x32x16_bf16 v[64:79], v[10:13], v[84:87], v[64:79]
	s_waitcnt lgkmcnt(4)
	v_mfma_f32_32x32x16_bf16 v[48:63], v[128:131], v[80:83], v[48:63]
	v_mfma_f32_32x32x16_bf16 v[64:79], v[116:119], v[88:91], v[64:79]
	s_waitcnt lgkmcnt(3)
	v_mfma_f32_32x32x16_bf16 v[48:63], v[132:135], v[84:87], v[48:63]
	v_mfma_f32_32x32x16_bf16 v[64:79], v[120:123], v[92:95], v[64:79]
	s_waitcnt lgkmcnt(2)
	v_mfma_f32_32x32x16_bf16 v[48:63], v[188:191], v[88:91], v[48:63]
	v_mfma_f32_32x32x16_bf16 v[64:79], v[124:127], v[96:99], v[64:79]
	ds_read_b128 v[132:135], v2 offset:13312
	ds_read_b128 v[124:127], v2 offset:13344
	ds_read_b128 v[128:131], v3 offset:13312
	ds_read_b128 v[120:123], v3 offset:13344
	ds_read_b128 v[116:119], v2 offset:13376
	ds_read_b128 v[6:9], v2 offset:13408
	ds_read_b128 v[10:13], v3 offset:13376
	ds_read_b128 v[2:5], v3 offset:13408
	s_waitcnt lgkmcnt(9)
	v_mfma_f32_32x32x16_bf16 v[48:63], v[194:197], v[92:95], v[48:63]
	s_waitcnt lgkmcnt(8)
	v_mfma_f32_32x32x16_bf16 v[48:63], v[198:201], v[96:99], v[48:63]
	v_max3_f32 v14, v64, s36, v65
	v_max3_f32 v14, v14, v66, v67
	v_max3_f32 v14, v14, v68, v69
	v_max3_f32 v14, v14, v70, v71
	v_max3_f32 v14, v14, v72, v73
	v_max3_f32 v14, v14, v74, v75
	v_max3_f32 v14, v14, v76, v77
	v_max3_f32 v14, v14, v78, v79
	s_nop 3
	v_max3_f32 v14, v14, v48, v49
	v_max3_f32 v14, v14, v50, v51
	v_max3_f32 v14, v14, v52, v53
	v_max3_f32 v14, v14, v54, v55
	v_max3_f32 v14, v14, v56, v57
	v_max3_f32 v14, v14, v58, v59
	v_max3_f32 v14, v14, v60, v61
	v_max3_f32 v14, v14, v62, v63
	v_mul_f32_e32 v14, 0x3e16c740, v14
	v_cmp_lt_i32_e32 vcc, v183, v184
	v_max_f32_e32 v0, v0, v14
	s_nop 0
	v_cndmask_b32_e32 v14, v182, v183, vcc
	v_lshlrev_b32_e32 v14, 2, v14
	ds_bpermute_b32 v15, v14, v0
	s_waitcnt lgkmcnt(0)
	v_max_f32_e32 v15, v15, v15
	v_max_f32_e32 v15, v0, v15
	v_pk_fma_f32 v[208:209], v[64:65], s[36:37], v[14:15] op_sel:[0,1,1] op_sel_hi:[1,1,1] neg_lo:[0,0,1] neg_hi:[0,0,1]
	v_exp_f32_e32 v65, v208
	v_exp_f32_e32 v64, v209
	v_fma_f32 v0, v66, s37, -v15
	v_exp_f32_e32 v66, v0
	v_fma_f32 v67, v67, s37, -v15
	v_exp_f32_e32 v67, v67
	v_fma_f32 v68, v68, s37, -v15
	v_sub_f32_e32 v0, v186, v15
	v_add_f32_e32 v186, 0, v65
	v_exp_f32_e32 v68, v68
	v_fma_f32 v69, v69, s37, -v15
	v_add_f32_e32 v186, v64, v186
	v_exp_f32_e32 v69, v69
	v_fma_f32 v70, v70, s37, -v15
	v_add_f32_e32 v186, v66, v186
	v_exp_f32_e32 v70, v70
	v_fma_f32 v71, v71, s37, -v15
	v_add_f32_e32 v186, v67, v186
	v_exp_f32_e32 v71, v71
	v_fma_f32 v72, v72, s37, -v15
	v_add_f32_e32 v186, v68, v186
	v_exp_f32_e32 v72, v72
	v_fma_f32 v73, v73, s37, -v15
	v_add_f32_e32 v186, v69, v186
	v_exp_f32_e32 v73, v73
	v_fma_f32 v74, v74, s37, -v15
	v_add_f32_e32 v186, v70, v186
	v_exp_f32_e32 v74, v74
	v_fma_f32 v75, v75, s37, -v15
	v_add_f32_e32 v186, v71, v186
	v_exp_f32_e32 v75, v75
	v_fma_f32 v76, v76, s37, -v15
	v_add_f32_e32 v186, v72, v186
	v_exp_f32_e32 v76, v76
	v_fma_f32 v77, v77, s37, -v15
	v_add_f32_e32 v186, v73, v186
	v_exp_f32_e32 v77, v77
	v_fma_f32 v78, v78, s37, -v15
	v_add_f32_e32 v186, v74, v186
	v_exp_f32_e32 v78, v78
	v_fma_f32 v79, v79, s37, -v15
	v_add_f32_e32 v186, v75, v186
	v_exp_f32_e32 v79, v79
	v_pk_fma_f32 v[206:207], v[48:49], s[36:37], v[14:15] op_sel:[0,1,1] op_sel_hi:[1,1,1] neg_lo:[0,0,1] neg_hi:[0,0,1]
	v_add_f32_e32 v186, v76, v186
	v_exp_f32_e32 v187, v206
	v_add_f32_e32 v186, v77, v186
	v_exp_f32_e32 v188, v207
	v_pk_fma_f32 v[206:207], v[50:51], s[36:37], v[14:15] op_sel:[0,1,1] op_sel_hi:[1,1,1] neg_lo:[0,0,1] neg_hi:[0,0,1]
	v_add_f32_e32 v186, v78, v186
	v_exp_f32_e32 v189, v206
	v_add_f32_e32 v48, v79, v186
	v_exp_f32_e32 v186, v207
	v_fma_f32 v49, v52, s37, -v15
	v_add_f32_e32 v48, v187, v48
	v_exp_f32_e32 v52, v49
	v_fma_f32 v49, v53, s37, -v15
	v_add_f32_e32 v48, v188, v48
	v_exp_f32_e32 v53, v49
	v_fma_f32 v49, v54, s37, -v15
	v_add_f32_e32 v48, v189, v48
	v_exp_f32_e32 v54, v49
	v_add_f32_e32 v48, v186, v48
	v_add_f32_e32 v48, v52, v48
	v_exp_f32_e32 v0, v0
	v_add_f32_e32 v48, v53, v48
	v_add_f32_e32 v190, v54, v48
	v_fma_f32 v48, v55, s37, -v15
	v_exp_f32_e32 v55, v48
	v_fma_f32 v48, v56, s37, -v15
	v_exp_f32_e32 v56, v48
	v_pk_mul_f32 v[46:47], v[46:47], v[0:1] op_sel_hi:[1,0]
	v_pk_mul_f32 v[44:45], v[44:45], v[0:1] op_sel_hi:[1,0]
	v_pk_mul_f32 v[42:43], v[42:43], v[0:1] op_sel_hi:[1,0]
	v_pk_mul_f32 v[40:41], v[40:41], v[0:1] op_sel_hi:[1,0]
	v_pk_mul_f32 v[38:39], v[38:39], v[0:1] op_sel_hi:[1,0]
	v_pk_mul_f32 v[36:37], v[36:37], v[0:1] op_sel_hi:[1,0]
; #define MFMA(a, b, c) __builtin_amdgcn_mfma_f32_32x32x16_bf16((a), (b), (c), 0, 0, 0)
; DI unsigned pack2(float a, float b) { f32x2_t v = {a, b}; bf16x2_t r = __builtin_convertvector(v, bf16x2_t); return __builtin_bit_cast(unsigned, r); }
; DI float shx(float v, int m) { return __shfl_xor(v, m, 64); }
; DI int kperm(int r) { return (r & 0x13) | ((r & 8) >> 1) | ((r & 4) << 1); }
; template <int DQK, bool MASKED, int MODE, class MF>
; DI void attn_step(const bf16_t* sK, const bf16_t* sVt, const bf16x8 (&qf)[DQK / 16], f32x16& o0, f32x16& o1, float& m, float& l,
;                   float sc, const MF& mf, int lane, f32x16 (&s)[2], float invl, bool lanevalid = true) {
;   const int r = lane & 31, h = lane >> 5;
;   const int pr = kperm(r);
;   constexpr int KST = DQK + 8;
;   bf16x8 kf[2][DQK / 16];
; #pragma unroll
;   for (int sub = 0; sub < 2; ++sub)
; #pragma unroll
;     for (int ks = 0; ks < DQK / 16; ++ks) kf[sub][ks] = *(const bf16x8*)(sK + (sub * 32 + pr) * KST + ks * 16 + 8 * h);
;   __builtin_amdgcn_sched_barrier(0);
; #pragma unroll
;   for (int q = 0; q < 16; ++q) { s[0][q] = 0.f; s[1][q] = 0.f; }
; #pragma unroll
;   for (int ks = 0; ks < DQK / 16; ++ks) {
;     s[0] = MFMA(kf[0][ks], qf[ks], s[0]);
;     s[1] = MFMA(kf[1][ks], qf[ks], s[1]);
;   }
;     ...
;   if (MODE != 2) {
;     ps += shx(ps, 32);
;     l = l * alpha + ps;
;   }
;   if (MODE == 1) return;
;   if (MODE == 0) {
; #pragma unroll
;     for (int q = 0; q < 16; ++q) { o0[q] *= alpha; o1[q] *= alpha; }
;   }
; #pragma unroll
;   for (int sub = 0; sub < 2; ++sub)
; #pragma unroll
;     for (int s2 = 0; s2 < 2; ++s2) {
;       union { bf16x8 v; unsigned u[4]; } pb;
; #pragma unroll
;       for (int e = 0; e < 4; ++e) pb.u[e] = pack2(s[sub][8 * s2 + 2 * e], s[sub][8 * s2 + 2 * e + 1]);
;       o0 = MFMA(vf[sub][s2][0], pb.v, o0);
;       o1 = MFMA(vf[sub][s2][1], pb.v, o1);
;     }
	v_pk_mul_f32 v[34:35], v[34:35], v[0:1] op_sel_hi:[1,0]
	v_pk_mul_f32 v[32:33], v[32:33], v[0:1] op_sel_hi:[1,0]
	v_cvt_pk_bf16_f32 v48, v65, v64
	v_cvt_pk_bf16_f32 v49, v66, v67
	v_cvt_pk_bf16_f32 v50, v68, v69
	v_cvt_pk_bf16_f32 v51, v70, v71
	v_pk_mul_f32 v[30:31], v[30:31], v[0:1] op_sel_hi:[1,0]
	v_pk_mul_f32 v[28:29], v[28:29], v[0:1] op_sel_hi:[1,0]
	v_mfma_f32_32x32x16_bf16 v[32:47], v[132:135], v[48:51], v[32:47]
	v_mul_f32_e64 v26, v26, v0
	v_mul_f32_e64 v27, v27, v0
	v_mul_f32_e64 v24, v24, v0
	v_mul_f32_e64 v25, v25, v0
	v_mul_f32_e64 v22, v22, v0
	v_mul_f32_e64 v23, v23, v0
	v_pk_mul_f32 v[20:21], v[20:21], v[0:1] op_sel_hi:[1,0]
	v_pk_mul_f32 v[18:19], v[18:19], v[0:1] op_sel_hi:[1,0]
	v_pk_mul_f32 v[16:17], v[16:17], v[0:1] op_sel_hi:[1,0]
	v_fma_f32 v57, v57, s37, -v15
	v_exp_f32_e32 v57, v57
	v_mfma_f32_32x32x16_bf16 v[16:31], v[128:131], v[48:51], v[16:31]
	v_add_f32_e32 v48, v55, v190
	v_add_f32_e32 v64, v56, v48
	v_cvt_pk_bf16_f32 v48, v72, v73
	v_cvt_pk_bf16_f32 v49, v74, v75
	v_cvt_pk_bf16_f32 v50, v76, v77
	v_cvt_pk_bf16_f32 v51, v78, v79
	v_fma_f32 v58, v58, s37, -v15
	v_exp_f32_e32 v58, v58
	v_mfma_f32_32x32x16_bf16 v[32:47], v[124:127], v[48:51], v[32:47]
	v_fma_f32 v59, v59, s37, -v15
	v_exp_f32_e32 v59, v59
	v_add_f32_e32 v64, v57, v64
	v_add_f32_e32 v64, v58, v64
	v_add_f32_e32 v64, v59, v64
	v_mfma_f32_32x32x16_bf16 v[16:31], v[120:123], v[48:51], v[16:31]
	v_fma_f32 v48, v60, s37, -v15
	v_exp_f32_e32 v60, v48
	v_cvt_pk_bf16_f32 v48, v187, v188
	v_cvt_pk_bf16_f32 v49, v189, v186
	v_cvt_pk_bf16_f32 v50, v52, v53
	v_cvt_pk_bf16_f32 v51, v54, v55
	v_fma_f32 v53, v61, s37, -v15
	v_exp_f32_e32 v53, v53
	v_mfma_f32_32x32x16_bf16 v[32:47], v[116:119], v[48:51], v[32:47]
	v_pk_fma_f32 v[206:207], v[62:63], s[36:37], v[14:15] op_sel:[0,1,1] op_sel_hi:[1,1,1] neg_lo:[0,0,1] neg_hi:[0,0,1]
	v_exp_f32_e32 v54, v206
	v_exp_f32_e32 v55, v207
	v_add_f32_e32 v52, v60, v64
	v_mov_b32_e32 v186, v15
	v_mfma_f32_32x32x16_bf16 v[16:31], v[10:13], v[48:51], v[16:31]
	v_add_f32_e32 v10, v53, v52
	v_add_f32_e32 v10, v54, v10
	v_add_f32_e32 v48, v55, v10
	v_cvt_pk_bf16_f32 v10, v56, v57
	v_cvt_pk_bf16_f32 v11, v58, v59
	v_cvt_pk_bf16_f32 v12, v60, v53
	v_cvt_pk_bf16_f32 v13, v54, v55
	s_nop 1
	v_mfma_f32_32x32x16_bf16 v[32:47], v[6:9], v[10:13], v[32:47]
	ds_bpermute_b32 v6, v14, v48
	s_waitcnt lgkmcnt(0)
	v_add_f32_e32 v6, v48, v6
	v_fmac_f32_e32 v6, v165, v0
	v_mfma_f32_32x32x16_bf16 v[16:31], v[2:5], v[10:13], v[16:31]
	v_mov_b32_e32 v165, v6
.LBB0_788:
	s_andn2_saveexec_b64 s[24:25], s[24:25]
	s_cbranch_execz .LBB0_790
	v_lshl_add_u32 v14, s40, 1, v176
	ds_read_b128 v[2:5], v14
	ds_read_b128 v[6:9], v14 offset:32
	ds_read_b128 v[10:13], v14 offset:64
	ds_read_b128 v[116:119], v14 offset:96
	ds_read_b128 v[120:123], v14 offset:128
	ds_read_b128 v[124:127], v14 offset:160
	ds_read_b128 v[48:51], v14 offset:6656
	ds_read_b128 v[128:131], v14 offset:6688
	ds_read_b128 v[132:135], v14 offset:6720
	ds_read_b128 v[188:191], v14 offset:6752
	ds_read_b128 v[194:197], v14 offset:6784
	ds_read_b128 v[198:201], v14 offset:6816
	s_waitcnt lgkmcnt(11)
	v_mfma_f32_32x32x16_bf16 v[64:79], v[2:5], v[100:103], 0
	v_lshlrev_b32_e32 v2, 1, v175
	v_add3_u32 v3, s39, v172, v2
	v_add3_u32 v2, s39, v173, v2
	s_waitcnt lgkmcnt(10)
	v_mfma_f32_32x32x16_bf16 v[64:79], v[6:9], v[80:83], v[64:79]
	s_waitcnt lgkmcnt(5)
	v_mfma_f32_32x32x16_bf16 v[48:63], v[48:51], v[100:103], 0
	v_mfma_f32_32x32x16_bf16 v[64:79], v[10:13], v[84:87], v[64:79]
	s_waitcnt lgkmcnt(4)
	v_mfma_f32_32x32x16_bf16 v[48:63], v[128:131], v[80:83], v[48:63]
	v_mfma_f32_32x32x16_bf16 v[64:79], v[116:119], v[88:91], v[64:79]
	s_waitcnt lgkmcnt(3)
	v_mfma_f32_32x32x16_bf16 v[48:63], v[132:135], v[84:87], v[48:63]
	v_mfma_f32_32x32x16_bf16 v[64:79], v[120:123], v[92:95], v[64:79]
	s_waitcnt lgkmcnt(2)
	v_mfma_f32_32x32x16_bf16 v[48:63], v[188:191], v[88:91], v[48:63]
	v_mfma_f32_32x32x16_bf16 v[64:79], v[124:127], v[96:99], v[64:79]
	ds_read_b128 v[132:135], v3 offset:13312
	ds_read_b128 v[124:127], v3 offset:13344
	ds_read_b128 v[128:131], v2 offset:13312
	ds_read_b128 v[120:123], v2 offset:13344
	ds_read_b128 v[116:119], v3 offset:13376
	ds_read_b128 v[6:9], v3 offset:13408
	ds_read_b128 v[10:13], v2 offset:13376
	ds_read_b128 v[2:5], v2 offset:13408
	s_waitcnt lgkmcnt(9)
	v_mfma_f32_32x32x16_bf16 v[48:63], v[194:197], v[92:95], v[48:63]
	s_waitcnt lgkmcnt(8)
; DI float fexp2(float x) { return __builtin_amdgcn_exp2f(x); }
; DI float shx(float v, int m) { return __shfl_xor(v, m, 64); }
; template <int DQK, bool MASKED, int MODE, class MF>
; DI void attn_step(const bf16_t* sK, const bf16_t* sVt, const bf16x8 (&qf)[DQK / 16], f32x16& o0, f32x16& o1, float& m, float& l,
;                   float sc, const MF& mf, int lane, f32x16 (&s)[2], float invl, bool lanevalid = true) {
;     ...
;   float mxr = -3.0e38f;
; #pragma unroll
;   for (int sub = 0; sub < 2; ++sub)
; #pragma unroll
;     for (int q = 0; q < 16; ++q) {
;       if (MASKED) { const int kk = sub * 32 + 16 * (q >> 3) + 8 * h + (q & 7); s[sub][q] = mf(kk) ? s[sub][q] : -3.0e38f; }
;       if (MODE != 2) mxr = fmaxf(mxr, s[sub][q]);
;     }
;   float alpha = 1.f;
;   if (MODE != 2) {
;     float mx = fmaxf(m, mxr * sc);
;     mx = fmaxf(mx, shx(mx, 32));
;     if (!MASKED) mx = lanevalid ? mx : m;
;     alpha = fexp2(m - mx);
;     m = mx;
;   }
; DI void phase_attn_mla(const Params& P, bf16_t* og, unsigned char* smem, int L, int G) {
;     ...
;         auto mf = [&](int kk) { return key0 + kk <= t; };
;         if (key0 + 63 > t0) attn_step<96, true, 0>(sK + cb * KVB96, sVt + cb * KVB96, qf, o0, o1, m, l, sc, mf, lane, s, 0.f);
	v_mfma_f32_32x32x16_bf16 v[48:63], v[198:201], v[96:99], v[48:63]
	v_add_u32_e32 v14, s14, v175
	v_cmp_le_i32_e32 vcc, v14, v164
	s_nop 1
	v_cndmask_b32_e32 v15, v185, v64, vcc
	v_cmp_lt_i32_e32 vcc, v14, v164
	s_nop 1
	v_cndmask_b32_e32 v64, v185, v65, vcc
	v_add_u32_e32 v65, 2, v14
	v_cmp_le_i32_e32 vcc, v65, v164
	s_nop 1
	v_cndmask_b32_e32 v65, v185, v66, vcc
	v_add_u32_e32 v66, 3, v14
	v_cmp_le_i32_e32 vcc, v66, v164
	s_nop 1
	v_cndmask_b32_e32 v66, v185, v67, vcc
	v_add_u32_e32 v67, 4, v14
	v_cmp_le_i32_e32 vcc, v67, v164
	s_nop 1
	v_cndmask_b32_e32 v67, v185, v68, vcc
	v_add_u32_e32 v68, 5, v14
	v_cmp_le_i32_e32 vcc, v68, v164
	s_nop 1
	v_cndmask_b32_e32 v68, v185, v69, vcc
	v_add_u32_e32 v69, 6, v14
	v_cmp_le_i32_e32 vcc, v69, v164
	s_nop 1
	v_cndmask_b32_e32 v69, v185, v70, vcc
	v_add_u32_e32 v70, s14, v174
	v_or_b32_e32 v187, 7, v70
	v_cmp_le_i32_e32 vcc, v187, v164
	v_add_u32_e32 v187, 16, v14
	s_nop 0
	v_cndmask_b32_e32 v71, v185, v71, vcc
	v_cmp_le_i32_e32 vcc, v187, v164
	v_add_u32_e32 v187, 17, v14
	s_nop 0
	v_cndmask_b32_e32 v72, v185, v72, vcc
	v_cmp_le_i32_e32 vcc, v187, v164
	v_add_u32_e32 v187, 18, v14
	s_nop 0
	v_cndmask_b32_e32 v73, v185, v73, vcc
	v_cmp_le_i32_e32 vcc, v187, v164
	v_add_u32_e32 v187, 19, v14
	s_nop 0
	v_cndmask_b32_e32 v74, v185, v74, vcc
	v_cmp_le_i32_e32 vcc, v187, v164
	v_add_u32_e32 v187, 20, v14
	s_nop 0
	v_cndmask_b32_e32 v75, v185, v75, vcc
	v_cmp_le_i32_e32 vcc, v187, v164
	v_add_u32_e32 v187, 21, v14
	s_nop 0
	v_cndmask_b32_e32 v76, v185, v76, vcc
	v_cmp_le_i32_e32 vcc, v187, v164
	v_add_u32_e32 v187, 22, v14
	s_nop 0
	v_cndmask_b32_e32 v77, v185, v77, vcc
	v_cmp_le_i32_e32 vcc, v187, v164
	v_or_b32_e32 v187, 23, v70
	s_nop 0
	v_cndmask_b32_e32 v78, v185, v78, vcc
	v_cmp_le_i32_e32 vcc, v187, v164
	v_add_u32_e32 v187, 32, v14
	s_nop 0
	v_cndmask_b32_e32 v79, v185, v79, vcc
	v_cmp_le_i32_e32 vcc, v187, v164
	v_add_u32_e32 v187, 33, v14
	s_nop 0
	v_cndmask_b32_e32 v48, v185, v48, vcc
	v_cmp_le_i32_e32 vcc, v187, v164
	v_add_u32_e32 v187, 34, v14
	s_nop 0
	v_cndmask_b32_e32 v49, v185, v49, vcc
	v_cmp_le_i32_e32 vcc, v187, v164
	v_add_u32_e32 v187, 35, v14
	s_nop 0
	v_cndmask_b32_e32 v50, v185, v50, vcc
	v_cmp_le_i32_e32 vcc, v187, v164
	v_add_u32_e32 v187, 36, v14
	s_nop 0
	v_cndmask_b32_e32 v51, v185, v51, vcc
	v_cmp_le_i32_e32 vcc, v187, v164
	v_add_u32_e32 v187, 37, v14
	s_nop 0
	v_cndmask_b32_e32 v52, v185, v52, vcc
	v_cmp_le_i32_e32 vcc, v187, v164
	v_add_u32_e32 v187, 38, v14
	s_nop 0
	v_cndmask_b32_e32 v53, v185, v53, vcc
	v_cmp_le_i32_e32 vcc, v187, v164
	v_or_b32_e32 v187, 39, v70
	s_nop 0
	v_cndmask_b32_e32 v54, v185, v54, vcc
	v_cmp_le_i32_e32 vcc, v187, v164
	v_add_u32_e32 v187, 48, v14
	s_nop 0
	v_cndmask_b32_e32 v55, v185, v55, vcc
	v_cmp_le_i32_e32 vcc, v187, v164
	v_add_u32_e32 v187, 49, v14
	s_nop 0
	v_cndmask_b32_e32 v56, v185, v56, vcc
	v_cmp_le_i32_e32 vcc, v187, v164
	v_add_u32_e32 v187, 50, v14
	s_nop 0
	v_cndmask_b32_e32 v57, v185, v57, vcc
	v_cmp_le_i32_e32 vcc, v187, v164
	v_add_u32_e32 v187, 51, v14
	s_nop 0
	v_cndmask_b32_e32 v58, v185, v58, vcc
	v_cmp_le_i32_e32 vcc, v187, v164
	v_add_u32_e32 v187, 52, v14
	s_nop 0
	v_cndmask_b32_e32 v59, v185, v59, vcc
	v_cmp_le_i32_e32 vcc, v187, v164
	v_add_u32_e32 v187, 53, v14
	v_add_u32_e32 v14, 54, v14
	v_cndmask_b32_e32 v60, v185, v60, vcc
	v_cmp_le_i32_e32 vcc, v187, v164
	s_nop 1
	v_cndmask_b32_e32 v61, v185, v61, vcc
	v_cmp_le_i32_e32 vcc, v14, v164
	s_nop 1
	v_cndmask_b32_e32 v14, v185, v62, vcc
	v_or_b32_e32 v62, 55, v70
	v_cmp_le_i32_e32 vcc, v62, v164
	s_nop 1
	v_cndmask_b32_e32 v62, v185, v63, vcc
	v_max3_f32 v63, v15, s36, v64
	v_max3_f32 v63, v63, v65, v66
	v_max3_f32 v63, v63, v67, v68
	v_max3_f32 v63, v63, v69, v71
	v_max3_f32 v63, v63, v72, v73
	v_max3_f32 v63, v63, v74, v75
	v_max3_f32 v63, v63, v76, v77
	v_max3_f32 v63, v63, v78, v79
	v_max3_f32 v63, v63, v48, v49
	v_max3_f32 v63, v63, v50, v51
	v_max3_f32 v63, v63, v52, v53
	v_max3_f32 v63, v63, v54, v55
	v_max3_f32 v63, v63, v56, v57
	v_max3_f32 v63, v63, v58, v59
	v_max3_f32 v63, v63, v60, v61
	v_max3_f32 v63, v63, v14, v62
	v_mul_f32_e32 v63, 0x3e16c740, v63
	v_cmp_lt_i32_e32 vcc, v183, v184
	v_max_f32_e32 v0, v0, v63
	s_nop 0
	v_cndmask_b32_e32 v63, v182, v183, vcc
	v_lshlrev_b32_e32 v63, 2, v63
	ds_bpermute_b32 v70, v63, v0
	s_waitcnt lgkmcnt(0)
; #define MFMA(a, b, c) __builtin_amdgcn_mfma_f32_32x32x16_bf16((a), (b), (c), 0, 0, 0)
; DI unsigned pack2(float a, float b) { f32x2_t v = {a, b}; bf16x2_t r = __builtin_convertvector(v, bf16x2_t); return __builtin_bit_cast(unsigned, r); }
; DI float fexp2(float x) { return __builtin_amdgcn_exp2f(x); }
; DI float shx(float v, int m) { return __shfl_xor(v, m, 64); }
; template <int DQK, bool MASKED, int MODE, class MF>
; DI void attn_step(const bf16_t* sK, const bf16_t* sVt, const bf16x8 (&qf)[DQK / 16], f32x16& o0, f32x16& o1, float& m, float& l,
;                   float sc, const MF& mf, int lane, f32x16 (&s)[2], float invl, bool lanevalid = true) {
;     ...
;   float alpha = 1.f;
;   if (MODE != 2) {
;     float mx = fmaxf(m, mxr * sc);
;     mx = fmaxf(mx, shx(mx, 32));
;     if (!MASKED) mx = lanevalid ? mx : m;
;     alpha = fexp2(m - mx);
;     m = mx;
;   }
;   const float moff = (!MASKED && !lanevalid) ? 1.0e30f : m;
;   float ps = 0.f;
; #pragma unroll
;   for (int sub = 0; sub < 2; ++sub)
; #pragma unroll
;     for (int q = 0; q < 16; ++q) {
;       float pv = fexp2(__builtin_fmaf(s[sub][q], sc, -moff));
;       if (MASKED && MODE != 0) pv = (s[sub][q] > -1.0e38f) ? pv : 0.f;
;       if (MODE == 2) pv *= invl;
;       s[sub][q] = pv;
;       ps += pv;
;     }
;   if (MODE != 2) {
;     ps += shx(ps, 32);
;     l = l * alpha + ps;
;   }
;   if (MODE == 1) return;
;   if (MODE == 0) {
; #pragma unroll
;     for (int q = 0; q < 16; ++q) { o0[q] *= alpha; o1[q] *= alpha; }
;   }
; #pragma unroll
;   for (int sub = 0; sub < 2; ++sub)
; #pragma unroll
;     for (int s2 = 0; s2 < 2; ++s2) {
;       union { bf16x8 v; unsigned u[4]; } pb;
; #pragma unroll
;       for (int e = 0; e < 4; ++e) pb.u[e] = pack2(s[sub][8 * s2 + 2 * e], s[sub][8 * s2 + 2 * e + 1]);
;       o0 = MFMA(vf[sub][s2][0], pb.v, o0);
;       o1 = MFMA(vf[sub][s2][1], pb.v, o1);
;     }
	v_max_f32_e32 v70, v70, v70
	v_max_f32_e32 v70, v0, v70
	v_fma_f32 v0, v15, s37, -v70
	v_exp_f32_e32 v15, v0
	v_fma_f32 v0, v64, s37, -v70
	v_exp_f32_e32 v64, v0
	v_fma_f32 v0, v65, s37, -v70
	v_exp_f32_e32 v65, v0
	v_fma_f32 v66, v66, s37, -v70
	v_exp_f32_e32 v66, v66
	v_fma_f32 v67, v67, s37, -v70
	v_sub_f32_e32 v0, v186, v70
	v_add_f32_e32 v186, 0, v15
	v_exp_f32_e32 v67, v67
	v_fma_f32 v68, v68, s37, -v70
	v_add_f32_e32 v186, v64, v186
	v_exp_f32_e32 v68, v68
	v_fma_f32 v69, v69, s37, -v70
	v_add_f32_e32 v186, v65, v186
	v_exp_f32_e32 v69, v69
	v_fma_f32 v71, v71, s37, -v70
	v_add_f32_e32 v186, v66, v186
	v_exp_f32_e32 v71, v71
	v_fma_f32 v72, v72, s37, -v70
	v_add_f32_e32 v186, v67, v186
	v_exp_f32_e32 v72, v72
	v_fma_f32 v73, v73, s37, -v70
	v_add_f32_e32 v186, v68, v186
	v_exp_f32_e32 v73, v73
	v_fma_f32 v74, v74, s37, -v70
	v_add_f32_e32 v186, v69, v186
	v_exp_f32_e32 v74, v74
	v_fma_f32 v75, v75, s37, -v70
	v_add_f32_e32 v186, v71, v186
	v_exp_f32_e32 v75, v75
	v_fma_f32 v76, v76, s37, -v70
	v_add_f32_e32 v186, v72, v186
	v_exp_f32_e32 v76, v76
	v_fma_f32 v77, v77, s37, -v70
	v_add_f32_e32 v186, v73, v186
	v_exp_f32_e32 v77, v77
	v_fma_f32 v78, v78, s37, -v70
	v_add_f32_e32 v186, v74, v186
	v_exp_f32_e32 v78, v78
	v_fma_f32 v79, v79, s37, -v70
	v_add_f32_e32 v186, v75, v186
	v_exp_f32_e32 v79, v79
	v_pk_fma_f32 v[206:207], v[48:49], s[36:37], v[70:71] op_sel:[0,1,0] op_sel_hi:[1,1,0] neg_lo:[0,0,1] neg_hi:[0,0,1]
	v_add_f32_e32 v186, v76, v186
	v_exp_f32_e32 v187, v206
	v_add_f32_e32 v186, v77, v186
	v_exp_f32_e32 v188, v207
	v_pk_fma_f32 v[206:207], v[50:51], s[36:37], v[70:71] op_sel:[0,1,0] op_sel_hi:[1,1,0] neg_lo:[0,0,1] neg_hi:[0,0,1]
	v_add_f32_e32 v186, v78, v186
	v_exp_f32_e32 v189, v206
	v_add_f32_e32 v48, v79, v186
	v_exp_f32_e32 v186, v207
	v_fma_f32 v49, v52, s37, -v70
	v_add_f32_e32 v48, v187, v48
	v_exp_f32_e32 v52, v49
	v_fma_f32 v49, v53, s37, -v70
	v_add_f32_e32 v48, v188, v48
	v_exp_f32_e32 v53, v49
	v_fma_f32 v49, v54, s37, -v70
	v_add_f32_e32 v48, v189, v48
	v_exp_f32_e32 v54, v49
	v_add_f32_e32 v48, v186, v48
	v_add_f32_e32 v48, v52, v48
	v_exp_f32_e32 v0, v0
	v_add_f32_e32 v48, v53, v48
	v_add_f32_e32 v190, v54, v48
	v_fma_f32 v48, v55, s37, -v70
	v_exp_f32_e32 v55, v48
	v_fma_f32 v48, v56, s37, -v70
	v_exp_f32_e32 v56, v48
	v_pk_mul_f32 v[46:47], v[46:47], v[0:1] op_sel_hi:[1,0]
	v_pk_mul_f32 v[44:45], v[44:45], v[0:1] op_sel_hi:[1,0]
	v_pk_mul_f32 v[42:43], v[42:43], v[0:1] op_sel_hi:[1,0]
	v_pk_mul_f32 v[40:41], v[40:41], v[0:1] op_sel_hi:[1,0]
	v_pk_mul_f32 v[38:39], v[38:39], v[0:1] op_sel_hi:[1,0]
	v_pk_mul_f32 v[36:37], v[36:37], v[0:1] op_sel_hi:[1,0]
	v_pk_mul_f32 v[34:35], v[34:35], v[0:1] op_sel_hi:[1,0]
	v_pk_mul_f32 v[32:33], v[32:33], v[0:1] op_sel_hi:[1,0]
	v_pk_mul_f32 v[30:31], v[30:31], v[0:1] op_sel_hi:[1,0]
	v_cvt_pk_bf16_f32 v48, v15, v64
	v_cvt_pk_bf16_f32 v49, v65, v66
	v_cvt_pk_bf16_f32 v50, v67, v68
	v_cvt_pk_bf16_f32 v51, v69, v71
	v_pk_mul_f32 v[28:29], v[28:29], v[0:1] op_sel_hi:[1,0]
	v_pk_mul_f32 v[26:27], v[26:27], v[0:1] op_sel_hi:[1,0]
	v_pk_mul_f32 v[24:25], v[24:25], v[0:1] op_sel_hi:[1,0]
	v_pk_mul_f32 v[22:23], v[22:23], v[0:1] op_sel_hi:[1,0]
	v_pk_mul_f32 v[20:21], v[20:21], v[0:1] op_sel_hi:[1,0]
	v_pk_mul_f32 v[18:19], v[18:19], v[0:1] op_sel_hi:[1,0]
	v_pk_mul_f32 v[16:17], v[16:17], v[0:1] op_sel_hi:[1,0]
	v_mfma_f32_32x32x16_bf16 v[32:47], v[132:135], v[48:51], v[32:47]
	v_fma_f32 v57, v57, s37, -v70
	v_exp_f32_e32 v57, v57
	v_fma_f32 v58, v58, s37, -v70
	v_exp_f32_e32 v58, v58
	v_fma_f32 v59, v59, s37, -v70
	v_add_f32_e32 v15, v55, v190
	v_exp_f32_e32 v59, v59
	v_mfma_f32_32x32x16_bf16 v[16:31], v[128:131], v[48:51], v[16:31]
	v_cvt_pk_bf16_f32 v48, v72, v73
	v_cvt_pk_bf16_f32 v49, v74, v75
	v_cvt_pk_bf16_f32 v50, v76, v77
	v_cvt_pk_bf16_f32 v51, v78, v79
	v_add_f32_e32 v15, v56, v15
	v_add_f32_e32 v15, v57, v15
	v_fma_f32 v14, v14, s37, -v70
	v_mfma_f32_32x32x16_bf16 v[32:47], v[124:127], v[48:51], v[32:47]
	v_add_f32_e32 v15, v58, v15
	v_exp_f32_e32 v14, v14
	v_add_f32_e32 v15, v59, v15
	v_mfma_f32_32x32x16_bf16 v[16:31], v[120:123], v[48:51], v[16:31]
	v_fma_f32 v48, v60, s37, -v70
	v_exp_f32_e32 v60, v48
	v_cvt_pk_bf16_f32 v48, v187, v188
	v_cvt_pk_bf16_f32 v49, v189, v186
	v_cvt_pk_bf16_f32 v50, v52, v53
	v_cvt_pk_bf16_f32 v51, v54, v55
	v_fma_f32 v52, v61, s37, -v70
	v_exp_f32_e32 v52, v52
	v_mfma_f32_32x32x16_bf16 v[32:47], v[116:119], v[48:51], v[32:47]
	v_fma_f32 v53, v62, s37, -v70
	v_exp_f32_e32 v53, v53
	v_add_f32_e32 v15, v60, v15
	v_mov_b32_e32 v186, v70
	v_mfma_f32_32x32x16_bf16 v[16:31], v[10:13], v[48:51], v[16:31]
	v_add_f32_e32 v10, v52, v15
	v_add_f32_e32 v10, v14, v10
	v_add_f32_e32 v15, v53, v10
	v_cvt_pk_bf16_f32 v10, v56, v57
	v_cvt_pk_bf16_f32 v11, v58, v59
	v_cvt_pk_bf16_f32 v12, v60, v52
	v_cvt_pk_bf16_f32 v13, v14, v53
	s_nop 1
	v_mfma_f32_32x32x16_bf16 v[32:47], v[6:9], v[10:13], v[32:47]
	ds_bpermute_b32 v6, v63, v15
	s_waitcnt lgkmcnt(0)
	v_add_f32_e32 v6, v15, v6
	v_fmac_f32_e32 v6, v165, v0
	v_mfma_f32_32x32x16_bf16 v[16:31], v[2:5], v[10:13], v[16:31]
	v_mov_b32_e32 v165, v6

; DI float bf2f(bf16_t b) { return __uint_as_float(((unsigned)b) << 16); }
; DI float sigmoidf_(float x) { return __builtin_amdgcn_rcpf(1.f + __expf(-x)); }
; DI void kv64_fetch(KVR& R, const bf16_t* kbase, int kstride, const bf16_t* vtbase, int vtstride, int key0, bool withV, int tid) {
;   const int row0 = tid >> 3, kc = tid & 7, row1 = row0 + 32;
;   R.k0 = ldg16(kbase + (size_t)(key0 + row0) * kstride + kc * 8);
;   R.k1 = ldg16(kbase + (size_t)(key0 + row1) * kstride + kc * 8);
;   if (withV) { R.v0 = ldg16(vtbase + (size_t)row0 * vtstride + key0 + kc * 8); R.v1 = ldg16(vtbase + (size_t)row1 * vtstride + key0 + kc * 8); }
; }
; DI void kv64_commit(const KVR& R, bf16_t* sK, bf16_t* sVt, bool withV, int tid) {
;   const int row0 = tid >> 3, kc = tid & 7, row1 = row0 + 32;
;   __syncthreads();
;   *(u32x4*)(sK + row0 * 72 + kc * 8) = R.k0;
;   *(u32x4*)(sK + row1 * 72 + kc * 8) = R.k1;
;   if (withV) { *(u32x4*)(sVt + row0 * 72 + kc * 8) = R.v0; *(u32x4*)(sVt + row1 * 72 + kc * 8) = R.v1; }
;   __syncthreads();
; }
; DI void phase_attn_nsa(const Params& P, bf16_t* og, unsigned char* smem, int L, int G) {
;     ...
;     bf16x8 qf[4];
; #pragma unroll
;     for (int ks = 0; ks < 4; ++ks) qf[ks] = *(const bf16x8*)(big + NS_Q + tok * 1024 + head * 64 + ks * 16 + 8 * h);
;     const bf16_t* glp = big + NS_GL + tok * 64;
;     const float g0 = sigmoidf_(bf2f(glp[head])), g1 = sigmoidf_(bf2f(glp[16 + head])), g2 = sigmoidf_(bf2f(glp[32 + head]));
;     f32x16 o0, o1, s[2];
;     {
;       const bf16_t* kb = big + NS_KC2 + (size_t)((b * 4 + g) * 128) * 64;
;       const bf16_t* vb = big + NS_VCT + (size_t)((b * 4 + g) * 64) * 128;
;       float m = NEGF, l = 0.f;
;       KVR R; kv64_fetch(R, kb, 64, vb, 128, 0, false, tid);
; #pragma unroll
;       for (int tile = 0; tile < 2; ++tile) {
;         const int key0 = tile * 64;
;         kv64_commit(R, sK, sVt, false, tid);
;         if (tile == 0) kv64_fetch(R, kb, 64, vb, 128, 64, false, tid); else kv64_fetch(R, kb, 64, vb, 128, 0, true, tid);
;         __builtin_amdgcn_sched_barrier(0);
;         auto mf = [&](int kk) { return (key0 + kk) * 16 + 31 <= t; };
;         attn_step<64, true, 1>(sK, sVt, qf, o0, o1, m, l, sc, mf, lane, s, 0.f);
.LBB0_1278:
	v_ashrrev_i32_e32 v114, 2, v2
	v_and_b32_e32 v118, 31, v120
	s_lshl_b32 s46, s44, 5
	v_ashrrev_i32_e32 v115, 31, v114
	v_or_b32_e32 v136, s46, v118
	v_lshlrev_b64 v[134:135], 11, v[114:115]
	v_mov_b32_e32 v137, v1
	v_bfe_u32 v168, v120, 6, 2
	v_and_b32_e32 v119, 3, v2
	v_lshl_add_u64 v[4:5], v[134:135], 0, v[136:137]
	v_lshl_or_b32 v121, v119, 2, v168
	v_lshlrev_b64 v[6:7], 11, v[4:5]
	v_readlane_b32 s0, v246, 38
	v_lshl_add_u64 v[6:7], s[76:77], 0, v[6:7]
	v_lshlrev_b32_e32 v0, 7, v121
	v_lshlrev_b64 v[4:5], 7, v[4:5]
	v_readlane_b32 s1, v246, 39
	v_lshl_add_u64 v[12:13], v[6:7], 0, v[0:1]
	v_lshlrev_b32_e32 v0, 1, v121
	v_lshl_add_u64 v[4:5], s[0:1], 0, v[4:5]
	v_lshl_add_u64 v[14:15], v[4:5], 0, v[0:1]
	v_lshlrev_b32_e32 v4, 7, v2
	v_ashrrev_i32_e32 v5, 31, v4
	v_readlane_b32 s0, v246, 40
	v_lshlrev_b32_e32 v0, 3, v120
	v_lshlrev_b64 v[4:5], 7, v[4:5]
	v_readlane_b32 s1, v246, 41
	v_bfe_u32 v169, v120, 3, 5
	v_and_b32_e32 v0, 56, v0
	v_lshl_add_u64 v[8:9], s[0:1], 0, v[4:5]
	v_or_b32_e32 v174, 32, v169
	v_lshlrev_b32_e32 v140, 1, v0
	v_lshlrev_b32_e32 v0, 7, v169
	v_mov_b32_e32 v141, v1
	v_lshl_add_u64 v[4:5], v[8:9], 0, v[0:1]
	v_lshlrev_b32_e32 v0, 7, v174
	v_lshl_add_u64 v[46:47], v[4:5], 0, v[140:141]
	v_lshl_add_u64 v[8:9], v[8:9], 0, v[0:1]
	global_load_dwordx4 v[4:7], v[46:47], off
	v_lshl_add_u64 v[42:43], v[8:9], 0, v[140:141]
	global_load_dwordx4 v[8:11], v[42:43], off
	v_lshrrev_b32_e32 v0, 2, v120
	v_and_b32_e32 v56, 8, v0
	v_mov_b32_e32 v139, v1
	v_lshlrev_b32_e32 v138, 1, v56
	v_lshl_add_u64 v[12:13], v[12:13], 0, v[138:139]
	global_load_dwordx4 v[74:77], v[12:13], off
	global_load_dwordx4 v[78:81], v[12:13], off offset:32
	global_load_dwordx4 v[82:85], v[12:13], off offset:64
	global_load_dwordx4 v[86:89], v[12:13], off offset:96
	global_load_ushort v124, v[14:15], off
	global_load_ushort v123, v[14:15], off offset:32
	global_load_ushort v122, v[14:15], off offset:64
	s_movk_i32 s0, 0x3000
	v_mul_u32_u24_e32 v0, 0x48, v169
	v_lshlrev_b32_e32 v0, 1, v0
	v_add_co_u32_e32 v50, vcc, s0, v46
	v_add3_u32 v170, v153, v0, v140
	s_nop 0
	v_addc_co_u32_e32 v51, vcc, 0, v47, vcc
	s_barrier
	v_lshlrev_b32_e32 v116, 6, v2
	v_ashrrev_i32_e32 v117, 31, v116
	v_readlane_b32 s0, v246, 42
	v_lshlrev_b64 v[2:3], 8, v[116:117]
	v_readlane_b32 s1, v246, 43
	v_and_b32_e32 v0, 19, v120
	v_bfe_u32 v139, v120, 2, 4
	v_cmp_lt_i32_e32 vcc, v164, v165
	v_lshl_add_u64 v[52:53], s[0:1], 0, v[2:3]
	v_and_b32_e32 v171, 8, v139
	v_lshl_add_u64 v[2:3], v[52:53], 0, v[140:141]
	v_lshl_add_u32 v57, v171, 1, v153
	s_movk_i32 s47, 0x90
	v_and_b32_e32 v137, 63, v120
	v_lshlrev_b32_e32 v54, 8, v174
	v_mov_b32_e32 v55, v1
	v_writelane_b32 v245, s2, 25
	v_lshl_add_u64 v[48:49], v[2:3], 0, v[54:55]
	s_waitcnt vmcnt(8)
	ds_write_b128 v170, v[4:7]
	s_waitcnt vmcnt(7)
	ds_write_b128 v170, v[8:11] offset:4608
	s_waitcnt lgkmcnt(0)
	s_barrier
	global_load_dwordx4 v[34:37], v[50:51], off
	global_load_dwordx4 v[38:41], v[50:51], off offset:-4096
	v_lshrrev_b32_e32 v4, 1, v120
	v_lshlrev_b32_e32 v5, 1, v120
	v_and_b32_e32 v4, 4, v4
	v_and_b32_e32 v5, 8, v5
	v_or3_b32 v125, v4, v0, v5
	v_cndmask_b32_e32 v0, v163, v164, vcc
	v_lshlrev_b32_e32 v173, 2, v0
	v_lshlrev_b32_e32 v0, 8, v169
	v_mad_u32_u24 v172, v125, s47, v57
	v_lshl_add_u64 v[44:45], v[2:3], 0, v[0:1]
	ds_read_b128 v[2:5], v172
	ds_read_b128 v[18:21], v172 offset:32
	ds_read_b128 v[22:25], v172 offset:64
	ds_read_b128 v[26:29], v172 offset:96
	ds_read_b128 v[30:33], v172 offset:4608
	ds_read_b128 v[62:65], v172 offset:4640
	ds_read_b128 v[66:69], v172 offset:4672
	ds_read_b128 v[70:73], v172 offset:4704
	s_waitcnt vmcnt(8) lgkmcnt(7)
	v_mfma_f32_32x32x16_bf16 v[2:17], v[2:5], v[74:77], 0
	v_lshlrev_b32_e32 v59, 4, v171
	v_lshlrev_b32_e32 v60, 4, v139
	v_or_b32_e32 v58, 0x11f, v59
	s_waitcnt lgkmcnt(0)
	s_barrier
	s_waitcnt vmcnt(0)
	ds_write_b128 v170, v[38:41]
	ds_write_b128 v170, v[34:37] offset:4608
	v_mfma_f32_32x32x16_bf16 v[2:17], v[18:21], v[78:81], v[2:17]
	v_or_b32_e32 v18, 31, v59
	v_cmp_gt_u32_e64 s[0:1], v18, v136
	v_or_b32_e32 v19, 47, v59
	v_or_b32_e32 v20, 63, v59
	v_writelane_b32 v245, s0, 26
	v_or_b32_e32 v21, 0x4f, v59
	s_waitcnt lgkmcnt(0)
	v_mfma_f32_32x32x16_bf16 v[2:17], v[22:25], v[82:85], v[2:17]
	v_writelane_b32 v245, s1, 27
	v_or_b32_e32 v22, 0x5f, v59
	v_or_b32_e32 v23, 0x6f, v59
	v_or_b32_e32 v24, 0x7f, v60
	v_or_b32_e32 v25, 0x70, v60
	v_add_u32_e32 v25, 31, v25
	s_barrier
; #define MFMA(a, b, c) __builtin_amdgcn_mfma_f32_32x32x16_bf16((a), (b), (c), 0, 0, 0)
; DI float fexp2(float x) { return __builtin_amdgcn_exp2f(x); }
; DI float shx(float v, int m) { return __shfl_xor(v, m, 64); }
; template <int DQK, bool MASKED, int MODE, class MF>
; DI void attn_step(const bf16_t* sK, const bf16_t* sVt, const bf16x8 (&qf)[DQK / 16], f32x16& o0, f32x16& o1, float& m, float& l,
;                   float sc, const MF& mf, int lane, f32x16 (&s)[2], float invl, bool lanevalid = true) {
;     ...
;   for (int sub = 0; sub < 2; ++sub)
; #pragma unroll
;     for (int ks = 0; ks < DQK / 16; ++ks) kf[sub][ks] = *(const bf16x8*)(sK + (sub * 32 + pr) * KST + ks * 16 + 8 * h);
;   __builtin_amdgcn_sched_barrier(0);
; #pragma unroll
;   for (int q = 0; q < 16; ++q) { s[0][q] = 0.f; s[1][q] = 0.f; }
; #pragma unroll
;   for (int ks = 0; ks < DQK / 16; ++ks) {
;     s[0] = MFMA(kf[0][ks], qf[ks], s[0]);
;     s[1] = MFMA(kf[1][ks], qf[ks], s[1]);
;   }
;   bf16x8 vf[2][2][2];
;   if (MODE != 1) {
; #pragma unroll
;     for (int sub = 0; sub < 2; ++sub)
; #pragma unroll
;       for (int s2 = 0; s2 < 2; ++s2) {
;         vf[sub][s2][0] = *(const bf16x8*)(sVt + r * 72 + sub * 32 + s2 * 16 + 8 * h);
;         vf[sub][s2][1] = *(const bf16x8*)(sVt + (32 + r) * 72 + sub * 32 + s2 * 16 + 8 * h);
;       }
;     __builtin_amdgcn_sched_barrier(0);
;   }
;   float mxr = -3.0e38f;
; #pragma unroll
;   for (int sub = 0; sub < 2; ++sub)
; #pragma unroll
;     for (int q = 0; q < 16; ++q) {
;       if (MASKED) { const int kk = sub * 32 + 16 * (q >> 3) + 8 * h + (q & 7); s[sub][q] = mf(kk) ? s[sub][q] : -3.0e38f; }
;       if (MODE != 2) mxr = fmaxf(mxr, s[sub][q]);
;     }
;   float alpha = 1.f;
;   if (MODE != 2) {
;     float mx = fmaxf(m, mxr * sc);
;     mx = fmaxf(mx, shx(mx, 32));
;     if (!MASKED) mx = lanevalid ? mx : m;
;     alpha = fexp2(m - mx);
;     m = mx;
;   }
	v_mfma_f32_32x32x16_bf16 v[2:17], v[26:29], v[86:89], v[2:17]
	global_load_dwordx4 v[34:37], v[48:49], off
	global_load_dwordx4 v[38:41], v[44:45], off
	s_nop 0
	global_load_dwordx4 v[42:45], v[42:43], off
	s_nop 0
	global_load_dwordx4 v[46:49], v[46:47], off
	s_nop 5
	v_cndmask_b32_e64 v2, v2, v166, s[0:1]
	v_cmp_gt_u32_e64 s[0:1], v19, v136
	v_cmp_lt_f32_e32 vcc, s48, v2
	s_nop 0
	v_writelane_b32 v245, s0, 28
	s_nop 1
	v_writelane_b32 v245, s1, 29
	v_cndmask_b32_e64 v3, v3, v166, s[0:1]
	v_cmp_gt_u32_e64 s[0:1], v20, v136
	s_nop 1
	v_writelane_b32 v245, s0, 30
	s_nop 1
	v_writelane_b32 v245, s1, 31
	v_cndmask_b32_e64 v4, v4, v166, s[0:1]
	v_cmp_gt_u32_e64 s[0:1], v21, v136
	s_nop 1
	v_writelane_b32 v245, s0, 32
	s_nop 1
	v_writelane_b32 v245, s1, 33
	v_cndmask_b32_e64 v5, v5, v166, s[0:1]
	v_cmp_gt_u32_e64 s[0:1], v22, v136
	s_nop 1
	v_writelane_b32 v245, s0, 34
	s_nop 1
	v_writelane_b32 v245, s1, 35
	v_cndmask_b32_e64 v6, v6, v166, s[0:1]
	v_cmp_gt_u32_e64 s[0:1], v23, v136
	s_nop 1
	v_writelane_b32 v245, s0, 36
	s_nop 1
	v_writelane_b32 v245, s1, 37
	v_cndmask_b32_e64 v7, v7, v166, s[0:1]
	v_cmp_gt_u32_e64 s[0:1], v24, v136
	s_nop 1
	v_writelane_b32 v245, s0, 38
	s_nop 1
	v_writelane_b32 v245, s1, 39
	v_cndmask_b32_e64 v8, v8, v166, s[0:1]
	v_cmp_gt_u32_e64 s[0:1], v25, v136
	v_mfma_f32_32x32x16_bf16 v[18:33], v[30:33], v[74:77], 0
	s_nop 0
	v_writelane_b32 v245, s0, 40
	s_nop 1
	v_writelane_b32 v245, s1, 41
	v_cndmask_b32_e64 v9, v9, v166, s[0:1]
	v_cmp_gt_u32_e64 s[0:1], v58, v136
	v_or_b32_e32 v58, 0x12f, v59
	v_mfma_f32_32x32x16_bf16 v[18:33], v[62:65], v[78:81], v[18:33]
	v_writelane_b32 v245, s0, 42
	s_nop 1
	v_writelane_b32 v245, s1, 43
	v_cndmask_b32_e64 v10, v10, v166, s[0:1]
	v_cmp_gt_u32_e64 s[0:1], v58, v136
	v_or_b32_e32 v58, 0x13f, v59
	v_mfma_f32_32x32x16_bf16 v[18:33], v[66:69], v[82:85], v[18:33]
	v_writelane_b32 v245, s0, 44
	s_nop 1
	v_writelane_b32 v245, s1, 45
	v_cndmask_b32_e64 v11, v11, v166, s[0:1]
	v_cmp_gt_u32_e64 s[0:1], v58, v136
	v_or_b32_e32 v58, 0x14f, v59
	v_mfma_f32_32x32x16_bf16 v[18:33], v[70:73], v[86:89], v[18:33]
	v_writelane_b32 v245, s0, 46
	s_nop 1
	v_writelane_b32 v245, s1, 47
	v_cndmask_b32_e64 v12, v12, v166, s[0:1]
	v_cmp_gt_u32_e64 s[0:1], v58, v136
	v_or_b32_e32 v58, 0x15f, v59
	s_nop 0
	v_writelane_b32 v245, s0, 48
	s_nop 1
	v_writelane_b32 v245, s1, 49
	v_cndmask_b32_e64 v13, v13, v166, s[0:1]
	v_cmp_gt_u32_e64 s[0:1], v58, v136
	v_or_b32_e32 v58, 0x16f, v59
	s_nop 0
	v_writelane_b32 v245, s0, 50
	s_nop 1
	v_writelane_b32 v245, s1, 51
	v_cndmask_b32_e64 v14, v14, v166, s[0:1]
	v_cmp_gt_u32_e64 s[0:1], v58, v136
	v_or_b32_e32 v58, 0x17f, v60
	v_cmp_gt_u32_e64 s[52:53], v58, v136
	v_or_b32_e32 v58, 0x170, v60
	v_add_u32_e32 v58, 31, v58
	v_cmp_gt_u32_e64 s[58:59], v58, v136
	v_or_b32_e32 v58, 0x21f, v59
	v_cmp_gt_u32_e64 s[62:63], v58, v136
	v_or_b32_e32 v58, 0x22f, v59
	v_cmp_gt_u32_e64 s[64:65], v58, v136
	v_or_b32_e32 v58, 0x23f, v59
	v_cmp_gt_u32_e64 s[66:67], v58, v136
	v_or_b32_e32 v58, 0x24f, v59
	v_cmp_gt_u32_e64 s[68:69], v58, v136
	v_or_b32_e32 v58, 0x25f, v59
	v_cmp_gt_u32_e64 s[70:71], v58, v136
	v_or_b32_e32 v58, 0x26f, v59
	v_cmp_gt_u32_e64 s[74:75], v58, v136
	v_or_b32_e32 v58, 0x27f, v60
	v_cmp_gt_u32_e64 s[76:77], v58, v136
	v_or_b32_e32 v58, 0x270, v60
	v_add_u32_e32 v58, 31, v58
	v_cmp_gt_u32_e64 s[82:83], v58, v136
	v_or_b32_e32 v58, 0x31f, v59
	v_cmp_gt_u32_e64 s[84:85], v58, v136
	v_or_b32_e32 v58, 0x32f, v59
	v_cmp_gt_u32_e64 s[86:87], v58, v136
	v_or_b32_e32 v58, 0x33f, v59
	v_cmp_gt_u32_e64 s[90:91], v58, v136
	v_or_b32_e32 v58, 0x34f, v59
	v_cmp_gt_u32_e64 s[94:95], v58, v136
	v_or_b32_e32 v58, 0x35f, v59
	v_cmp_gt_u32_e64 s[96:97], v58, v136
	v_or_b32_e32 v58, 0x36f, v59
	v_cmp_gt_u32_e64 s[40:41], v58, v136
	v_or_b32_e32 v58, 0x37f, v60
	v_cmp_gt_u32_e64 s[36:37], v58, v136
	v_or_b32_e32 v58, 0x370, v60
	v_add_u32_e32 v58, 31, v58
	v_cmp_gt_u32_e64 s[34:35], v58, v136
	v_max3_f32 v58, v2, s8, v3
	v_max3_f32 v58, v58, v4, v5
	v_max3_f32 v58, v58, v6, v7
	v_max3_f32 v58, v58, v8, v9
	v_max3_f32 v58, v58, v10, v11
	v_writelane_b32 v245, s0, 52
	v_max3_f32 v58, v58, v12, v13
	v_cndmask_b32_e64 v16, v16, v166, s[52:53]
	v_cndmask_b32_e64 v15, v15, v166, s[0:1]
	v_cndmask_b32_e64 v17, v17, v166, s[58:59]
	v_max3_f32 v58, v58, v14, v15
	v_cndmask_b32_e64 v18, v18, v166, s[62:63]
	v_cndmask_b32_e64 v19, v19, v166, s[64:65]
	v_max3_f32 v58, v58, v16, v17
	v_cndmask_b32_e64 v20, v20, v166, s[66:67]
	v_cndmask_b32_e64 v21, v21, v166, s[68:69]
	v_max3_f32 v58, v58, v18, v19
	v_cndmask_b32_e64 v22, v22, v166, s[70:71]
	v_cndmask_b32_e64 v23, v23, v166, s[74:75]
	v_max3_f32 v58, v58, v20, v21
	v_cndmask_b32_e64 v24, v24, v166, s[76:77]
	v_cndmask_b32_e64 v25, v25, v166, s[82:83]
	v_max3_f32 v58, v58, v22, v23
	v_cndmask_b32_e64 v26, v26, v166, s[84:85]
	v_cndmask_b32_e64 v27, v27, v166, s[86:87]
	v_max3_f32 v58, v58, v24, v25
	v_cndmask_b32_e64 v28, v28, v166, s[90:91]
	v_cndmask_b32_e64 v29, v29, v166, s[94:95]
	v_max3_f32 v58, v58, v26, v27
	v_cndmask_b32_e64 v30, v30, v166, s[96:97]
	v_cndmask_b32_e64 v31, v31, v166, s[40:41]
	v_max3_f32 v58, v58, v28, v29
	v_cndmask_b32_e64 v32, v32, v166, s[36:37]
	v_cndmask_b32_e64 v33, v33, v166, s[34:35]
	v_max3_f32 v58, v58, v30, v31
	v_max3_f32 v58, v58, v32, v33
	v_mul_f32_e32 v58, 0x3e38aa3b, v58
	v_max_f32_e32 v58, 0xf149f2ca, v58
	ds_bpermute_b32 v61, v173, v58
	v_writelane_b32 v245, s1, 53
	s_waitcnt lgkmcnt(0)
; DI float fexp2(float x) { return __builtin_amdgcn_exp2f(x); }
; DI float shx(float v, int m) { return __shfl_xor(v, m, 64); }
; template <int DQK, bool MASKED, int MODE, class MF>
; DI void attn_step(const bf16_t* sK, const bf16_t* sVt, const bf16x8 (&qf)[DQK / 16], f32x16& o0, f32x16& o1, float& m, float& l,
;                   float sc, const MF& mf, int lane, f32x16 (&s)[2], float invl, bool lanevalid = true) {
;     ...
;   const float moff = (!MASKED && !lanevalid) ? 1.0e30f : m;
;   float ps = 0.f;
; #pragma unroll
;   for (int sub = 0; sub < 2; ++sub)
; #pragma unroll
;     for (int q = 0; q < 16; ++q) {
;       float pv = fexp2(__builtin_fmaf(s[sub][q], sc, -moff));
;       if (MASKED && MODE != 0) pv = (s[sub][q] > -1.0e38f) ? pv : 0.f;
;       if (MODE == 2) pv *= invl;
;       s[sub][q] = pv;
;       ps += pv;
;     }
;   if (MODE != 2) {
;     ps += shx(ps, 32);
;     l = l * alpha + ps;
;   }
	v_max_f32_e32 v61, v61, v61
	v_max_f32_e32 v58, v58, v61
	v_fma_f32 v61, v2, s33, -v58
	v_exp_f32_e32 v61, v61
	v_fma_f32 v62, v4, s33, -v58
	v_exp_f32_e32 v62, v62
	v_add_f32_e32 v61, 0, v61
	v_cndmask_b32_e32 v2, 0, v61, vcc
	v_fma_f32 v61, v3, s33, -v58
	v_exp_f32_e32 v61, v61
	v_cmp_lt_f32_e32 vcc, s48, v3
	s_nop 1
	v_cndmask_b32_e32 v3, 0, v61, vcc
	v_cmp_lt_f32_e32 vcc, s48, v4
	v_add_f32_e32 v2, v3, v2
	v_pk_fma_f32 v[222:223], v[6:7], s[32:33], v[58:59] op_sel:[0,1,0] op_sel_hi:[1,1,0] neg_lo:[0,0,1] neg_hi:[0,0,1]
	v_cndmask_b32_e32 v3, 0, v62, vcc
	v_add_f32_e32 v2, v3, v2
	v_fma_f32 v3, v5, s33, -v58
	v_exp_f32_e32 v3, v3
	v_exp_f32_e32 v4, v222
	v_cmp_lt_f32_e32 vcc, s48, v5
	s_nop 1
	v_cndmask_b32_e32 v3, 0, v3, vcc
	v_cmp_lt_f32_e32 vcc, s48, v6
	v_add_f32_e32 v2, v3, v2
	s_nop 0
	v_cndmask_b32_e32 v3, 0, v4, vcc
	v_add_f32_e32 v2, v3, v2
	v_exp_f32_e32 v3, v223
	v_pk_fma_f32 v[222:223], v[8:9], s[32:33], v[58:59] op_sel:[0,1,0] op_sel_hi:[1,1,0] neg_lo:[0,0,1] neg_hi:[0,0,1]
	v_exp_f32_e32 v4, v222
	v_cmp_lt_f32_e32 vcc, s48, v7
	s_nop 1
	v_cndmask_b32_e32 v3, 0, v3, vcc
	v_cmp_lt_f32_e32 vcc, s48, v8
	v_add_f32_e32 v2, v3, v2
	s_nop 0
	v_cndmask_b32_e32 v3, 0, v4, vcc
	v_add_f32_e32 v2, v3, v2
	v_exp_f32_e32 v3, v223
	v_pk_fma_f32 v[222:223], v[10:11], s[32:33], v[58:59] op_sel:[0,1,0] op_sel_hi:[1,1,0] neg_lo:[0,0,1] neg_hi:[0,0,1]
	v_exp_f32_e32 v4, v222
	v_cmp_lt_f32_e32 vcc, s48, v9
	s_nop 1
	v_cndmask_b32_e32 v3, 0, v3, vcc
	v_cmp_lt_f32_e32 vcc, s48, v10
	v_add_f32_e32 v2, v3, v2
	s_nop 0
	v_cndmask_b32_e32 v3, 0, v4, vcc
	v_add_f32_e32 v2, v3, v2
	v_exp_f32_e32 v3, v223
	v_pk_fma_f32 v[222:223], v[12:13], s[32:33], v[58:59] op_sel:[0,1,0] op_sel_hi:[1,1,0] neg_lo:[0,0,1] neg_hi:[0,0,1]
	v_exp_f32_e32 v4, v222
	v_cmp_lt_f32_e32 vcc, s48, v11
	s_nop 1
	v_cndmask_b32_e32 v3, 0, v3, vcc
	v_cmp_lt_f32_e32 vcc, s48, v12
	v_add_f32_e32 v2, v3, v2
	s_nop 0
	v_cndmask_b32_e32 v3, 0, v4, vcc
	v_add_f32_e32 v2, v3, v2
	v_exp_f32_e32 v3, v223
	v_pk_fma_f32 v[222:223], v[14:15], s[32:33], v[58:59] op_sel:[0,1,0] op_sel_hi:[1,1,0] neg_lo:[0,0,1] neg_hi:[0,0,1]
	v_exp_f32_e32 v4, v222
	v_cmp_lt_f32_e32 vcc, s48, v13
	s_nop 1
	v_cndmask_b32_e32 v3, 0, v3, vcc
	v_cmp_lt_f32_e32 vcc, s48, v14
	v_add_f32_e32 v2, v3, v2
	s_nop 0
	v_cndmask_b32_e32 v3, 0, v4, vcc
	v_add_f32_e32 v2, v3, v2
	v_exp_f32_e32 v3, v223
	v_pk_fma_f32 v[222:223], v[16:17], s[32:33], v[58:59] op_sel:[0,1,0] op_sel_hi:[1,1,0] neg_lo:[0,0,1] neg_hi:[0,0,1]
	v_exp_f32_e32 v4, v222
	v_cmp_lt_f32_e32 vcc, s48, v15
	s_nop 1
	v_cndmask_b32_e32 v3, 0, v3, vcc
	v_cmp_lt_f32_e32 vcc, s48, v16
	v_add_f32_e32 v2, v3, v2
	s_nop 0
	v_cndmask_b32_e32 v3, 0, v4, vcc
	v_add_f32_e32 v2, v3, v2
	v_exp_f32_e32 v3, v223
	v_pk_fma_f32 v[222:223], v[18:19], s[32:33], v[58:59] op_sel:[0,1,0] op_sel_hi:[1,1,0] neg_lo:[0,0,1] neg_hi:[0,0,1]
	v_exp_f32_e32 v4, v222
	v_cmp_lt_f32_e32 vcc, s48, v17
	s_nop 1
	v_cndmask_b32_e32 v3, 0, v3, vcc
	v_cmp_lt_f32_e32 vcc, s48, v18
	v_add_f32_e32 v2, v3, v2
	s_nop 0
	v_cndmask_b32_e32 v3, 0, v4, vcc
	v_add_f32_e32 v2, v3, v2
	v_exp_f32_e32 v3, v223
	v_cmp_lt_f32_e32 vcc, s48, v19
	v_pk_fma_f32 v[222:223], v[20:21], s[32:33], v[58:59] op_sel:[0,1,0] op_sel_hi:[1,1,0] neg_lo:[0,0,1] neg_hi:[0,0,1]
	v_exp_f32_e32 v4, v223
	v_cndmask_b32_e32 v3, 0, v3, vcc
	v_add_f32_e32 v2, v3, v2
	v_exp_f32_e32 v3, v222
	v_cmp_lt_f32_e32 vcc, s48, v20
	s_nop 1
	v_cndmask_b32_e32 v3, 0, v3, vcc
	v_cmp_lt_f32_e32 vcc, s48, v21
	v_add_f32_e32 v2, v3, v2
	s_nop 0
	v_cndmask_b32_e32 v3, 0, v4, vcc
	v_add_f32_e32 v2, v3, v2
	v_pk_fma_f32 v[222:223], v[22:23], s[32:33], v[58:59] op_sel:[0,1,0] op_sel_hi:[1,1,0] neg_lo:[0,0,1] neg_hi:[0,0,1]
	v_exp_f32_e32 v3, v222
	v_exp_f32_e32 v4, v223
	v_cmp_lt_f32_e32 vcc, s48, v22
	s_nop 1
	v_cndmask_b32_e32 v3, 0, v3, vcc
	v_cmp_lt_f32_e32 vcc, s48, v23
	v_add_f32_e32 v2, v3, v2
	s_nop 0
	v_cndmask_b32_e32 v3, 0, v4, vcc
	v_add_f32_e32 v2, v3, v2
	v_pk_fma_f32 v[222:223], v[24:25], s[32:33], v[58:59] op_sel:[0,1,0] op_sel_hi:[1,1,0] neg_lo:[0,0,1] neg_hi:[0,0,1]
	v_exp_f32_e32 v3, v222
	v_exp_f32_e32 v4, v223
	v_cmp_lt_f32_e32 vcc, s48, v24
	s_nop 1
	v_cndmask_b32_e32 v3, 0, v3, vcc
	v_cmp_lt_f32_e32 vcc, s48, v25
	v_add_f32_e32 v2, v3, v2
	s_nop 0
	v_cndmask_b32_e32 v3, 0, v4, vcc
	v_add_f32_e32 v2, v3, v2
	v_pk_fma_f32 v[222:223], v[26:27], s[32:33], v[58:59] op_sel:[0,1,0] op_sel_hi:[1,1,0] neg_lo:[0,0,1] neg_hi:[0,0,1]
	v_exp_f32_e32 v3, v222
	v_exp_f32_e32 v4, v223
	v_cmp_lt_f32_e32 vcc, s48, v26
	s_nop 1
	v_cndmask_b32_e32 v3, 0, v3, vcc
	v_cmp_lt_f32_e32 vcc, s48, v27
	v_add_f32_e32 v2, v3, v2
	s_nop 0
	v_cndmask_b32_e32 v3, 0, v4, vcc
	v_add_f32_e32 v2, v3, v2
	v_pk_fma_f32 v[222:223], v[28:29], s[32:33], v[58:59] op_sel:[0,1,0] op_sel_hi:[1,1,0] neg_lo:[0,0,1] neg_hi:[0,0,1]
	v_exp_f32_e32 v3, v222
	v_exp_f32_e32 v4, v223
	v_cmp_lt_f32_e32 vcc, s48, v28
	s_nop 1
	v_cndmask_b32_e32 v3, 0, v3, vcc
	v_cmp_lt_f32_e32 vcc, s48, v29
	v_add_f32_e32 v2, v3, v2
	s_nop 0
	v_cndmask_b32_e32 v3, 0, v4, vcc
	v_add_f32_e32 v2, v3, v2
	v_pk_fma_f32 v[222:223], v[30:31], s[32:33], v[58:59] op_sel:[0,1,0] op_sel_hi:[1,1,0] neg_lo:[0,0,1] neg_hi:[0,0,1]
	v_exp_f32_e32 v3, v222
	v_exp_f32_e32 v4, v223
	v_cmp_lt_f32_e32 vcc, s48, v30
	s_nop 1
	v_cndmask_b32_e32 v3, 0, v3, vcc
	v_cmp_lt_f32_e32 vcc, s48, v31
	v_add_f32_e32 v2, v3, v2
	s_nop 0
	v_cndmask_b32_e32 v3, 0, v4, vcc
	v_add_f32_e32 v2, v3, v2
	v_pk_fma_f32 v[222:223], v[32:33], s[32:33], v[58:59] op_sel:[0,1,0] op_sel_hi:[1,1,0] neg_lo:[0,0,1] neg_hi:[0,0,1]
	v_exp_f32_e32 v3, v222
	v_exp_f32_e32 v4, v223
	v_cmp_lt_f32_e32 vcc, s48, v32
	s_nop 1
	v_cndmask_b32_e32 v3, 0, v3, vcc
	v_cmp_lt_f32_e32 vcc, s48, v33
	v_add_f32_e32 v2, v3, v2
	s_nop 0
	v_cndmask_b32_e32 v3, 0, v4, vcc
	v_add_f32_e32 v2, v3, v2
	ds_bpermute_b32 v3, v173, v2
	v_sub_f32_e32 v4, 0xf149f2ca, v58
	v_exp_f32_e32 v4, v4
	s_waitcnt lgkmcnt(0)
; template <int DQK, bool MASKED, int MODE, class MF>
; DI void attn_step(const bf16_t* sK, const bf16_t* sVt, const bf16x8 (&qf)[DQK / 16], f32x16& o0, f32x16& o1, float& m, float& l,
;                   float sc, const MF& mf, int lane, f32x16 (&s)[2], float invl, bool lanevalid = true) {
;     ...
;   for (int sub = 0; sub < 2; ++sub)
; #pragma unroll
;     for (int ks = 0; ks < DQK / 16; ++ks) kf[sub][ks] = *(const bf16x8*)(sK + (sub * 32 + pr) * KST + ks * 16 + 8 * h);
;   __builtin_amdgcn_sched_barrier(0);
; #pragma unroll
;   for (int q = 0; q < 16; ++q) { s[0][q] = 0.f; s[1][q] = 0.f; }
; #pragma unroll
;   for (int ks = 0; ks < DQK / 16; ++ks) {
;     s[0] = MFMA(kf[0][ks], qf[ks], s[0]);
;     s[1] = MFMA(kf[1][ks], qf[ks], s[1]);
;   }
;   bf16x8 vf[2][2][2];
;   if (MODE != 1) {
; #pragma unroll
;     for (int sub = 0; sub < 2; ++sub)
; #pragma unroll
;       for (int s2 = 0; s2 < 2; ++s2) {
;         vf[sub][s2][0] = *(const bf16x8*)(sVt + r * 72 + sub * 32 + s2 * 16 + 8 * h);
;         vf[sub][s2][1] = *(const bf16x8*)(sVt + (32 + r) * 72 + sub * 32 + s2 * 16 + 8 * h);
;       }
;     __builtin_amdgcn_sched_barrier(0);
;   }
;   float mxr = -3.0e38f;
; #pragma unroll
;   for (int sub = 0; sub < 2; ++sub)
; #pragma unroll
;     for (int q = 0; q < 16; ++q) {
;       if (MASKED) { const int kk = sub * 32 + 16 * (q >> 3) + 8 * h + (q & 7); s[sub][q] = mf(kk) ? s[sub][q] : -3.0e38f; }
;       if (MODE != 2) mxr = fmaxf(mxr, s[sub][q]);
;     }
;   float alpha = 1.f;
;   if (MODE != 2) {
;     float mx = fmaxf(m, mxr * sc);
;     mx = fmaxf(mx, shx(mx, 32));
;     if (!MASKED) mx = lanevalid ? mx : m;
; DI void phase_attn_nsa(const Params& P, bf16_t* og, unsigned char* smem, int L, int G) {
;     ...
; #pragma unroll
;       for (int tile = 0; tile < 2; ++tile) {
;         const int key0 = tile * 64;
;         kv64_commit(R, sK, sVt, false, tid);
;         if (tile == 0) kv64_fetch(R, kb, 64, vb, 128, 64, false, tid); else kv64_fetch(R, kb, 64, vb, 128, 0, true, tid);
;         __builtin_amdgcn_sched_barrier(0);
;         auto mf = [&](int kk) { return (key0 + kk) * 16 + 31 <= t; };
;         attn_step<64, true, 1>(sK, sVt, qf, o0, o1, m, l, sc, mf, lane, s, 0.f);
;       }
;       const float invl = l > 0.f ? 1.f / l : 0.f;
;       o_zero(o0, o1);
;       float cprev = 0.f;
; #pragma unroll
;       for (int tile = 0; tile < 2; ++tile) {
	v_add_f32_e32 v61, v2, v3
	v_fmac_f32_e32 v61, 0, v4
	ds_read_b128 v[2:5], v172
	ds_read_b128 v[18:21], v172 offset:32
	ds_read_b128 v[22:25], v172 offset:64
	ds_read_b128 v[26:29], v172 offset:96
	ds_read_b128 v[30:33], v172 offset:4608
	ds_read_b128 v[62:65], v172 offset:4640
	ds_read_b128 v[66:69], v172 offset:4672
	ds_read_b128 v[70:73], v172 offset:4704
	s_waitcnt lgkmcnt(7)
	v_mfma_f32_32x32x16_bf16 v[2:17], v[2:5], v[74:77], 0
	v_or_b32_e32 v90, 0x51f, v59
	v_cmp_gt_u32_e64 s[60:61], v90, v136
	v_or_b32_e32 v90, 0x53f, v59
	v_or_b32_e32 v91, 0x52f, v59
	v_cmp_gt_u32_e64 s[78:79], v90, v136
	v_or_b32_e32 v90, 0x54f, v59
	v_cmp_gt_u32_e64 s[72:73], v91, v136
	s_waitcnt lgkmcnt(6)
	v_mfma_f32_32x32x16_bf16 v[2:17], v[18:21], v[78:81], v[2:17]
	v_or_b32_e32 v18, 0x41f, v59
	v_cmp_gt_u32_e64 s[0:1], v18, v136
	v_or_b32_e32 v19, 0x42f, v59
	v_or_b32_e32 v20, 0x43f, v59
	v_writelane_b32 v245, s0, 54
	v_or_b32_e32 v21, 0x44f, v59
	v_cmp_gt_u32_e64 s[80:81], v90, v136
	s_waitcnt lgkmcnt(5)
	v_mfma_f32_32x32x16_bf16 v[2:17], v[22:25], v[82:85], v[2:17]
	v_writelane_b32 v245, s1, 55
	v_or_b32_e32 v22, 0x45f, v59
	v_or_b32_e32 v25, 0x470, v60
	v_or_b32_e32 v23, 0x46f, v59
	v_or_b32_e32 v24, 0x47f, v60
	v_add_u32_e32 v25, 31, v25
	v_cmp_gt_u32_e64 s[54:55], v24, v136
	s_waitcnt lgkmcnt(4)
	v_mfma_f32_32x32x16_bf16 v[2:17], v[26:29], v[86:89], v[2:17]
	v_cmp_gt_u32_e64 s[56:57], v25, v136
	s_waitcnt lgkmcnt(0)
	s_barrier
	s_waitcnt vmcnt(0)
	ds_write_b128 v170, v[46:49]
	ds_write_b128 v170, v[42:45] offset:4608
	ds_write_b128 v170, v[38:41] offset:9216
	ds_write_b128 v170, v[34:37] offset:13824
	s_waitcnt lgkmcnt(0)
	s_barrier
	s_nop 1
	v_cndmask_b32_e64 v2, v2, v166, s[0:1]
	v_cmp_gt_u32_e64 s[0:1], v19, v136
	v_cndmask_b32_e64 v8, v8, v166, s[54:55]
	v_cndmask_b32_e64 v9, v9, v166, s[56:57]
	v_writelane_b32 v245, s0, 56
	v_cndmask_b32_e64 v10, v10, v166, s[60:61]
	v_cndmask_b32_e64 v11, v11, v166, s[72:73]
	v_writelane_b32 v245, s1, 57
	v_cndmask_b32_e64 v3, v3, v166, s[0:1]
	v_cmp_gt_u32_e64 s[0:1], v20, v136
	v_cndmask_b32_e64 v12, v12, v166, s[78:79]
	v_cndmask_b32_e64 v13, v13, v166, s[80:81]
	v_writelane_b32 v245, s0, 58
	v_cmp_lt_f32_e32 vcc, s48, v2
	s_nop 0
	v_writelane_b32 v245, s1, 59
	v_cndmask_b32_e64 v4, v4, v166, s[0:1]
	v_cmp_gt_u32_e64 s[0:1], v21, v136
	v_or_b32_e32 v126, 32, v137
	v_mad_u32_u24 v98, v118, s47, v57
	v_writelane_b32 v245, s0, 60
	v_mad_u32_u24 v129, v126, s47, v57
	s_nop 0
	v_writelane_b32 v245, s1, 61
	v_cndmask_b32_e64 v5, v5, v166, s[0:1]
	v_cmp_gt_u32_e64 s[0:1], v22, v136
	s_nop 1
	v_writelane_b32 v245, s0, 62
	s_nop 1
	v_writelane_b32 v245, s1, 63
	v_cndmask_b32_e64 v6, v6, v166, s[0:1]
	v_cmp_gt_u32_e64 s[0:1], v23, v136
	v_mfma_f32_32x32x16_bf16 v[18:33], v[30:33], v[74:77], 0
	s_nop 0
	v_writelane_b32 v244, s0, 0
	s_nop 1
	v_writelane_b32 v244, s1, 1
	v_cndmask_b32_e64 v7, v7, v166, s[0:1]
	v_mfma_f32_32x32x16_bf16 v[18:33], v[62:65], v[78:81], v[18:33]
	v_or_b32_e32 v62, 0x55f, v59
	v_cmp_gt_u32_e64 s[88:89], v62, v136
	v_or_b32_e32 v62, 0x56f, v59
	v_cmp_gt_u32_e64 s[92:93], v62, v136
	v_or_b32_e32 v62, 0x57f, v60
	v_cmp_gt_u32_e64 s[42:43], v62, v136
	v_or_b32_e32 v62, 0x570, v60
	v_add_u32_e32 v62, 31, v62
	v_cmp_gt_u32_e64 s[38:39], v62, v136
	v_or_b32_e32 v62, 0x61f, v59
	v_cmp_gt_u32_e64 s[30:31], v62, v136
	v_or_b32_e32 v62, 0x62f, v59
	v_cmp_gt_u32_e64 s[28:29], v62, v136
	v_or_b32_e32 v62, 0x63f, v59
	v_cmp_gt_u32_e64 s[26:27], v62, v136
	v_or_b32_e32 v62, 0x64f, v59
	v_cmp_gt_u32_e64 s[16:17], v62, v136
	v_or_b32_e32 v62, 0x65f, v59
	v_cmp_gt_u32_e64 s[18:19], v62, v136
	v_or_b32_e32 v62, 0x66f, v59
	v_cmp_gt_u32_e64 s[20:21], v62, v136
	v_or_b32_e32 v62, 0x67f, v60
	v_cmp_gt_u32_e64 s[22:23], v62, v136
	v_or_b32_e32 v62, 0x670, v60
	v_mfma_f32_32x32x16_bf16 v[18:33], v[66:69], v[82:85], v[18:33]
	v_add_u32_e32 v62, 31, v62
	v_cmp_gt_u32_e64 s[24:25], v62, v136
	v_or_b32_e32 v62, 0x71f, v59
	v_cmp_gt_u32_e64 s[14:15], v62, v136
	v_or_b32_e32 v62, 0x72f, v59
	v_cmp_gt_u32_e64 s[12:13], v62, v136
	v_or_b32_e32 v62, 0x73f, v59
	v_cmp_gt_u32_e64 s[10:11], v62, v136
	v_or_b32_e32 v62, 0x74f, v59
	v_cmp_gt_u32_e64 s[8:9], v62, v136
	v_or_b32_e32 v62, 0x75f, v59
	v_or_b32_e32 v59, 0x76f, v59
	v_cmp_gt_u32_e64 s[4:5], v59, v136
	v_or_b32_e32 v59, 0x77f, v60
	v_cmp_gt_u32_e64 s[2:3], v59, v136
	v_or_b32_e32 v59, 0x770, v60
	v_mfma_f32_32x32x16_bf16 v[18:33], v[70:73], v[86:89], v[18:33]
	v_add_u32_e32 v59, 31, v59
	v_cmp_gt_u32_e64 s[0:1], v59, v136
	v_max3_f32 v59, v2, s49, v3
	v_max3_f32 v59, v59, v4, v5
	v_max3_f32 v59, v59, v6, v7
	v_max3_f32 v59, v59, v8, v9
	v_max3_f32 v59, v59, v10, v11
	v_cndmask_b32_e64 v14, v14, v166, s[88:89]
	v_cndmask_b32_e64 v15, v15, v166, s[92:93]
	v_max3_f32 v59, v59, v12, v13
	v_cndmask_b32_e64 v16, v16, v166, s[42:43]
	v_cndmask_b32_e64 v17, v17, v166, s[38:39]
	v_max3_f32 v59, v59, v14, v15
	v_cndmask_b32_e64 v18, v18, v166, s[30:31]
	v_cndmask_b32_e64 v19, v19, v166, s[28:29]
	v_max3_f32 v59, v59, v16, v17
	v_cndmask_b32_e64 v20, v20, v166, s[26:27]
	v_cndmask_b32_e64 v21, v21, v166, s[16:17]
	v_max3_f32 v59, v59, v18, v19
	v_cndmask_b32_e64 v22, v22, v166, s[18:19]
	v_cndmask_b32_e64 v23, v23, v166, s[20:21]
	v_max3_f32 v59, v59, v20, v21
	v_cndmask_b32_e64 v24, v24, v166, s[22:23]
	v_cndmask_b32_e64 v25, v25, v166, s[24:25]
	v_max3_f32 v59, v59, v22, v23
	v_cndmask_b32_e64 v26, v26, v166, s[14:15]
	v_cndmask_b32_e64 v27, v27, v166, s[12:13]
	v_max3_f32 v59, v59, v24, v25
	v_cndmask_b32_e64 v28, v28, v166, s[10:11]
	v_cndmask_b32_e64 v29, v29, v166, s[8:9]
	v_cmp_gt_u32_e64 s[6:7], v62, v136
	v_max3_f32 v59, v59, v26, v27
	v_cndmask_b32_e64 v31, v31, v166, s[4:5]
	v_cndmask_b32_e64 v30, v30, v166, s[6:7]
	v_max3_f32 v59, v59, v28, v29
	v_cndmask_b32_e64 v32, v32, v166, s[2:3]
	v_cndmask_b32_e64 v33, v33, v166, s[0:1]
	v_max3_f32 v59, v59, v30, v31
	v_max3_f32 v59, v59, v32, v33
	v_mul_f32_e32 v59, 0x3e38aa3b, v59
	v_max_f32_e32 v59, v58, v59
	ds_bpermute_b32 v60, v173, v59
	s_waitcnt lgkmcnt(0)
; DI float fexp2(float x) { return __builtin_amdgcn_exp2f(x); }
; DI float shx(float v, int m) { return __shfl_xor(v, m, 64); }
; template <int DQK, bool MASKED, int MODE, class MF>
; DI void attn_step(const bf16_t* sK, const bf16_t* sVt, const bf16x8 (&qf)[DQK / 16], f32x16& o0, f32x16& o1, float& m, float& l,
;                   float sc, const MF& mf, int lane, f32x16 (&s)[2], float invl, bool lanevalid = true) {
;     ...
;   const float moff = (!MASKED && !lanevalid) ? 1.0e30f : m;
;   float ps = 0.f;
; #pragma unroll
;   for (int sub = 0; sub < 2; ++sub)
; #pragma unroll
;     for (int q = 0; q < 16; ++q) {
;       float pv = fexp2(__builtin_fmaf(s[sub][q], sc, -moff));
;       if (MASKED && MODE != 0) pv = (s[sub][q] > -1.0e38f) ? pv : 0.f;
;       if (MODE == 2) pv *= invl;
;       s[sub][q] = pv;
;       ps += pv;
;     }
;   if (MODE != 2) {
;     ps += shx(ps, 32);
;     l = l * alpha + ps;
;   }
; DI void phase_attn_nsa(const Params& P, bf16_t* og, unsigned char* smem, int L, int G) {
;     ...
;         if (tile == 0) kv64_fetch(R, kb, 64, vb, 128, 64, true, tid);
	v_max_f32_e32 v60, v60, v60
	v_max_f32_e32 v127, v59, v60
	v_fma_f32 v59, v2, s33, -v127
	v_exp_f32_e32 v59, v59
	v_fma_f32 v60, v3, s33, -v127
	v_exp_f32_e32 v60, v60
	v_add_f32_e32 v59, 0, v59
	v_cndmask_b32_e32 v2, 0, v59, vcc
	v_cmp_lt_f32_e32 vcc, s48, v3
	v_fma_f32 v59, v5, s33, -v127
	v_exp_f32_e32 v59, v59
	v_cndmask_b32_e32 v3, 0, v60, vcc
	v_add_f32_e32 v2, v3, v2
	v_fma_f32 v3, v4, s33, -v127
	v_exp_f32_e32 v3, v3
	v_cmp_lt_f32_e32 vcc, s48, v4
	v_fma_f32 v4, v7, s33, -v127
	v_exp_f32_e32 v4, v4
	v_cndmask_b32_e32 v3, 0, v3, vcc
	v_cmp_lt_f32_e32 vcc, s48, v5
	v_add_f32_e32 v2, v3, v2
	s_nop 0
	v_cndmask_b32_e32 v3, 0, v59, vcc
	v_add_f32_e32 v2, v3, v2
	v_fma_f32 v3, v6, s33, -v127
	v_exp_f32_e32 v3, v3
	v_cmp_lt_f32_e32 vcc, s48, v6
	s_nop 1
	v_cndmask_b32_e32 v3, 0, v3, vcc
	v_cmp_lt_f32_e32 vcc, s48, v7
	v_add_f32_e32 v2, v3, v2
	s_nop 0
	v_cndmask_b32_e32 v3, 0, v4, vcc
	v_add_f32_e32 v2, v3, v2
	v_fma_f32 v3, v8, s33, -v127
	v_exp_f32_e32 v3, v3
	v_fma_f32 v4, v9, s33, -v127
	v_exp_f32_e32 v4, v4
	v_cmp_lt_f32_e32 vcc, s48, v8
	s_nop 1
	v_cndmask_b32_e32 v3, 0, v3, vcc
	v_cmp_lt_f32_e32 vcc, s48, v9
	v_add_f32_e32 v2, v3, v2
	s_nop 0
	v_cndmask_b32_e32 v3, 0, v4, vcc
	v_add_f32_e32 v2, v3, v2
	v_fma_f32 v3, v10, s33, -v127
	v_exp_f32_e32 v3, v3
	v_fma_f32 v4, v11, s33, -v127
	v_exp_f32_e32 v4, v4
	v_cmp_lt_f32_e32 vcc, s48, v10
	s_nop 1
	v_cndmask_b32_e32 v3, 0, v3, vcc
	v_cmp_lt_f32_e32 vcc, s48, v11
	v_add_f32_e32 v2, v3, v2
	s_nop 0
	v_cndmask_b32_e32 v3, 0, v4, vcc
	v_add_f32_e32 v2, v3, v2
	v_fma_f32 v3, v12, s33, -v127
	v_exp_f32_e32 v3, v3
	v_fma_f32 v4, v13, s33, -v127
	v_exp_f32_e32 v4, v4
	v_cmp_lt_f32_e32 vcc, s48, v12
	s_nop 1
	v_cndmask_b32_e32 v3, 0, v3, vcc
	v_cmp_lt_f32_e32 vcc, s48, v13
	v_add_f32_e32 v2, v3, v2
	s_nop 0
	v_cndmask_b32_e32 v3, 0, v4, vcc
	v_add_f32_e32 v2, v3, v2
	v_fma_f32 v3, v14, s33, -v127
	v_exp_f32_e32 v3, v3
	v_fma_f32 v4, v15, s33, -v127
	v_exp_f32_e32 v4, v4
	v_cmp_lt_f32_e32 vcc, s48, v14
	s_nop 1
	v_cndmask_b32_e32 v3, 0, v3, vcc
	v_cmp_lt_f32_e32 vcc, s48, v15
	v_add_f32_e32 v2, v3, v2
	s_nop 0
	v_cndmask_b32_e32 v3, 0, v4, vcc
	v_add_f32_e32 v2, v3, v2
	v_pk_fma_f32 v[224:225], v[16:17], s[32:33], v[126:127] op_sel:[0,1,1] op_sel_hi:[1,1,1] neg_lo:[0,0,1] neg_hi:[0,0,1]
	v_exp_f32_e32 v3, v224
	v_exp_f32_e32 v4, v225
	v_cmp_lt_f32_e32 vcc, s48, v16
	s_nop 1
	v_cndmask_b32_e32 v3, 0, v3, vcc
	v_cmp_lt_f32_e32 vcc, s48, v17
	v_add_f32_e32 v2, v3, v2
	s_nop 0
	v_cndmask_b32_e32 v3, 0, v4, vcc
	v_add_f32_e32 v2, v3, v2
	v_fma_f32 v3, v18, s33, -v127
	v_exp_f32_e32 v3, v3
	v_fma_f32 v4, v19, s33, -v127
	v_exp_f32_e32 v4, v4
	v_cmp_lt_f32_e32 vcc, s48, v18
	s_nop 1
	v_cndmask_b32_e32 v3, 0, v3, vcc
	v_cmp_lt_f32_e32 vcc, s48, v19
	v_add_f32_e32 v2, v3, v2
	s_nop 0
	v_cndmask_b32_e32 v3, 0, v4, vcc
	v_add_f32_e32 v2, v3, v2
	v_fma_f32 v3, v20, s33, -v127
	v_exp_f32_e32 v3, v3
	v_fma_f32 v4, v21, s33, -v127
	v_exp_f32_e32 v4, v4
	v_cmp_lt_f32_e32 vcc, s48, v20
	s_nop 1
	v_cndmask_b32_e32 v3, 0, v3, vcc
	v_cmp_lt_f32_e32 vcc, s48, v21
	v_add_f32_e32 v2, v3, v2
	s_nop 0
	v_cndmask_b32_e32 v3, 0, v4, vcc
	v_add_f32_e32 v2, v3, v2
	v_fma_f32 v3, v22, s33, -v127
	v_exp_f32_e32 v3, v3
	v_fma_f32 v4, v23, s33, -v127
	v_exp_f32_e32 v4, v4
	v_cmp_lt_f32_e32 vcc, s48, v22
	s_nop 1
	v_cndmask_b32_e32 v3, 0, v3, vcc
	v_cmp_lt_f32_e32 vcc, s48, v23
	v_add_f32_e32 v2, v3, v2
	s_nop 0
	v_cndmask_b32_e32 v3, 0, v4, vcc
	v_add_f32_e32 v6, v3, v2
	v_fma_f32 v2, v24, s33, -v127
	v_exp_f32_e32 v7, v2
	v_fma_f32 v2, v25, s33, -v127
	v_exp_f32_e32 v8, v2
	v_lshl_add_u64 v[2:3], v[52:53], 0, v[54:55]
	v_lshl_add_u64 v[2:3], v[2:3], 0, v[140:141]
	v_lshl_add_u64 v[4:5], v[52:53], 0, v[0:1]
	v_lshl_add_u64 v[4:5], v[4:5], 0, v[140:141]
	global_load_dwordx4 v[34:37], v[2:3], off offset:128
	global_load_dwordx4 v[38:41], v[4:5], off offset:128
	global_load_dwordx4 v[42:45], v[50:51], off
	global_load_dwordx4 v[46:49], v[50:51], off offset:-4096
	v_cmp_lt_f32_e32 vcc, s48, v24
	v_fma_f32 v3, v27, s33, -v127
	v_exp_f32_e32 v3, v3
	v_cndmask_b32_e32 v0, 0, v7, vcc
	v_cmp_lt_f32_e32 vcc, s48, v25
	v_add_f32_e32 v0, v0, v6
	s_nop 0
	v_cndmask_b32_e32 v2, 0, v8, vcc
	v_add_f32_e32 v0, v2, v0
	v_fma_f32 v2, v26, s33, -v127
	v_exp_f32_e32 v2, v2
	v_cmp_lt_f32_e32 vcc, s48, v26
	s_nop 1
	v_cndmask_b32_e32 v2, 0, v2, vcc
	v_cmp_lt_f32_e32 vcc, s48, v27
	v_add_f32_e32 v0, v2, v0
	s_nop 0
	v_cndmask_b32_e32 v2, 0, v3, vcc
	v_add_f32_e32 v0, v2, v0
	v_fma_f32 v2, v28, s33, -v127
	v_exp_f32_e32 v2, v2
	v_fma_f32 v3, v29, s33, -v127
	v_exp_f32_e32 v3, v3
	v_cmp_lt_f32_e32 vcc, s48, v28
	s_nop 1
	v_cndmask_b32_e32 v2, 0, v2, vcc
	v_cmp_lt_f32_e32 vcc, s48, v29
	v_add_f32_e32 v0, v2, v0
	s_nop 0
	v_cndmask_b32_e32 v2, 0, v3, vcc
	v_add_f32_e32 v0, v2, v0
	v_fma_f32 v2, v30, s33, -v127
	v_exp_f32_e32 v2, v2
	v_fma_f32 v3, v31, s33, -v127
	v_exp_f32_e32 v3, v3
	v_cmp_lt_f32_e32 vcc, s48, v30
	s_nop 1
	v_cndmask_b32_e32 v2, 0, v2, vcc
	v_cmp_lt_f32_e32 vcc, s48, v31
	v_add_f32_e32 v0, v2, v0
	s_nop 0
	v_cndmask_b32_e32 v2, 0, v3, vcc
	v_add_f32_e32 v0, v2, v0
	v_fma_f32 v2, v32, s33, -v127
	v_exp_f32_e32 v2, v2
	v_fma_f32 v3, v33, s33, -v127
	v_exp_f32_e32 v3, v3
	v_cmp_lt_f32_e32 vcc, s48, v32
	s_nop 1
	v_cndmask_b32_e32 v2, 0, v2, vcc
	v_cmp_lt_f32_e32 vcc, s48, v33
	v_add_f32_e32 v0, v2, v0
	s_nop 0
	v_cndmask_b32_e32 v2, 0, v3, vcc
	v_add_f32_e32 v0, v2, v0
	ds_bpermute_b32 v2, v173, v0
	v_sub_f32_e32 v3, v58, v127
	v_exp_f32_e32 v3, v3
	s_waitcnt lgkmcnt(0)
; DI float fexp2(float x) { return __builtin_amdgcn_exp2f(x); }
; template <int DQK, bool MASKED, int MODE, class MF>
; DI void attn_step(const bf16_t* sK, const bf16_t* sVt, const bf16x8 (&qf)[DQK / 16], f32x16& o0, f32x16& o1, float& m, float& l,
;                   float sc, const MF& mf, int lane, f32x16 (&s)[2], float invl, bool lanevalid = true) {
;     ...
;   const float moff = (!MASKED && !lanevalid) ? 1.0e30f : m;
;   float ps = 0.f;
; #pragma unroll
;   for (int sub = 0; sub < 2; ++sub)
; #pragma unroll
;     for (int q = 0; q < 16; ++q) {
;       float pv = fexp2(__builtin_fmaf(s[sub][q], sc, -moff));
;       if (MASKED && MODE != 0) pv = (s[sub][q] > -1.0e38f) ? pv : 0.f;
;       if (MODE == 2) pv *= invl;
;       s[sub][q] = pv;
;       ps += pv;
;     }
; DI void phase_attn_nsa(const Params& P, bf16_t* og, unsigned char* smem, int L, int G) {
;     ...
;       const float invl = l > 0.f ? 1.f / l : 0.f;
;       o_zero(o0, o1);
;       float cprev = 0.f;
; #pragma unroll
;       for (int tile = 0; tile < 2; ++tile) {
;         const int key0 = tile * 64;
;         kv64_commit(R, sK, sVt, true, tid);
;         if (tile == 0) kv64_fetch(R, kb, 64, vb, 128, 64, true, tid);
;         __builtin_amdgcn_sched_barrier(0);
;         auto mf = [&](int kk) { return (key0 + kk) * 16 + 31 <= t; };
;         float l2 = 0.f;
;         attn_step<64, true, 2>(sK, sVt, qf, o0, o1, m, l2, sc, mf, lane, s, invl);
	v_add_f32_e32 v0, v0, v2
	v_fmac_f32_e32 v0, v3, v61
	v_div_scale_f32 v2, vcc, v0, v0, 1.0
	v_rcp_f32_e32 v3, v2
	s_nop 0
	v_fma_f32 v4, -v2, v3, 1.0
	v_fmac_f32_e32 v3, v4, v3
	v_div_scale_f32 v4, vcc, 1.0, v0, 1.0
	v_mul_f32_e32 v5, v4, v3
	v_fma_f32 v6, -v2, v5, v4
	v_fmac_f32_e32 v5, v6, v3
	v_fma_f32 v2, -v2, v5, v4
	v_div_fmas_f32 v2, v2, v3, v5
	v_div_fixup_f32 v2, v2, v0, 1.0
	v_cmp_lt_f32_e32 vcc, 0, v0
	s_nop 1
	v_cndmask_b32_e32 v0, 0, v2, vcc
	v_lshl_or_b32 v2, v168, 5, v118
	v_mul_u32_u24_e32 v2, 0x84, v2
	v_add3_u32 v128, v153, v2, v56
	v_cmp_gt_u32_e32 vcc, 32, v137
	v_add_u32_e32 v99, 0x9200, v128
	ds_read_b128 v[2:5], v172
	ds_read_b128 v[50:53], v172 offset:32
	ds_read_b128 v[54:57], v172 offset:64
	ds_read_b128 v[58:61], v172 offset:96
	ds_read_b128 v[6:9], v172 offset:4608
	ds_read_b128 v[62:65], v172 offset:4640
	ds_read_b128 v[66:69], v172 offset:4672
	ds_read_b128 v[70:73], v172 offset:4704
	s_waitcnt lgkmcnt(7)
	v_mfma_f32_32x32x16_bf16 v[18:33], v[2:5], v[74:77], 0
	s_waitcnt lgkmcnt(3)
	v_mfma_f32_32x32x16_bf16 v[2:17], v[6:9], v[74:77], 0
	v_mfma_f32_32x32x16_bf16 v[18:33], v[50:53], v[78:81], v[18:33]
	s_waitcnt lgkmcnt(2)
	v_mfma_f32_32x32x16_bf16 v[2:17], v[62:65], v[78:81], v[2:17]
	v_mfma_f32_32x32x16_bf16 v[18:33], v[54:57], v[82:85], v[18:33]
	s_waitcnt lgkmcnt(1)
	v_mfma_f32_32x32x16_bf16 v[2:17], v[66:69], v[82:85], v[2:17]
	v_mfma_f32_32x32x16_bf16 v[18:33], v[58:61], v[86:89], v[18:33]
	s_waitcnt lgkmcnt(0)
	v_mfma_f32_32x32x16_bf16 v[2:17], v[70:73], v[86:89], v[2:17]
	ds_read_b128 v[94:97], v98 offset:9216
	ds_read_b128 v[90:93], v98 offset:9248
	ds_read_b128 v[62:65], v129 offset:9216
	ds_read_b128 v[58:61], v129 offset:9248
	ds_read_b128 v[70:73], v98 offset:9280
	ds_read_b128 v[54:57], v129 offset:9280
	ds_read_b128 v[66:69], v98 offset:9312
	ds_read_b128 v[50:53], v129 offset:9312
	v_readlane_b32 s50, v245, 26
	v_readlane_b32 s51, v245, 27
	s_nop 1
	v_cndmask_b32_e64 v100, v16, v166, s[36:37]
	v_cndmask_b32_e64 v101, v17, v166, s[34:35]
	v_cndmask_b32_e64 v18, v18, v166, s[50:51]
	v_readlane_b32 s50, v245, 28
	v_readlane_b32 s51, v245, 29
	v_fma_f32 v16, v18, s33, -v127
	v_exp_f32_e32 v16, v16
	v_cndmask_b32_e64 v19, v19, v166, s[50:51]
	v_fma_f32 v17, v19, s33, -v127
	v_exp_f32_e32 v17, v17
	v_readlane_b32 s50, v245, 30
	v_readlane_b32 s51, v245, 31
	v_cmp_lt_f32_e64 s[34:35], s48, v18
	v_cndmask_b32_e64 v32, v32, v166, s[52:53]
	v_cndmask_b32_e64 v20, v20, v166, s[50:51]
	v_readlane_b32 s50, v245, 32
	v_cndmask_b32_e64 v102, 0, v16, s[34:35]
	v_cmp_lt_f32_e64 s[34:35], s48, v19
	v_readlane_b32 s51, v245, 33
	v_cndmask_b32_e64 v33, v33, v166, s[58:59]
	v_cndmask_b32_e64 v17, 0, v17, s[34:35]
	v_cndmask_b32_e64 v21, v21, v166, s[50:51]
	v_mul_f32_e32 v103, v17, v0
	v_pk_fma_f32 v[224:225], v[20:21], s[32:33], v[126:127] op_sel:[0,1,1] op_sel_hi:[1,1,1] neg_lo:[0,0,1] neg_hi:[0,0,1]
	v_exp_f32_e32 v17, v224
	v_readlane_b32 s50, v245, 34
	v_exp_f32_e32 v18, v225
	v_readlane_b32 s51, v245, 35
	v_cmp_lt_f32_e64 s[34:35], s48, v20
	v_cndmask_b32_e64 v2, v2, v166, s[62:63]
	v_cndmask_b32_e64 v22, v22, v166, s[50:51]
	v_readlane_b32 s50, v245, 36
	v_readlane_b32 s51, v245, 37
	v_cndmask_b32_e64 v104, 0, v17, s[34:35]
	v_cmp_lt_f32_e64 s[34:35], s48, v21
	v_cndmask_b32_e64 v23, v23, v166, s[50:51]
	v_pk_fma_f32 v[224:225], v[22:23], s[32:33], v[126:127] op_sel:[0,1,1] op_sel_hi:[1,1,1] neg_lo:[0,0,1] neg_hi:[0,0,1]
	v_cndmask_b32_e64 v105, 0, v18, s[34:35]
	v_exp_f32_e32 v18, v224
	v_exp_f32_e32 v20, v225
	v_readlane_b32 s50, v245, 38
	v_readlane_b32 s51, v245, 39
	v_cmp_lt_f32_e64 s[34:35], s48, v22
	v_cndmask_b32_e64 v3, v3, v166, s[64:65]
	v_cndmask_b32_e64 v24, v24, v166, s[50:51]
	v_readlane_b32 s50, v245, 40
	v_cndmask_b32_e64 v22, 0, v18, s[34:35]
	v_cmp_lt_f32_e64 s[34:35], s48, v23
	v_readlane_b32 s51, v245, 41
	v_cndmask_b32_e64 v4, v4, v166, s[66:67]
	v_cndmask_b32_e64 v18, 0, v20, s[34:35]
	v_cndmask_b32_e64 v25, v25, v166, s[50:51]
	v_mul_f32_e32 v23, v18, v0
	v_pk_fma_f32 v[224:225], v[24:25], s[32:33], v[126:127] op_sel:[0,1,1] op_sel_hi:[1,1,1] neg_lo:[0,0,1] neg_hi:[0,0,1]
	v_readlane_b32 s50, v245, 42
	v_exp_f32_e32 v18, v224
	v_readlane_b32 s51, v245, 43
	v_exp_f32_e32 v20, v225
	v_cmp_lt_f32_e64 s[34:35], s48, v24
	v_cndmask_b32_e64 v26, v26, v166, s[50:51]
	v_readlane_b32 s50, v245, 44
	v_readlane_b32 s51, v245, 45
	v_cndmask_b32_e64 v24, 0, v18, s[34:35]
	v_cmp_lt_f32_e64 s[34:35], s48, v25
	v_cndmask_b32_e64 v27, v27, v166, s[50:51]
	v_pk_fma_f32 v[224:225], v[26:27], s[32:33], v[126:127] op_sel:[0,1,1] op_sel_hi:[1,1,1] neg_lo:[0,0,1] neg_hi:[0,0,1]
	v_cndmask_b32_e64 v25, 0, v20, s[34:35]
	v_exp_f32_e32 v18, v224
	v_exp_f32_e32 v20, v225
	v_readlane_b32 s50, v245, 46
	v_readlane_b32 s51, v245, 47
	v_cmp_lt_f32_e64 s[34:35], s48, v26
	v_cndmask_b32_e64 v5, v5, v166, s[68:69]
	v_cndmask_b32_e64 v28, v28, v166, s[50:51]
	v_readlane_b32 s50, v245, 48
	v_cndmask_b32_e64 v26, 0, v18, s[34:35]
	v_cmp_lt_f32_e64 s[34:35], s48, v27
	v_readlane_b32 s51, v245, 49
	v_cndmask_b32_e64 v6, v6, v166, s[70:71]
	v_cndmask_b32_e64 v18, 0, v20, s[34:35]
	v_cndmask_b32_e64 v29, v29, v166, s[50:51]
	v_mul_f32_e32 v27, v18, v0
	v_pk_fma_f32 v[224:225], v[28:29], s[32:33], v[126:127] op_sel:[0,1,1] op_sel_hi:[1,1,1] neg_lo:[0,0,1] neg_hi:[0,0,1]
	v_readlane_b32 s50, v245, 50
	v_exp_f32_e32 v18, v224
	v_readlane_b32 s51, v245, 51
	v_exp_f32_e32 v20, v225
	v_cmp_lt_f32_e64 s[34:35], s48, v28
	v_cndmask_b32_e64 v30, v30, v166, s[50:51]
	v_readlane_b32 s50, v245, 52
	v_readlane_b32 s51, v245, 53
	v_cndmask_b32_e64 v28, 0, v18, s[34:35]
	v_cmp_lt_f32_e64 s[34:35], s48, v29
	v_cndmask_b32_e64 v31, v31, v166, s[50:51]
; #define MFMA(a, b, c) __builtin_amdgcn_mfma_f32_32x32x16_bf16((a), (b), (c), 0, 0, 0)
; DI unsigned pack2(float a, float b) { f32x2_t v = {a, b}; bf16x2_t r = __builtin_convertvector(v, bf16x2_t); return __builtin_bit_cast(unsigned, r); }
; DI float fexp2(float x) { return __builtin_amdgcn_exp2f(x); }
; DI float shx(float v, int m) { return __shfl_xor(v, m, 64); }
; template <int DQK, bool MASKED, int MODE, class MF>
; DI void attn_step(const bf16_t* sK, const bf16_t* sVt, const bf16x8 (&qf)[DQK / 16], f32x16& o0, f32x16& o1, float& m, float& l,
;                   float sc, const MF& mf, int lane, f32x16 (&s)[2], float invl, bool lanevalid = true) {
;     ...
; #pragma unroll
;   for (int sub = 0; sub < 2; ++sub)
; #pragma unroll
;     for (int q = 0; q < 16; ++q) {
;       float pv = fexp2(__builtin_fmaf(s[sub][q], sc, -moff));
;       if (MASKED && MODE != 0) pv = (s[sub][q] > -1.0e38f) ? pv : 0.f;
;       if (MODE == 2) pv *= invl;
;       s[sub][q] = pv;
;       ps += pv;
;     }
;   if (MODE != 2) {
;     ps += shx(ps, 32);
;     l = l * alpha + ps;
;   }
;   if (MODE == 1) return;
;   if (MODE == 0) {
; #pragma unroll
;     for (int q = 0; q < 16; ++q) { o0[q] *= alpha; o1[q] *= alpha; }
;   }
; #pragma unroll
;   for (int sub = 0; sub < 2; ++sub)
; #pragma unroll
;     for (int s2 = 0; s2 < 2; ++s2) {
;       union { bf16x8 v; unsigned u[4]; } pb;
; #pragma unroll
;       for (int e = 0; e < 4; ++e) pb.u[e] = pack2(s[sub][8 * s2 + 2 * e], s[sub][8 * s2 + 2 * e + 1]);
;       o0 = MFMA(vf[sub][s2][0], pb.v, o0);
;       o1 = MFMA(vf[sub][s2][1], pb.v, o1);
;     }
; DI void phase_attn_nsa(const Params& P, bf16_t* og, unsigned char* smem, int L, int G) {
;     ...
; #pragma unroll
;         for (int sub = 0; sub < 2; ++sub)
; #pragma unroll
;           for (int s2 = 0; s2 < 2; ++s2) {
;             const int Gi = tile * 4 + sub * 2 + s2;
;             const int q0 = 8 * s2;
;             const float Aj = s[sub][q0] + s[sub][q0 + 1] + s[sub][q0 + 2] + s[sub][q0 + 3];
;             const float Bj = s[sub][q0 + 4] + s[sub][q0 + 5] + s[sub][q0 + 6] + s[sub][q0 + 7] + s[sub][q0 + 3];
;             const float cx = shx(s[sub][q0 + 7], 32);
;             const float add = h ? cx : cprev;
;             cprev = cx;
;             impL[(w * 32 + r) * 33 + 4 * Gi + 2 * h] = Aj + add;
;             impL[(w * 32 + r) * 33 + 4 * Gi + 2 * h + 1] = Bj;
;           }
	v_pk_fma_f32 v[224:225], v[30:31], s[32:33], v[126:127] op_sel:[0,1,1] op_sel_hi:[1,1,1] neg_lo:[0,0,1] neg_hi:[0,0,1]
	v_cndmask_b32_e64 v29, 0, v20, s[34:35]
	v_exp_f32_e32 v18, v224
	v_exp_f32_e32 v20, v225
	v_cmp_lt_f32_e64 s[34:35], s48, v30
	v_cndmask_b32_e64 v7, v7, v166, s[74:75]
	v_cndmask_b32_e64 v8, v8, v166, s[76:77]
	v_cndmask_b32_e64 v30, 0, v18, s[34:35]
	v_cmp_lt_f32_e64 s[34:35], s48, v31
	v_cndmask_b32_e64 v9, v9, v166, s[82:83]
	v_cndmask_b32_e64 v10, v10, v166, s[84:85]
	v_cndmask_b32_e64 v18, 0, v20, s[34:35]
	v_mul_f32_e32 v31, v18, v0
	v_pk_fma_f32 v[224:225], v[32:33], s[32:33], v[126:127] op_sel:[0,1,1] op_sel_hi:[1,1,1] neg_lo:[0,0,1] neg_hi:[0,0,1]
	v_exp_f32_e32 v18, v224
	v_exp_f32_e32 v20, v225
	v_cmp_lt_f32_e64 s[34:35], s48, v32
	v_cndmask_b32_e64 v11, v11, v166, s[86:87]
	v_cndmask_b32_e64 v12, v12, v166, s[90:91]
	v_cndmask_b32_e64 v32, 0, v18, s[34:35]
	v_cmp_lt_f32_e64 s[34:35], s48, v33
	v_pk_fma_f32 v[222:223], v[2:3], s[32:33], v[126:127] op_sel:[0,1,1] op_sel_hi:[1,1,1] neg_lo:[0,0,1] neg_hi:[0,0,1]
	v_exp_f32_e32 v18, v222
	v_cndmask_b32_e64 v33, 0, v20, s[34:35]
	v_exp_f32_e32 v20, v223
	v_cmp_lt_f32_e64 s[34:35], s48, v2
	v_cndmask_b32_e64 v13, v13, v166, s[94:95]
	v_cndmask_b32_e64 v14, v14, v166, s[96:97]
	v_cndmask_b32_e64 v130, 0, v18, s[34:35]
	v_cmp_lt_f32_e64 s[34:35], s48, v3
	v_pk_fma_f32 v[222:223], v[4:5], s[32:33], v[126:127] op_sel:[0,1,1] op_sel_hi:[1,1,1] neg_lo:[0,0,1] neg_hi:[0,0,1]
	v_exp_f32_e32 v3, v223
	v_cndmask_b32_e64 v2, 0, v20, s[34:35]
	v_mul_f32_e32 v132, v2, v0
	v_exp_f32_e32 v2, v222
	v_cmp_lt_f32_e64 s[34:35], s48, v4
	v_cndmask_b32_e64 v15, v15, v166, s[40:41]
	v_mul_f32_e32 v16, v102, v0
	v_cndmask_b32_e64 v133, 0, v2, s[34:35]
	v_cmp_lt_f32_e64 s[34:35], s48, v5
	v_pk_fma_f32 v[222:223], v[6:7], s[32:33], v[126:127] op_sel:[0,1,1] op_sel_hi:[1,1,1] neg_lo:[0,0,1] neg_hi:[0,0,1]
	v_exp_f32_e32 v2, v222
	v_cndmask_b32_e64 v142, 0, v3, s[34:35]
	v_exp_f32_e32 v3, v223
	v_cmp_lt_f32_e64 s[34:35], s48, v6
	v_mul_f32_e32 v17, v104, v0
	v_mul_f32_e32 v19, v105, v0
	v_cndmask_b32_e64 v144, 0, v2, s[34:35]
	v_cmp_lt_f32_e64 s[34:35], s48, v7
	v_mul_f32_e32 v21, v22, v0
	v_mul_f32_e32 v106, v24, v0
	v_cndmask_b32_e64 v2, 0, v3, s[34:35]
	v_mul_f32_e32 v146, v2, v0
	v_pk_fma_f32 v[222:223], v[8:9], s[32:33], v[126:127] op_sel:[0,1,1] op_sel_hi:[1,1,1] neg_lo:[0,0,1] neg_hi:[0,0,1]
	v_exp_f32_e32 v2, v222
	v_exp_f32_e32 v3, v223
	v_cmp_lt_f32_e64 s[34:35], s48, v8
	v_mul_f32_e32 v107, v25, v0
	v_cvt_pk_bf16_f32 v18, v16, v103
	v_cndmask_b32_e64 v147, 0, v2, s[34:35]
	v_cmp_lt_f32_e64 s[34:35], s48, v9
	v_pk_fma_f32 v[222:223], v[10:11], s[32:33], v[126:127] op_sel:[0,1,1] op_sel_hi:[1,1,1] neg_lo:[0,0,1] neg_hi:[0,0,1]
	v_exp_f32_e32 v2, v222
	v_cndmask_b32_e64 v149, 0, v3, s[34:35]
	v_exp_f32_e32 v3, v223
	v_cmp_lt_f32_e64 s[34:35], s48, v10
	v_cvt_pk_bf16_f32 v19, v17, v19
	v_cvt_pk_bf16_f32 v20, v21, v23
	v_cndmask_b32_e64 v151, 0, v2, s[34:35]
	v_cmp_lt_f32_e64 s[34:35], s48, v11
	v_cvt_pk_bf16_f32 v21, v106, v107
	v_mul_f32_e32 v108, v26, v0
	v_cndmask_b32_e64 v2, 0, v3, s[34:35]
	v_mul_f32_e32 v176, v2, v0
	v_pk_fma_f32 v[222:223], v[12:13], s[32:33], v[126:127] op_sel:[0,1,1] op_sel_hi:[1,1,1] neg_lo:[0,0,1] neg_hi:[0,0,1]
	v_exp_f32_e32 v2, v222
	v_exp_f32_e32 v3, v223
	v_cmp_lt_f32_e64 s[34:35], s48, v12
	v_mul_f32_e32 v109, v28, v0
	v_mul_f32_e32 v110, v29, v0
	v_cndmask_b32_e64 v177, 0, v2, s[34:35]
	v_cmp_lt_f32_e64 s[34:35], s48, v13
	v_pk_fma_f32 v[222:223], v[14:15], s[32:33], v[126:127] op_sel:[0,1,1] op_sel_hi:[1,1,1] neg_lo:[0,0,1] neg_hi:[0,0,1]
	v_exp_f32_e32 v2, v222
	v_cndmask_b32_e64 v179, 0, v3, s[34:35]
	v_exp_f32_e32 v3, v223
	v_cmp_lt_f32_e64 s[34:35], s48, v14
	v_mul_f32_e32 v111, v30, v0
	v_mul_f32_e32 v112, v32, v0
	v_cndmask_b32_e64 v181, 0, v2, s[34:35]
	v_cmp_lt_f32_e64 s[34:35], s48, v15
	v_pk_fma_f32 v[222:223], v[100:101], s[32:33], v[126:127] op_sel:[0,1,1] op_sel_hi:[1,1,1] neg_lo:[0,0,1] neg_hi:[0,0,1]
	v_exp_f32_e32 v184, v222
	v_cndmask_b32_e64 v183, 0, v3, s[34:35]
	s_waitcnt lgkmcnt(7)
	v_mfma_f32_32x32x16_bf16 v[2:17], v[94:97], v[18:21], 0
	v_mul_f32_e32 v113, v33, v0
	v_cvt_pk_bf16_f32 v94, v108, v27
	v_cvt_pk_bf16_f32 v95, v109, v110
	v_cvt_pk_bf16_f32 v96, v111, v31
	v_cvt_pk_bf16_f32 v97, v112, v113
	v_mul_f32_e32 v131, v130, v0
	v_mul_f32_e32 v141, v133, v0
	s_waitcnt lgkmcnt(6)
	v_mfma_f32_32x32x16_bf16 v[2:17], v[90:93], v[94:97], v[2:17]
	v_mul_f32_e32 v143, v142, v0
	v_mul_f32_e32 v145, v144, v0
	v_mul_f32_e32 v148, v147, v0
	v_mul_f32_e32 v150, v149, v0
	v_exp_f32_e32 v109, v223
	v_cvt_pk_bf16_f32 v90, v131, v132
	v_cvt_pk_bf16_f32 v91, v141, v143
	v_cvt_pk_bf16_f32 v92, v145, v146
	v_cvt_pk_bf16_f32 v93, v148, v150
	v_cmp_lt_f32_e64 s[34:35], s48, v100
	v_mul_f32_e32 v175, v151, v0
	s_waitcnt lgkmcnt(3)
	v_mfma_f32_32x32x16_bf16 v[2:17], v[70:73], v[90:93], v[2:17]
	v_cndmask_b32_e64 v100, 0, v184, s[34:35]
	v_cmp_lt_f32_e64 s[34:35], s48, v101
	v_mul_f32_e32 v178, v177, v0
	v_mul_f32_e32 v180, v179, v0
	v_cndmask_b32_e64 v101, 0, v109, s[34:35]
	v_mul_f32_e32 v182, v181, v0
	v_mul_f32_e32 v106, v183, v0
	v_mul_f32_e32 v108, v100, v0
	v_mul_f32_e32 v109, v101, v0
	v_cvt_pk_bf16_f32 v70, v175, v176
	v_cvt_pk_bf16_f32 v71, v178, v180
	v_cvt_pk_bf16_f32 v72, v182, v106
	v_cvt_pk_bf16_f32 v73, v108, v109
	v_fmac_f32_e32 v103, v102, v0
	v_fmac_f32_e32 v23, v22, v0
	s_waitcnt lgkmcnt(1)
	v_mfma_f32_32x32x16_bf16 v[2:17], v[66:69], v[70:73], v[2:17]
	ds_bpermute_b32 v66, v173, v107
	ds_bpermute_b32 v67, v173, v113
	v_fmac_f32_e32 v103, v104, v0
	v_fmac_f32_e32 v23, v24, v0
	v_fmac_f32_e32 v103, v105, v0
	v_fmac_f32_e32 v23, v25, v0
	s_waitcnt lgkmcnt(1)
; template <int DQK, bool MASKED, int MODE, class MF>
; DI void attn_step(const bf16_t* sK, const bf16_t* sVt, const bf16x8 (&qf)[DQK / 16], f32x16& o0, f32x16& o1, float& m, float& l,
;                   float sc, const MF& mf, int lane, f32x16 (&s)[2], float invl, bool lanevalid = true) {
;     ...
;   bf16x8 kf[2][DQK / 16];
; #pragma unroll
;   for (int sub = 0; sub < 2; ++sub)
; #pragma unroll
;     for (int ks = 0; ks < DQK / 16; ++ks) kf[sub][ks] = *(const bf16x8*)(sK + (sub * 32 + pr) * KST + ks * 16 + 8 * h);
;   __builtin_amdgcn_sched_barrier(0);
; #pragma unroll
;   for (int q = 0; q < 16; ++q) { s[0][q] = 0.f; s[1][q] = 0.f; }
; #pragma unroll
;   for (int ks = 0; ks < DQK / 16; ++ks) {
;     s[0] = MFMA(kf[0][ks], qf[ks], s[0]);
;     s[1] = MFMA(kf[1][ks], qf[ks], s[1]);
;   }
;   bf16x8 vf[2][2][2];
;   if (MODE != 1) {
; #pragma unroll
;     for (int sub = 0; sub < 2; ++sub)
; #pragma unroll
;       for (int s2 = 0; s2 < 2; ++s2) {
;         vf[sub][s2][0] = *(const bf16x8*)(sVt + r * 72 + sub * 32 + s2 * 16 + 8 * h);
;         vf[sub][s2][1] = *(const bf16x8*)(sVt + (32 + r) * 72 + sub * 32 + s2 * 16 + 8 * h);
;       }
;     __builtin_amdgcn_sched_barrier(0);
;   }
;   float mxr = -3.0e38f;
; #pragma unroll
;   for (int sub = 0; sub < 2; ++sub)
; #pragma unroll
;     for (int q = 0; q < 16; ++q) {
;       if (MASKED) { const int kk = sub * 32 + 16 * (q >> 3) + 8 * h + (q & 7); s[sub][q] = mf(kk) ? s[sub][q] : -3.0e38f; }
;       if (MODE != 2) mxr = fmaxf(mxr, s[sub][q]);
;     }
;   float alpha = 1.f;
;   if (MODE != 2) {
;     float mx = fmaxf(m, mxr * sc);
;     mx = fmaxf(mx, shx(mx, 32));
;     if (!MASKED) mx = lanevalid ? mx : m;
;     alpha = fexp2(m - mx);
;     m = mx;
;   }
;   const float moff = (!MASKED && !lanevalid) ? 1.0e30f : m;
;   float ps = 0.f;
; #pragma unroll
;   for (int sub = 0; sub < 2; ++sub)
; #pragma unroll
;     for (int q = 0; q < 16; ++q) {
;       float pv = fexp2(__builtin_fmaf(s[sub][q], sc, -moff));
;       if (MASKED && MODE != 0) pv = (s[sub][q] > -1.0e38f) ? pv : 0.f;
;       if (MODE == 2) pv *= invl;
;       s[sub][q] = pv;
;       ps += pv;
;     }
; DI void phase_attn_nsa(const Params& P, bf16_t* og, unsigned char* smem, int L, int G) {
;     ...
;       for (int tile = 0; tile < 2; ++tile) {
;         const int key0 = tile * 64;
;         kv64_commit(R, sK, sVt, true, tid);
	v_cndmask_b32_e64 v22, v66, 0, vcc
	v_fmac_f32_e32 v27, v26, v0
	v_fmac_f32_e32 v31, v30, v0
	v_fmac_f32_e32 v23, v105, v0
	v_add_f32_e32 v22, v22, v103
	v_fmac_f32_e32 v27, v28, v0
	v_fmac_f32_e32 v31, v32, v0
	ds_write2_b32 v99, v22, v23 offset1:1
	v_fmac_f32_e32 v27, v29, v0
	v_fmac_f32_e32 v31, v33, v0
	s_waitcnt lgkmcnt(1)
	v_cndmask_b32_e32 v22, v67, v66, vcc
	v_fmac_f32_e32 v31, v29, v0
	v_add_f32_e32 v22, v22, v27
	v_add_u32_e32 v23, 0x9210, v128
	ds_write2_b32 v23, v22, v31 offset1:1
	s_nop 0
	v_mfma_f32_32x32x16_bf16 v[18:33], v[62:65], v[18:21], 0
	v_fmac_f32_e32 v132, v130, v0
	ds_bpermute_b32 v62, v173, v150
	ds_bpermute_b32 v130, v173, v109
	v_fmac_f32_e32 v146, v144, v0
	v_fmac_f32_e32 v176, v151, v0
	v_fmac_f32_e32 v106, v181, v0
	v_fmac_f32_e32 v132, v133, v0
	v_mfma_f32_32x32x16_bf16 v[18:33], v[58:61], v[94:97], v[18:33]
	v_fmac_f32_e32 v146, v147, v0
	v_fmac_f32_e32 v176, v177, v0
	v_fmac_f32_e32 v106, v100, v0
	v_fmac_f32_e32 v132, v142, v0
	v_fmac_f32_e32 v146, v149, v0
	s_waitcnt lgkmcnt(1)
	v_cndmask_b32_e32 v63, v62, v67, vcc
	v_fmac_f32_e32 v176, v179, v0
	v_mfma_f32_32x32x16_bf16 v[18:33], v[54:57], v[90:93], v[18:33]
	v_fmac_f32_e32 v106, v101, v0
	s_waitcnt lgkmcnt(0)
	v_cndmask_b32_e32 v54, v130, v62, vcc
	v_fmac_f32_e32 v146, v142, v0
	v_add_f32_e32 v63, v63, v132
	v_add_u32_e32 v58, 0x9220, v128
	v_fmac_f32_e32 v106, v179, v0
	v_add_f32_e32 v54, v54, v176
	v_mfma_f32_32x32x16_bf16 v[18:33], v[50:53], v[70:73], v[18:33]
	v_add_u32_e32 v55, 0x9230, v128
	ds_write2_b32 v58, v63, v146 offset1:1
	ds_write2_b32 v55, v54, v106 offset1:1
	s_waitcnt lgkmcnt(0)
	s_barrier
	s_waitcnt vmcnt(0)
	ds_write_b128 v170, v[46:49]
	ds_write_b128 v170, v[42:45] offset:4608
	ds_write_b128 v170, v[38:41] offset:9216
	ds_write_b128 v170, v[34:37] offset:13824
	s_waitcnt lgkmcnt(0)
	s_barrier
	ds_read_b128 v[34:37], v172
	ds_read_b128 v[66:69], v172 offset:32
	ds_read_b128 v[70:73], v172 offset:64
	ds_read_b128 v[90:93], v172 offset:96
	ds_read_b128 v[38:41], v172 offset:4608
	ds_read_b128 v[94:97], v172 offset:4640
	ds_read_b128 v[100:103], v172 offset:4672
	ds_read_b128 v[104:107], v172 offset:4704
	s_waitcnt lgkmcnt(7)
	v_mfma_f32_32x32x16_bf16 v[50:65], v[34:37], v[74:77], 0
	s_waitcnt lgkmcnt(3)
	v_mfma_f32_32x32x16_bf16 v[34:49], v[38:41], v[74:77], 0
	v_mfma_f32_32x32x16_bf16 v[50:65], v[66:69], v[78:81], v[50:65]
	s_waitcnt lgkmcnt(2)
	v_mfma_f32_32x32x16_bf16 v[34:49], v[94:97], v[78:81], v[34:49]
	v_mfma_f32_32x32x16_bf16 v[50:65], v[70:73], v[82:85], v[50:65]
	s_waitcnt lgkmcnt(1)
	v_mfma_f32_32x32x16_bf16 v[34:49], v[100:103], v[82:85], v[34:49]
	v_mfma_f32_32x32x16_bf16 v[50:65], v[90:93], v[86:89], v[50:65]
	s_waitcnt lgkmcnt(0)
	v_mfma_f32_32x32x16_bf16 v[34:49], v[104:107], v[86:89], v[34:49]
	ds_read_b128 v[110:113], v98 offset:9216
	ds_read_b128 v[106:109], v98 offset:9248
	ds_read_b128 v[94:97], v129 offset:9216
	ds_read_b128 v[90:93], v129 offset:9248
	ds_read_b128 v[102:105], v98 offset:9280
	ds_read_b128 v[70:73], v129 offset:9280
	ds_read_b128 v[98:101], v98 offset:9312
	ds_read_b128 v[66:69], v129 offset:9312
	v_readlane_b32 s34, v245, 54
	v_readlane_b32 s35, v245, 55
	s_nop 1
	v_cndmask_b32_e64 v129, v49, v166, s[0:1]
	v_cndmask_b32_e64 v56, v56, v166, s[54:55]
	v_cndmask_b32_e64 v50, v50, v166, s[34:35]
	v_readlane_b32 s34, v245, 56
	v_readlane_b32 s35, v245, 57
	v_fma_f32 v49, v50, s33, -v127
	v_exp_f32_e32 v49, v49
	v_cndmask_b32_e64 v51, v51, v166, s[34:35]
	v_fma_f32 v131, v51, s33, -v127
	v_exp_f32_e32 v131, v131
	v_readlane_b32 s34, v245, 58
	v_readlane_b32 s35, v245, 59
	v_cmp_lt_f32_e64 s[0:1], s48, v50
	v_cndmask_b32_e64 v57, v57, v166, s[56:57]
	v_cndmask_b32_e64 v52, v52, v166, s[34:35]
	v_readlane_b32 s34, v245, 60
	v_cndmask_b32_e64 v132, 0, v49, s[0:1]
	v_cmp_lt_f32_e64 s[0:1], s48, v51
	v_readlane_b32 s35, v245, 61
	v_cndmask_b32_e64 v58, v58, v166, s[60:61]
	v_cndmask_b32_e64 v50, 0, v131, s[0:1]
	v_cndmask_b32_e64 v53, v53, v166, s[34:35]
	v_readlane_b32 s34, v245, 62
	v_mul_f32_e32 v131, v0, v50
	v_pk_fma_f32 v[224:225], v[52:53], s[32:33], v[126:127] op_sel:[0,1,1] op_sel_hi:[1,1,1] neg_lo:[0,0,1] neg_hi:[0,0,1]
	v_readlane_b32 s35, v245, 63
	v_exp_f32_e32 v50, v224
	v_cndmask_b32_e64 v54, v54, v166, s[34:35]
	v_readlane_b32 s34, v244, 0
	v_readlane_b32 s35, v244, 1
	v_exp_f32_e32 v51, v225
	v_cmp_lt_f32_e64 s[0:1], s48, v52
	v_cndmask_b32_e64 v55, v55, v166, s[34:35]
	v_pk_fma_f32 v[224:225], v[54:55], s[32:33], v[126:127] op_sel:[0,1,1] op_sel_hi:[1,1,1] neg_lo:[0,0,1] neg_hi:[0,0,1]
	v_cndmask_b32_e64 v133, 0, v50, s[0:1]
	v_cmp_lt_f32_e64 s[0:1], s48, v53
	v_exp_f32_e32 v52, v224
	v_exp_f32_e32 v53, v225
	v_cndmask_b32_e64 v141, 0, v51, s[0:1]
	v_cmp_lt_f32_e64 s[0:1], s48, v54
	v_pk_fma_f32 v[224:225], v[56:57], s[32:33], v[126:127] op_sel:[0,1,1] op_sel_hi:[1,1,1] neg_lo:[0,0,1] neg_hi:[0,0,1]
	v_exp_f32_e32 v54, v225
	v_cndmask_b32_e64 v142, 0, v52, s[0:1]
	v_cmp_lt_f32_e64 s[0:1], s48, v55
	v_cndmask_b32_e64 v59, v59, v166, s[72:73]
	v_pk_fma_f32 v[226:227], v[58:59], s[32:33], v[126:127] op_sel:[0,1,1] op_sel_hi:[1,1,1] neg_lo:[0,0,1] neg_hi:[0,0,1]
	v_cndmask_b32_e64 v53, 0, v53, s[0:1]
	v_mul_f32_e32 v143, v0, v53
	v_exp_f32_e32 v53, v224
	v_cmp_lt_f32_e64 s[0:1], s48, v56
	v_exp_f32_e32 v55, v227
	v_cndmask_b32_e64 v60, v60, v166, s[78:79]
	v_cndmask_b32_e64 v56, 0, v53, s[0:1]
	v_cmp_lt_f32_e64 s[0:1], s48, v57
	v_cndmask_b32_e64 v61, v61, v166, s[80:81]
	v_cndmask_b32_e64 v62, v62, v166, s[88:89]
	v_cndmask_b32_e64 v57, 0, v54, s[0:1]
	v_exp_f32_e32 v54, v226
	v_cmp_lt_f32_e64 s[0:1], s48, v58
	v_pk_fma_f32 v[224:225], v[60:61], s[32:33], v[126:127] op_sel:[0,1,1] op_sel_hi:[1,1,1] neg_lo:[0,0,1] neg_hi:[0,0,1]
; #define MFMA(a, b, c) __builtin_amdgcn_mfma_f32_32x32x16_bf16((a), (b), (c), 0, 0, 0)
; DI unsigned pack2(float a, float b) { f32x2_t v = {a, b}; bf16x2_t r = __builtin_convertvector(v, bf16x2_t); return __builtin_bit_cast(unsigned, r); }
; DI float fexp2(float x) { return __builtin_amdgcn_exp2f(x); }
; DI float shx(float v, int m) { return __shfl_xor(v, m, 64); }
; template <int DQK, bool MASKED, int MODE, class MF>
; DI void attn_step(const bf16_t* sK, const bf16_t* sVt, const bf16x8 (&qf)[DQK / 16], f32x16& o0, f32x16& o1, float& m, float& l,
;                   float sc, const MF& mf, int lane, f32x16 (&s)[2], float invl, bool lanevalid = true) {
;     ...
; #pragma unroll
;   for (int sub = 0; sub < 2; ++sub)
; #pragma unroll
;     for (int q = 0; q < 16; ++q) {
;       float pv = fexp2(__builtin_fmaf(s[sub][q], sc, -moff));
;       if (MASKED && MODE != 0) pv = (s[sub][q] > -1.0e38f) ? pv : 0.f;
;       if (MODE == 2) pv *= invl;
;       s[sub][q] = pv;
;       ps += pv;
;     }
;   if (MODE != 2) {
;     ps += shx(ps, 32);
;     l = l * alpha + ps;
;   }
;   if (MODE == 1) return;
;   if (MODE == 0) {
; #pragma unroll
;     for (int q = 0; q < 16; ++q) { o0[q] *= alpha; o1[q] *= alpha; }
;   }
; #pragma unroll
;   for (int sub = 0; sub < 2; ++sub)
; #pragma unroll
;     for (int s2 = 0; s2 < 2; ++s2) {
;       union { bf16x8 v; unsigned u[4]; } pb;
; #pragma unroll
;       for (int e = 0; e < 4; ++e) pb.u[e] = pack2(s[sub][8 * s2 + 2 * e], s[sub][8 * s2 + 2 * e + 1]);
;       o0 = MFMA(vf[sub][s2][0], pb.v, o0);
;       o1 = MFMA(vf[sub][s2][1], pb.v, o1);
;     }
	v_cndmask_b32_e64 v63, v63, v166, s[92:93]
	v_cndmask_b32_e64 v58, 0, v54, s[0:1]
	v_cmp_lt_f32_e64 s[0:1], s48, v59
	v_exp_f32_e32 v145, v225
	v_pk_fma_f32 v[226:227], v[62:63], s[32:33], v[126:127] op_sel:[0,1,1] op_sel_hi:[1,1,1] neg_lo:[0,0,1] neg_hi:[0,0,1]
	v_cndmask_b32_e64 v55, 0, v55, s[0:1]
	v_mul_f32_e32 v59, v0, v55
	v_exp_f32_e32 v55, v224
	v_exp_f32_e32 v146, v226
	v_cmp_lt_f32_e64 s[0:1], s48, v60
	v_exp_f32_e32 v147, v227
	v_cndmask_b32_e64 v64, v64, v166, s[42:43]
	v_cndmask_b32_e64 v60, 0, v55, s[0:1]
	v_cmp_lt_f32_e64 s[0:1], s48, v61
	v_cndmask_b32_e64 v65, v65, v166, s[38:39]
	v_cndmask_b32_e64 v34, v34, v166, s[30:31]
	v_cndmask_b32_e64 v61, 0, v145, s[0:1]
	v_cmp_lt_f32_e64 s[0:1], s48, v62
	v_pk_fma_f32 v[224:225], v[64:65], s[32:33], v[126:127] op_sel:[0,1,1] op_sel_hi:[1,1,1] neg_lo:[0,0,1] neg_hi:[0,0,1]
	v_cndmask_b32_e64 v35, v35, v166, s[28:29]
	v_cndmask_b32_e64 v62, 0, v146, s[0:1]
	v_cmp_lt_f32_e64 s[0:1], s48, v63
	v_exp_f32_e32 v148, v225
	v_pk_fma_f32 v[222:223], v[34:35], s[32:33], v[126:127] op_sel:[0,1,1] op_sel_hi:[1,1,1] neg_lo:[0,0,1] neg_hi:[0,0,1]
	v_cndmask_b32_e64 v63, 0, v147, s[0:1]
	v_exp_f32_e32 v147, v224
	v_exp_f32_e32 v149, v222
	v_cmp_lt_f32_e64 s[0:1], s48, v64
	v_exp_f32_e32 v150, v223
	v_cndmask_b32_e64 v36, v36, v166, s[26:27]
	v_cndmask_b32_e64 v64, 0, v147, s[0:1]
	v_cmp_lt_f32_e64 s[0:1], s48, v65
	v_cndmask_b32_e64 v37, v37, v166, s[16:17]
	v_cndmask_b32_e64 v38, v38, v166, s[18:19]
	v_cndmask_b32_e64 v65, 0, v148, s[0:1]
	v_cmp_lt_f32_e64 s[0:1], s48, v34
	v_cndmask_b32_e64 v39, v39, v166, s[20:21]
	v_cndmask_b32_e64 v40, v40, v166, s[22:23]
	v_cndmask_b32_e64 v149, 0, v149, s[0:1]
	v_cmp_lt_f32_e64 s[0:1], s48, v35
	v_pk_fma_f32 v[222:223], v[36:37], s[32:33], v[126:127] op_sel:[0,1,1] op_sel_hi:[1,1,1] neg_lo:[0,0,1] neg_hi:[0,0,1]
	v_exp_f32_e32 v35, v223
	v_cndmask_b32_e64 v34, 0, v150, s[0:1]
	v_mul_f32_e32 v150, v0, v34
	v_exp_f32_e32 v34, v222
	v_cmp_lt_f32_e64 s[0:1], s48, v36
	v_cndmask_b32_e64 v41, v41, v166, s[24:25]
	v_cndmask_b32_e64 v42, v42, v166, s[14:15]
	v_cndmask_b32_e64 v175, 0, v34, s[0:1]
	v_cmp_lt_f32_e64 s[0:1], s48, v37
	v_pk_fma_f32 v[222:223], v[38:39], s[32:33], v[126:127] op_sel:[0,1,1] op_sel_hi:[1,1,1] neg_lo:[0,0,1] neg_hi:[0,0,1]
	v_exp_f32_e32 v34, v222
	v_cndmask_b32_e64 v177, 0, v35, s[0:1]
	v_exp_f32_e32 v35, v223
	v_cmp_lt_f32_e64 s[0:1], s48, v38
	v_cndmask_b32_e64 v43, v43, v166, s[12:13]
	v_cndmask_b32_e64 v44, v44, v166, s[10:11]
	v_cndmask_b32_e64 v179, 0, v34, s[0:1]
	v_cmp_lt_f32_e64 s[0:1], s48, v39
	v_cndmask_b32_e64 v45, v45, v166, s[8:9]
	v_cndmask_b32_e64 v46, v46, v166, s[6:7]
	v_cndmask_b32_e64 v34, 0, v35, s[0:1]
	v_mul_f32_e32 v181, v0, v34
	v_pk_fma_f32 v[222:223], v[40:41], s[32:33], v[126:127] op_sel:[0,1,1] op_sel_hi:[1,1,1] neg_lo:[0,0,1] neg_hi:[0,0,1]
	v_exp_f32_e32 v34, v222
	v_exp_f32_e32 v35, v223
	v_cmp_lt_f32_e64 s[0:1], s48, v40
	v_cndmask_b32_e64 v47, v47, v166, s[4:5]
	v_cndmask_b32_e64 v48, v48, v166, s[2:3]
	v_cndmask_b32_e64 v182, 0, v34, s[0:1]
	v_cmp_lt_f32_e64 s[0:1], s48, v41
	v_pk_fma_f32 v[222:223], v[42:43], s[32:33], v[126:127] op_sel:[0,1,1] op_sel_hi:[1,1,1] neg_lo:[0,0,1] neg_hi:[0,0,1]
	v_exp_f32_e32 v34, v222
	v_cndmask_b32_e64 v184, 0, v35, s[0:1]
	v_exp_f32_e32 v35, v223
	v_cmp_lt_f32_e64 s[0:1], s48, v42
	v_mul_f32_e32 v49, v0, v132
	v_mul_f32_e32 v50, v0, v133
	v_cndmask_b32_e64 v42, 0, v34, s[0:1]
	v_cmp_lt_f32_e64 s[0:1], s48, v43
	v_mul_f32_e32 v51, v0, v141
	v_mul_f32_e32 v52, v0, v142
	v_cndmask_b32_e64 v34, 0, v35, s[0:1]
	v_mul_f32_e32 v43, v0, v34
	v_pk_fma_f32 v[222:223], v[44:45], s[32:33], v[126:127] op_sel:[0,1,1] op_sel_hi:[1,1,1] neg_lo:[0,0,1] neg_hi:[0,0,1]
	v_exp_f32_e32 v34, v222
	v_exp_f32_e32 v35, v223
	v_cmp_lt_f32_e64 s[0:1], s48, v44
	v_mul_f32_e32 v53, v0, v56
	v_mul_f32_e32 v144, v0, v57
	v_cndmask_b32_e64 v44, 0, v34, s[0:1]
	v_cmp_lt_f32_e64 s[0:1], s48, v45
	v_pk_fma_f32 v[222:223], v[46:47], s[32:33], v[126:127] op_sel:[0,1,1] op_sel_hi:[1,1,1] neg_lo:[0,0,1] neg_hi:[0,0,1]
	v_exp_f32_e32 v34, v222
	v_cndmask_b32_e64 v45, 0, v35, s[0:1]
	v_exp_f32_e32 v35, v223
	v_cmp_lt_f32_e64 s[0:1], s48, v46
	v_cvt_pk_bf16_f32 v36, v52, v143
	v_cvt_pk_bf16_f32 v37, v53, v144
	v_cndmask_b32_e64 v46, 0, v34, s[0:1]
	v_cmp_lt_f32_e64 s[0:1], s48, v47
	v_fma_f32 v34, v48, s33, -v127
	v_exp_f32_e32 v39, v34
	v_cndmask_b32_e64 v38, 0, v35, s[0:1]
	v_cvt_pk_bf16_f32 v34, v49, v131
	v_cvt_pk_bf16_f32 v35, v50, v51
	v_mul_f32_e32 v54, v0, v58
	v_mul_f32_e32 v55, v0, v60
	s_waitcnt lgkmcnt(7)
	v_mfma_f32_32x32x16_bf16 v[2:17], v[110:113], v[34:37], v[2:17]
	v_mul_f32_e32 v145, v0, v61
	v_mul_f32_e32 v146, v0, v62
	v_mul_f32_e32 v63, v0, v63
	v_mul_f32_e32 v147, v0, v64
	v_mul_f32_e32 v148, v0, v65
	v_cmp_lt_f32_e64 s[0:1], s48, v48
	v_mul_f32_e32 v47, v0, v38
	v_cvt_pk_bf16_f32 v38, v54, v59
	v_cndmask_b32_e64 v110, 0, v39, s[0:1]
	v_cvt_pk_bf16_f32 v39, v55, v145
	v_cvt_pk_bf16_f32 v40, v146, v63
	v_cvt_pk_bf16_f32 v41, v147, v148
	v_mul_f32_e32 v151, v0, v149
	v_mul_f32_e32 v176, v0, v175
	s_waitcnt lgkmcnt(6)
; DI float shx(float v, int m) { return __shfl_xor(v, m, 64); }
; DI void phase_attn_nsa(const Params& P, bf16_t* og, unsigned char* smem, int L, int G) {
;     ...
; #pragma unroll
;         for (int sub = 0; sub < 2; ++sub)
; #pragma unroll
;           for (int s2 = 0; s2 < 2; ++s2) {
;             const int Gi = tile * 4 + sub * 2 + s2;
;             const int q0 = 8 * s2;
;             const float Aj = s[sub][q0] + s[sub][q0 + 1] + s[sub][q0 + 2] + s[sub][q0 + 3];
;             const float Bj = s[sub][q0 + 4] + s[sub][q0 + 5] + s[sub][q0 + 6] + s[sub][q0 + 7] + s[sub][q0 + 3];
;             const float cx = shx(s[sub][q0 + 7], 32);
;             const float add = h ? cx : cprev;
;             cprev = cx;
;             impL[(w * 32 + r) * 33 + 4 * Gi + 2 * h] = Aj + add;
;             impL[(w * 32 + r) * 33 + 4 * Gi + 2 * h + 1] = Bj;
;           }
;       }
;     }
;     __syncthreads();
; #pragma unroll
;     for (int pss = 0; pss < 4; ++pss) {
;       const int pair = pss * 256 + tid, q = pair >> 5, j = pair & 31;
;       scoreL[q * 33 + j] = impL[(0 * 32 + q) * 33 + j] + impL[(1 * 32 + q) * 33 + j] + impL[(2 * 32 + q) * 33 + j] + impL[(3 * 32 + q) * 33 + j];
;     }
;     __syncthreads();
; #pragma unroll
;     for (int pss = 0; pss < 4; ++pss) {
;       const int pair = pss * 256 + tid, q = pair >> 5, j = pair & 31;
;       const int tq = t0 + q, cur = tq >> 6;
;       const bool forced = (j == 0) || (j == cur) || (j == cur - 1);
;       const int nf = cur >= 2 ? 3 : cur + 1;
;       const int need = 8 - nf;
;       const bool cand = (j >= 1) && (j <= cur - 2);
;       const float sj = scoreL[q * 33 + j];
;       int rank = 0;
;       for (int j2 = 1; j2 <= cur - 2; ++j2) {
	v_mfma_f32_32x32x16_bf16 v[2:17], v[106:109], v[38:41], v[2:17]
	v_mul_f32_e32 v178, v0, v177
	v_mul_f32_e32 v180, v0, v179
	v_mul_f32_e32 v183, v0, v182
	v_mul_f32_e32 v185, v0, v184
	v_fma_f32 v48, v129, s33, -v127
	v_exp_f32_e32 v52, v48
	v_cvt_pk_bf16_f32 v48, v151, v150
	v_cvt_pk_bf16_f32 v49, v176, v178
	v_cvt_pk_bf16_f32 v50, v180, v181
	v_cvt_pk_bf16_f32 v51, v183, v185
	v_cmp_lt_f32_e64 s[0:1], s48, v129
	v_mul_f32_e32 v186, v0, v42
	s_waitcnt lgkmcnt(3)
	v_mfma_f32_32x32x16_bf16 v[2:17], v[102:105], v[48:51], v[2:17]
	v_cndmask_b32_e64 v102, 0, v52, s[0:1]
	v_mul_f32_e32 v187, v0, v44
	v_mul_f32_e32 v188, v0, v45
	v_mul_f32_e32 v189, v0, v46
	v_mul_f32_e32 v55, v0, v110
	v_mul_f32_e32 v103, v0, v102
	v_cvt_pk_bf16_f32 v52, v186, v43
	v_cvt_pk_bf16_f32 v53, v187, v188
	v_cvt_pk_bf16_f32 v54, v189, v47
	v_cvt_pk_bf16_f32 v55, v55, v103
	v_fmac_f32_e32 v131, v0, v132
	v_fmac_f32_e32 v143, v0, v142
	s_waitcnt lgkmcnt(1)
	v_mfma_f32_32x32x16_bf16 v[2:17], v[98:101], v[52:55], v[2:17]
	ds_bpermute_b32 v98, v173, v144
	v_fmac_f32_e32 v131, v0, v133
	v_fmac_f32_e32 v143, v0, v56
	v_fmac_f32_e32 v131, v0, v141
	v_fmac_f32_e32 v143, v0, v57
	s_waitcnt lgkmcnt(0)
	v_cndmask_b32_e32 v56, v98, v130, vcc
	v_fmac_f32_e32 v143, v0, v141
	v_add_f32_e32 v56, v131, v56
	v_add_u32_e32 v57, 0x9240, v128
	ds_write2_b32 v57, v56, v143 offset1:1
	ds_bpermute_b32 v56, v173, v148
	v_fmac_f32_e32 v59, v0, v58
	v_fmac_f32_e32 v63, v0, v62
	v_fmac_f32_e32 v59, v0, v60
	v_fmac_f32_e32 v63, v0, v64
	v_mfma_f32_32x32x16_bf16 v[18:33], v[94:97], v[34:37], v[18:33]
	v_fmac_f32_e32 v59, v0, v61
	v_fmac_f32_e32 v63, v0, v65
	s_waitcnt lgkmcnt(0)
	v_cndmask_b32_e32 v57, v56, v98, vcc
	v_fmac_f32_e32 v63, v0, v61
	v_add_f32_e32 v57, v59, v57
	v_add_u32_e32 v58, 0x9250, v128
	ds_write2_b32 v58, v57, v63 offset1:1
	ds_bpermute_b32 v57, v173, v185
	v_fmac_f32_e32 v43, v0, v42
	ds_bpermute_b32 v42, v173, v103
	v_fmac_f32_e32 v181, v0, v179
	v_fmac_f32_e32 v47, v0, v46
	v_fmac_f32_e32 v150, v0, v149
	v_fmac_f32_e32 v181, v0, v182
	v_fmac_f32_e32 v47, v0, v110
	v_fmac_f32_e32 v150, v0, v175
	v_fmac_f32_e32 v181, v0, v184
	v_fmac_f32_e32 v43, v0, v44
	v_fmac_f32_e32 v47, v0, v102
	v_fmac_f32_e32 v150, v0, v177
	v_fmac_f32_e32 v181, v0, v177
	v_fmac_f32_e32 v43, v0, v45
	v_fmac_f32_e32 v47, v0, v45
	s_waitcnt lgkmcnt(0)
	v_cndmask_b32_e32 v0, v42, v57, vcc
	v_mfma_f32_32x32x16_bf16 v[18:33], v[90:93], v[38:41], v[18:33]
	v_add_f32_e32 v0, v43, v0
	v_add_u32_e32 v34, 0x9270, v128
	v_bfe_u32 v46, v120, 5, 3
	v_cndmask_b32_e32 v56, v57, v56, vcc
	ds_write2_b32 v34, v0, v47 offset1:1
	v_mul_u32_u24_e32 v43, 33, v46
	v_mad_u32_u24 v0, v46, 33, v118
	v_add_f32_e32 v56, v150, v56
	v_add_u32_e32 v58, 0x9260, v128
	v_lshl_add_u32 v0, v0, 2, v153
	v_lshlrev_b32_e32 v38, 2, v43
	v_lshlrev_b32_e32 v34, 2, v118
	ds_write2_b32 v58, v56, v181 offset1:1
	s_waitcnt lgkmcnt(0)
	s_barrier
	v_add3_u32 v35, v153, v38, v34
	ds_read_b32 v36, v0 offset:37376
	ds_read_b32 v37, v35 offset:41600
	ds_read_b32 v39, v35 offset:45824
	ds_read_b32 v40, v35 offset:50048
	v_mfma_f32_32x32x16_bf16 v[18:33], v[70:73], v[48:51], v[18:33]
	s_lshr_b32 s20, s44, 1
	s_waitcnt lgkmcnt(2)
	v_add_f32_e32 v36, v36, v37
	s_waitcnt lgkmcnt(1)
	v_add_f32_e32 v36, v36, v39
	s_waitcnt lgkmcnt(0)
	v_add_f32_e32 v36, v36, v40
	ds_write_b32 v0, v36 offset:54272
	ds_read_b32 v0, v35 offset:38432
	ds_read_b32 v36, v35 offset:42656
	ds_read_b32 v37, v35 offset:46880
	ds_read_b32 v39, v35 offset:39488
	ds_read_b32 v40, v35 offset:43712
	ds_read_b32 v41, v35 offset:47936
	ds_read_b32 v42, v35 offset:44768
	ds_read_b32 v44, v35 offset:40544
	s_waitcnt lgkmcnt(6)
	v_add_f32_e32 v0, v0, v36
	ds_read_b32 v36, v35 offset:51104
	s_waitcnt lgkmcnt(6)
	v_add_f32_e32 v0, v0, v37
	v_mfma_f32_32x32x16_bf16 v[18:33], v[66:69], v[52:55], v[18:33]
	ds_read_b32 v37, v35 offset:52160
	ds_read_b32 v45, v35 offset:53216
	ds_read_b32 v47, v35 offset:48992
	s_min_u32 s0, s20, 2
	s_waitcnt lgkmcnt(3)
	v_add_f32_e32 v0, v0, v36
	ds_write_b32 v35, v0 offset:55328
	v_add_f32_e32 v0, v39, v40
	v_add_f32_e32 v0, v0, v41
	s_waitcnt lgkmcnt(3)
	v_add_f32_e32 v0, v0, v37
	ds_write_b32 v35, v0 offset:56384
	v_add_f32_e32 v0, v44, v42
	s_add_i32 s22, s20, -1
	s_xor_b32 s21, s0, 7
	s_add_i32 s23, s20, -2
	s_waitcnt lgkmcnt(2)
	v_add_f32_e32 v0, v0, v47
	v_add_u32_e32 v39, v153, v34
	s_cmp_gt_u32 s44, 5
	v_add_f32_e32 v0, v0, v45
	s_cselect_b64 s[10:11], -1, 0
	s_cmp_lt_u32 s44, 6
	v_add_u32_e32 v44, v39, v38
	s_mov_b64 s[2:3], -1
	ds_write_b32 v35, v0 offset:57440
	s_waitcnt lgkmcnt(0)
	s_barrier
	s_cbranch_scc1 .LBB0_1292
	ds_read_b32 v34, v44 offset:54272
	s_cmp_lt_u32 s23, 2
	s_cbranch_scc1 .LBB0_1284
	s_add_i32 s0, s20, -4
	s_lshr_b32 s14, s0, 1
	s_add_i32 s14, s14, 1
	s_cmp_lt_u32 s0, 6
	v_mov_b32_e32 v35, v118
	s_cbranch_scc1 .LBB0_1285
	s_and_b32 s16, s14, -4
	s_mov_b32 s13, 2
	v_lshl_add_u32 v0, v43, 2, v155
	s_mov_b32 s12, 1
	s_mov_b32 s15, 0
	v_mov_b32_e32 v36, 0
	v_mov_b32_e32 v37, 0

; DI float fexp2(float x) { return __builtin_amdgcn_exp2f(x); }
; template <int DQK, bool MASKED, int MODE, class MF>
; DI void attn_step(const bf16_t* sK, const bf16_t* sVt, const bf16x8 (&qf)[DQK / 16], f32x16& o0, f32x16& o1, float& m, float& l,
;                   float sc, const MF& mf, int lane, f32x16 (&s)[2], float invl, bool lanevalid = true) {
;     ...
;   float mxr = -3.0e38f;
; #pragma unroll
;   for (int sub = 0; sub < 2; ++sub)
; #pragma unroll
;     for (int q = 0; q < 16; ++q) {
;       if (MASKED) { const int kk = sub * 32 + 16 * (q >> 3) + 8 * h + (q & 7); s[sub][q] = mf(kk) ? s[sub][q] : -3.0e38f; }
;       if (MODE != 2) mxr = fmaxf(mxr, s[sub][q]);
;     }
;   float alpha = 1.f;
;   if (MODE != 2) {
;     float mx = fmaxf(m, mxr * sc);
;     mx = fmaxf(mx, shx(mx, 32));
;     if (!MASKED) mx = lanevalid ? mx : m;
;     alpha = fexp2(m - mx);
;     m = mx;
;   }
;   const float moff = (!MASKED && !lanevalid) ? 1.0e30f : m;
;   float ps = 0.f;
; #pragma unroll
;   for (int sub = 0; sub < 2; ++sub)
; #pragma unroll
;     for (int q = 0; q < 16; ++q) {
;       float pv = fexp2(__builtin_fmaf(s[sub][q], sc, -moff));
;       if (MASKED && MODE != 0) pv = (s[sub][q] > -1.0e38f) ? pv : 0.f;
;       if (MODE == 2) pv *= invl;
;       s[sub][q] = pv;
;       ps += pv;
;     }
;   if (MODE != 2) {
;     ps += shx(ps, 32);
;     l = l * alpha + ps;
;   }
;   if (MODE == 1) return;
;   if (MODE == 0) {
; #pragma unroll
;     for (int q = 0; q < 16; ++q) { o0[q] *= alpha; o1[q] *= alpha; }
;   }
; #pragma unroll
;   for (int sub = 0; sub < 2; ++sub)
; #pragma unroll
;     for (int s2 = 0; s2 < 2; ++s2) {
;       union { bf16x8 v; unsigned u[4]; } pb;
; #pragma unroll
;       for (int e = 0; e < 4; ++e) pb.u[e] = pack2(s[sub][8 * s2 + 2 * e], s[sub][8 * s2 + 2 * e + 1]);
;       o0 = MFMA(vf[sub][s2][0], pb.v, o0);
;       o1 = MFMA(vf[sub][s2][1], pb.v, o1);
;     }
; DI void phase_attn_nsa(const Params& P, bf16_t* og, unsigned char* smem, int L, int G) {
;     ...
;         if ((selU >> j) & 1u) {
;           const bool lsel = (sel >> j) & 1u;
;           auto mf = [&](int kk) { return lsel && (key0 + kk <= t); };
;           if (key0 + 63 > t0) attn_step<64, true, 0>(sK + cb * KVB64, sVt + cb * KVB64, qf, o0, o1, m, l, sc, mf, lane, s, 0.f);
;           else attn_step<64, false, 0>(sK + cb * KVB64, sVt + cb * KVB64, qf, o0, o1, m, l, sc, mf, lane, s, 0.f, lsel);
.LBB0_1349:
	s_lshr_b32 s1, s2, s0
	s_bitcmp0_b32 s1, 0
	s_cbranch_scc1 .LBB0_1355
	v_lshrrev_b32_e32 v0, s0, v183
	s_add_i32 s6, s44, 63
	s_mulk_i32 s5, 0x4800
	v_and_b32_e32 v190, 1, v0
	s_mov_b64 s[0:1], -1
	s_cmp_le_u32 s6, s46
	v_max_f32_e32 v188, v141, v141
	v_add_u32_e32 v189, s5, v153
	v_cmp_eq_u32_e32 vcc, 1, v190
	s_cbranch_scc0 .LBB0_1352
	v_add_u32_e32 v0, s5, v182
	ds_read_b128 v[34:37], v0
	ds_read_b128 v[38:41], v0 offset:32
	ds_read_b128 v[106:109], v0 offset:64
	ds_read_b128 v[110:113], v0 offset:96
	ds_read_b128 v[42:45], v0 offset:4608
	ds_read_b128 v[114:117], v0 offset:4640
	ds_read_b128 v[118:121], v0 offset:4672
	ds_read_b128 v[194:197], v0 offset:4704
	s_waitcnt lgkmcnt(7)
	v_mfma_f32_32x32x16_bf16 v[58:73], v[34:37], v[74:77], 0
	v_add3_u32 v0, v189, v175, v138
	v_add3_u32 v34, v189, v177, v138
	s_waitcnt lgkmcnt(3)
	v_mfma_f32_32x32x16_bf16 v[42:57], v[42:45], v[74:77], 0
	v_mfma_f32_32x32x16_bf16 v[58:73], v[38:41], v[78:81], v[58:73]
	s_waitcnt lgkmcnt(2)
	v_mfma_f32_32x32x16_bf16 v[42:57], v[114:117], v[78:81], v[42:57]
	v_mfma_f32_32x32x16_bf16 v[58:73], v[106:109], v[82:85], v[58:73]
	s_waitcnt lgkmcnt(1)
	v_mfma_f32_32x32x16_bf16 v[42:57], v[118:121], v[82:85], v[42:57]
	v_mfma_f32_32x32x16_bf16 v[58:73], v[110:113], v[86:89], v[58:73]
	ds_read_b128 v[198:201], v0 offset:9216
	ds_read_b128 v[126:129], v0 offset:9248
	ds_read_b128 v[130:133], v34 offset:9216
	ds_read_b128 v[122:125], v34 offset:9248
	ds_read_b128 v[118:121], v0 offset:9280
	ds_read_b128 v[110:113], v0 offset:9312
	ds_read_b128 v[114:117], v34 offset:9280
	ds_read_b128 v[106:109], v34 offset:9312
	s_waitcnt lgkmcnt(8)
	v_mfma_f32_32x32x16_bf16 v[42:57], v[194:197], v[86:89], v[42:57]
	s_nop 1
	v_max3_f32 v0, v58, s8, v59
	v_max3_f32 v0, v0, v60, v61
	v_max3_f32 v0, v0, v62, v63
	v_max3_f32 v0, v0, v64, v65
	v_max3_f32 v0, v0, v66, v67
	v_max3_f32 v0, v0, v68, v69
	v_max3_f32 v0, v0, v70, v71
	v_max3_f32 v0, v0, v72, v73
	s_nop 1
	v_max3_f32 v0, v0, v42, v43
	v_max3_f32 v0, v0, v44, v45
	v_max3_f32 v0, v0, v46, v47
	v_max3_f32 v0, v0, v48, v49
	v_max3_f32 v0, v0, v50, v51
	v_max3_f32 v0, v0, v52, v53
	v_max3_f32 v0, v0, v54, v55
	v_max3_f32 v0, v0, v56, v57
	v_mul_f32_e32 v0, 0x3e38aa3b, v0
	v_max_f32_e32 v0, v188, v0
	ds_bpermute_b32 v34, v173, v0
	s_mov_b64 s[0:1], 0
	s_waitcnt lgkmcnt(0)
	v_max_f32_e32 v34, v34, v34
	v_max_f32_e32 v34, v0, v34
	v_cndmask_b32_e64 v191, v167, -v34, vcc
	v_pk_fma_f32 v[226:227], v[58:59], s[32:33], v[190:191] op_sel:[0,1,1] op_sel_hi:[1,1,1]
	v_exp_f32_e32 v58, v226
	v_fmamk_f32 v37, v60, 0x3e38aa3b, v191
	v_exp_f32_e32 v59, v227
	v_exp_f32_e32 v60, v37
	v_fmamk_f32 v35, v61, 0x3e38aa3b, v191
	v_exp_f32_e32 v61, v35
	v_add_f32_e32 v36, 0, v58
	v_fmamk_f32 v35, v62, 0x3e38aa3b, v191
	v_add_f32_e32 v36, v59, v36
	v_exp_f32_e32 v62, v35
	v_fmamk_f32 v35, v63, 0x3e38aa3b, v191
	v_add_f32_e32 v36, v60, v36
	v_exp_f32_e32 v63, v35
	v_fmamk_f32 v35, v64, 0x3e38aa3b, v191
	v_exp_f32_e32 v64, v35
	v_add_f32_e32 v35, v61, v36
	v_fmamk_f32 v36, v65, 0x3e38aa3b, v191
	v_exp_f32_e32 v65, v36
	v_pk_fma_f32 v[226:227], v[66:67], s[32:33], v[190:191] op_sel:[0,1,1] op_sel_hi:[1,1,1]
	v_add_f32_e32 v35, v62, v35
	v_exp_f32_e32 v203, v226
	v_add_f32_e32 v35, v63, v35
	v_exp_f32_e32 v204, v227
	v_pk_fma_f32 v[226:227], v[68:69], s[32:33], v[190:191] op_sel:[0,1,1] op_sel_hi:[1,1,1]
	v_add_f32_e32 v35, v64, v35
	v_exp_f32_e32 v205, v226
	v_add_f32_e32 v35, v65, v35
	v_exp_f32_e32 v206, v227
	v_pk_fma_f32 v[226:227], v[70:71], s[32:33], v[190:191] op_sel:[0,1,1] op_sel_hi:[1,1,1]
	v_add_f32_e32 v35, v203, v35
	v_exp_f32_e32 v207, v226
	v_add_f32_e32 v35, v204, v35
	v_exp_f32_e32 v208, v227
	v_pk_fma_f32 v[226:227], v[72:73], s[32:33], v[190:191] op_sel:[0,1,1] op_sel_hi:[1,1,1]
	v_add_f32_e32 v35, v205, v35
	v_exp_f32_e32 v209, v226
	v_add_f32_e32 v35, v206, v35
	v_exp_f32_e32 v210, v227
	v_pk_fma_f32 v[222:223], v[42:43], s[32:33], v[190:191] op_sel:[0,1,1] op_sel_hi:[1,1,1]
	v_add_f32_e32 v35, v207, v35
	v_exp_f32_e32 v211, v222
	v_add_f32_e32 v35, v208, v35
	v_exp_f32_e32 v212, v223
	v_pk_fma_f32 v[222:223], v[44:45], s[32:33], v[190:191] op_sel:[0,1,1] op_sel_hi:[1,1,1]
	v_add_f32_e32 v35, v209, v35
	v_exp_f32_e32 v213, v222
	v_add_f32_e32 v35, v210, v35
	v_exp_f32_e32 v214, v223
	v_pk_fma_f32 v[222:223], v[46:47], s[32:33], v[190:191] op_sel:[0,1,1] op_sel_hi:[1,1,1]
	v_add_f32_e32 v35, v211, v35
	v_exp_f32_e32 v215, v222
	v_cndmask_b32_e32 v0, v141, v34, vcc
	v_add_f32_e32 v35, v212, v35
	v_exp_f32_e32 v216, v223
	v_pk_fma_f32 v[222:223], v[48:49], s[32:33], v[190:191] op_sel:[0,1,1] op_sel_hi:[1,1,1]
	v_sub_f32_e32 v34, v141, v0
	v_add_f32_e32 v35, v213, v35
	v_exp_f32_e32 v217, v222
	v_add_f32_e32 v35, v214, v35
	v_exp_f32_e32 v202, v34
	v_add_f32_e32 v35, v215, v35
	v_add_f32_e32 v35, v216, v35
	v_add_f32_e32 v218, v217, v35
	v_pk_fma_f32 v[224:225], v[50:51], s[32:33], v[190:191] op_sel:[0,1,1] op_sel_hi:[1,1,1]
	v_exp_f32_e32 v219, v223
	v_exp_f32_e32 v220, v224
	v_pk_mul_f32 v[48:49], v[32:33], v[202:203] op_sel_hi:[1,0]
	v_pk_mul_f32 v[46:47], v[30:31], v[202:203] op_sel_hi:[1,0]
	v_pk_mul_f32 v[44:45], v[28:29], v[202:203] op_sel_hi:[1,0]
	v_pk_mul_f32 v[42:43], v[26:27], v[202:203] op_sel_hi:[1,0]
	v_pk_mul_f32 v[40:41], v[24:25], v[202:203] op_sel_hi:[1,0]
	v_pk_mul_f32 v[38:39], v[22:23], v[202:203] op_sel_hi:[1,0]
	v_pk_mul_f32 v[36:37], v[20:21], v[202:203] op_sel_hi:[1,0]
	v_pk_mul_f32 v[34:35], v[18:19], v[202:203] op_sel_hi:[1,0]
	v_cvt_pk_bf16_f32 v194, v58, v59
	v_cvt_pk_bf16_f32 v195, v60, v61
	v_cvt_pk_bf16_f32 v196, v62, v63
	v_cvt_pk_bf16_f32 v197, v64, v65
	v_pk_mul_f32 v[72:73], v[16:17], v[202:203] op_sel_hi:[1,0]
; #define MFMA(a, b, c) __builtin_amdgcn_mfma_f32_32x32x16_bf16((a), (b), (c), 0, 0, 0)
; template <int DQK, bool MASKED, int MODE, class MF>
; DI void attn_step(const bf16_t* sK, const bf16_t* sVt, const bf16x8 (&qf)[DQK / 16], f32x16& o0, f32x16& o1, float& m, float& l,
;                   float sc, const MF& mf, int lane, f32x16 (&s)[2], float invl, bool lanevalid = true) {
;     ...
;   bf16x8 kf[2][DQK / 16];
; #pragma unroll
;   for (int sub = 0; sub < 2; ++sub)
; #pragma unroll
;     for (int ks = 0; ks < DQK / 16; ++ks) kf[sub][ks] = *(const bf16x8*)(sK + (sub * 32 + pr) * KST + ks * 16 + 8 * h);
;   __builtin_amdgcn_sched_barrier(0);
; #pragma unroll
;   for (int q = 0; q < 16; ++q) { s[0][q] = 0.f; s[1][q] = 0.f; }
; #pragma unroll
;   for (int ks = 0; ks < DQK / 16; ++ks) {
;     s[0] = MFMA(kf[0][ks], qf[ks], s[0]);
;     s[1] = MFMA(kf[1][ks], qf[ks], s[1]);
;   }
;   bf16x8 vf[2][2][2];
;   if (MODE != 1) {
; #pragma unroll
;     for (int sub = 0; sub < 2; ++sub)
; #pragma unroll
;       for (int s2 = 0; s2 < 2; ++s2) {
;         vf[sub][s2][0] = *(const bf16x8*)(sVt + r * 72 + sub * 32 + s2 * 16 + 8 * h);
;         vf[sub][s2][1] = *(const bf16x8*)(sVt + (32 + r) * 72 + sub * 32 + s2 * 16 + 8 * h);
;       }
;     __builtin_amdgcn_sched_barrier(0);
;   }
;   float mxr = -3.0e38f;
; #pragma unroll
;   for (int sub = 0; sub < 2; ++sub)
; #pragma unroll
;     for (int q = 0; q < 16; ++q) {
;       if (MASKED) { const int kk = sub * 32 + 16 * (q >> 3) + 8 * h + (q & 7); s[sub][q] = mf(kk) ? s[sub][q] : -3.0e38f; }
; DI void phase_attn_nsa(const Params& P, bf16_t* og, unsigned char* smem, int L, int G) {
;     ...
;         if ((selU >> j) & 1u) {
;           const bool lsel = (sel >> j) & 1u;
;           auto mf = [&](int kk) { return lsel && (key0 + kk <= t); };
;           if (key0 + 63 > t0) attn_step<64, true, 0>(sK + cb * KVB64, sVt + cb * KVB64, qf, o0, o1, m, l, sc, mf, lane, s, 0.f);
	v_pk_mul_f32 v[70:71], v[14:15], v[202:203] op_sel_hi:[1,0]
	v_mfma_f32_32x32x16_bf16 v[34:49], v[198:201], v[194:197], v[34:49]
	v_mul_f32_e64 v68, v12, v202
	v_mul_f32_e64 v69, v13, v202
	v_mul_f32_e64 v66, v10, v202
	v_mul_f32_e64 v67, v11, v202
	v_mul_f32_e64 v64, v8, v202
	v_mul_f32_e64 v65, v9, v202
	v_pk_mul_f32 v[62:63], v[6:7], v[202:203] op_sel_hi:[1,0]
	v_pk_mul_f32 v[60:61], v[4:5], v[202:203] op_sel_hi:[1,0]
	v_pk_mul_f32 v[58:59], v[2:3], v[202:203] op_sel_hi:[1,0]
	v_add_f32_e32 v50, v219, v218
	s_nop 0
	v_mfma_f32_32x32x16_bf16 v[58:73], v[130:133], v[194:197], v[58:73]
	v_cvt_pk_bf16_f32 v130, v203, v204
	v_cvt_pk_bf16_f32 v131, v205, v206
	v_cvt_pk_bf16_f32 v132, v207, v208
	v_cvt_pk_bf16_f32 v133, v209, v210
	v_add_f32_e32 v50, v220, v50
	v_fmamk_f32 v55, v55, 0x3e38aa3b, v191
	v_exp_f32_e32 v55, v55
	v_mfma_f32_32x32x16_bf16 v[34:49], v[126:129], v[130:133], v[34:49]
	v_exp_f32_e32 v126, v225
	v_pk_fma_f32 v[222:223], v[52:53], s[32:33], v[190:191] op_sel:[0,1,1] op_sel_hi:[1,1,1]
	v_exp_f32_e32 v127, v222
	v_exp_f32_e32 v128, v223
	v_add_f32_e32 v50, v126, v50
	v_add_f32_e32 v50, v127, v50
	v_mfma_f32_32x32x16_bf16 v[58:73], v[122:125], v[130:133], v[58:73]
	v_add_f32_e32 v122, v128, v50
	v_fmamk_f32 v50, v54, 0x3e38aa3b, v191
	v_exp_f32_e32 v54, v50
	v_fmamk_f32 v56, v56, 0x3e38aa3b, v191
	v_exp_f32_e32 v56, v56
	v_fmac_f32_e32 v191, 0x3e38aa3b, v57
	v_cvt_pk_bf16_f32 v50, v211, v212
	v_cvt_pk_bf16_f32 v51, v213, v214
	v_cvt_pk_bf16_f32 v52, v215, v216
	v_cvt_pk_bf16_f32 v53, v217, v219
	v_exp_f32_e32 v57, v191
	s_nop 0
	v_mfma_f32_32x32x16_bf16 v[34:49], v[118:121], v[50:53], v[34:49]
	v_add_f32_e32 v118, v54, v122
	v_cvt_pk_bf16_f32 v54, v54, v55
	v_mfma_f32_32x32x16_bf16 v[58:73], v[114:117], v[50:53], v[58:73]
	v_add_f32_e32 v50, v55, v118
	v_add_f32_e32 v50, v56, v50
	v_add_f32_e32 v50, v57, v50
	ds_bpermute_b32 v51, v173, v50
	v_cvt_pk_bf16_f32 v52, v220, v126
	v_cvt_pk_bf16_f32 v53, v127, v128
	v_cvt_pk_bf16_f32 v55, v56, v57
	s_waitcnt lgkmcnt(0)
	v_add_f32_e32 v50, v50, v51
	v_mfma_f32_32x32x16_bf16 v[34:49], v[110:113], v[52:55], v[34:49]
	v_fmac_f32_e32 v50, v185, v202
	v_mfma_f32_32x32x16_bf16 v[58:73], v[106:109], v[52:55], v[58:73]
.LBB0_1352:
	s_andn2_b64 vcc, exec, s[0:1]
	s_cbranch_vccnz .LBB0_1354
	v_add_u32_e32 v0, s5, v172
	s_nop 6
	ds_read_b128 v[34:37], v0
	s_nop 0
	ds_read_b128 v[66:69], v0 offset:32
	ds_read_b128 v[70:73], v0 offset:64
	ds_read_b128 v[106:109], v0 offset:96
	ds_read_b128 v[38:41], v0 offset:4608
	ds_read_b128 v[110:113], v0 offset:4640
	ds_read_b128 v[114:117], v0 offset:4672
	ds_read_b128 v[194:197], v0 offset:4704
	v_cmp_eq_u32_e32 vcc, 1, v190
	s_waitcnt lgkmcnt(7)
	v_mfma_f32_32x32x16_bf16 v[50:65], v[34:37], v[74:77], 0
	v_lshlrev_b32_e32 v0, 1, v171
	s_waitcnt lgkmcnt(3)
	v_mfma_f32_32x32x16_bf16 v[34:49], v[38:41], v[74:77], 0
	v_mfma_f32_32x32x16_bf16 v[50:65], v[66:69], v[78:81], v[50:65]
	s_waitcnt lgkmcnt(2)
	v_mfma_f32_32x32x16_bf16 v[34:49], v[110:113], v[78:81], v[34:49]
	v_mfma_f32_32x32x16_bf16 v[50:65], v[70:73], v[82:85], v[50:65]
	v_add3_u32 v70, v189, v175, v0
	v_add3_u32 v0, v189, v177, v0
	s_waitcnt lgkmcnt(1)
	v_mfma_f32_32x32x16_bf16 v[34:49], v[114:117], v[82:85], v[34:49]
	v_mfma_f32_32x32x16_bf16 v[50:65], v[106:109], v[86:89], v[50:65]
	ds_read_b128 v[66:69], v70 offset:9216
	ds_read_b128 v[126:129], v70 offset:9248
	ds_read_b128 v[130:133], v0 offset:9216
	ds_read_b128 v[122:125], v0 offset:9248
	ds_read_b128 v[118:121], v70 offset:9280
	ds_read_b128 v[110:113], v70 offset:9312
	ds_read_b128 v[114:117], v0 offset:9280
	ds_read_b128 v[106:109], v0 offset:9312
	s_waitcnt lgkmcnt(8)
	v_mfma_f32_32x32x16_bf16 v[34:49], v[194:197], v[86:89], v[34:49]
	v_add_u32_e32 v0, s44, v171
	v_cmp_le_u32_e64 s[0:1], v0, v136
	s_and_b64 s[0:1], vcc, s[0:1]
	v_add_u32_e32 v70, 2, v0
	v_cndmask_b32_e64 v50, v166, v50, s[0:1]
	v_cmp_lt_u32_e64 s[0:1], v0, v136
	s_and_b64 s[0:1], vcc, s[0:1]
	s_nop 0
	v_cndmask_b32_e64 v51, v166, v51, s[0:1]
	v_cmp_le_u32_e64 s[0:1], v70, v136
	s_and_b64 s[0:1], vcc, s[0:1]
	v_add_u32_e32 v70, 3, v0
	v_cndmask_b32_e64 v52, v166, v52, s[0:1]
	v_cmp_le_u32_e64 s[0:1], v70, v136
	s_and_b64 s[0:1], vcc, s[0:1]
	v_add_u32_e32 v70, 4, v0
	v_cndmask_b32_e64 v53, v166, v53, s[0:1]
	v_cmp_le_u32_e64 s[0:1], v70, v136
	s_and_b64 s[0:1], vcc, s[0:1]
	v_add_u32_e32 v70, 5, v0
	v_cndmask_b32_e64 v54, v166, v54, s[0:1]
	v_cmp_le_u32_e64 s[0:1], v70, v136
	s_and_b64 s[0:1], vcc, s[0:1]
	v_add_u32_e32 v70, 6, v0
	v_cndmask_b32_e64 v55, v166, v55, s[0:1]
	v_cmp_le_u32_e64 s[0:1], v70, v136
	v_add_u32_e32 v70, s44, v139
	s_and_b64 s[0:1], vcc, s[0:1]
	v_or_b32_e32 v71, 7, v70
	v_cndmask_b32_e64 v56, v166, v56, s[0:1]
	v_cmp_le_u32_e64 s[0:1], v71, v136
	s_and_b64 s[0:1], vcc, s[0:1]
	v_add_u32_e32 v71, 16, v0
	v_cndmask_b32_e64 v57, v166, v57, s[0:1]
	v_cmp_le_u32_e64 s[0:1], v71, v136
	s_and_b64 s[0:1], vcc, s[0:1]
	v_add_u32_e32 v71, 17, v0
	v_cndmask_b32_e64 v58, v166, v58, s[0:1]
	v_cmp_le_u32_e64 s[0:1], v71, v136
	s_and_b64 s[0:1], vcc, s[0:1]
	v_add_u32_e32 v71, 18, v0
	v_cndmask_b32_e64 v59, v166, v59, s[0:1]
	v_cmp_le_u32_e64 s[0:1], v71, v136
	s_and_b64 s[0:1], vcc, s[0:1]
	v_add_u32_e32 v71, 19, v0
	v_cndmask_b32_e64 v60, v166, v60, s[0:1]
	v_cmp_le_u32_e64 s[0:1], v71, v136
	s_and_b64 s[0:1], vcc, s[0:1]
	v_add_u32_e32 v71, 20, v0
	v_cndmask_b32_e64 v61, v166, v61, s[0:1]
	v_cmp_le_u32_e64 s[0:1], v71, v136
	s_and_b64 s[0:1], vcc, s[0:1]
	v_add_u32_e32 v71, 21, v0
	v_cndmask_b32_e64 v62, v166, v62, s[0:1]
	v_cmp_le_u32_e64 s[0:1], v71, v136
	s_and_b64 s[0:1], vcc, s[0:1]
	v_add_u32_e32 v71, 22, v0
	v_cndmask_b32_e64 v63, v166, v63, s[0:1]
; DI float shx(float v, int m) { return __shfl_xor(v, m, 64); }
; template <int DQK, bool MASKED, int MODE, class MF>
; DI void attn_step(const bf16_t* sK, const bf16_t* sVt, const bf16x8 (&qf)[DQK / 16], f32x16& o0, f32x16& o1, float& m, float& l,
;                   float sc, const MF& mf, int lane, f32x16 (&s)[2], float invl, bool lanevalid = true) {
;     ...
;   float mxr = -3.0e38f;
; #pragma unroll
;   for (int sub = 0; sub < 2; ++sub)
; #pragma unroll
;     for (int q = 0; q < 16; ++q) {
;       if (MASKED) { const int kk = sub * 32 + 16 * (q >> 3) + 8 * h + (q & 7); s[sub][q] = mf(kk) ? s[sub][q] : -3.0e38f; }
;       if (MODE != 2) mxr = fmaxf(mxr, s[sub][q]);
;     }
;   float alpha = 1.f;
;   if (MODE != 2) {
;     float mx = fmaxf(m, mxr * sc);
;     mx = fmaxf(mx, shx(mx, 32));
; DI void phase_attn_nsa(const Params& P, bf16_t* og, unsigned char* smem, int L, int G) {
;     ...
;         if ((selU >> j) & 1u) {
;           const bool lsel = (sel >> j) & 1u;
;           auto mf = [&](int kk) { return lsel && (key0 + kk <= t); };
;           if (key0 + 63 > t0) attn_step<64, true, 0>(sK + cb * KVB64, sVt + cb * KVB64, qf, o0, o1, m, l, sc, mf, lane, s, 0.f);
	v_cmp_le_u32_e64 s[0:1], v71, v136
	s_and_b64 s[0:1], vcc, s[0:1]
	v_or_b32_e32 v71, 23, v70
	v_cndmask_b32_e64 v64, v166, v64, s[0:1]
	v_cmp_le_u32_e64 s[0:1], v71, v136
	s_and_b64 s[0:1], vcc, s[0:1]
	v_add_u32_e32 v71, 32, v0
	v_cndmask_b32_e64 v65, v166, v65, s[0:1]
	v_cmp_le_u32_e64 s[0:1], v71, v136
	s_and_b64 s[0:1], vcc, s[0:1]
	v_add_u32_e32 v71, 33, v0
	v_cndmask_b32_e64 v34, v166, v34, s[0:1]
	v_cmp_le_u32_e64 s[0:1], v71, v136
	s_and_b64 s[0:1], vcc, s[0:1]
	v_add_u32_e32 v71, 34, v0
	v_cndmask_b32_e64 v35, v166, v35, s[0:1]
	v_cmp_le_u32_e64 s[0:1], v71, v136
	s_and_b64 s[0:1], vcc, s[0:1]
	v_add_u32_e32 v71, 35, v0
	v_cndmask_b32_e64 v36, v166, v36, s[0:1]
	v_cmp_le_u32_e64 s[0:1], v71, v136
	s_and_b64 s[0:1], vcc, s[0:1]
	v_add_u32_e32 v71, 36, v0
	v_cndmask_b32_e64 v37, v166, v37, s[0:1]
	v_cmp_le_u32_e64 s[0:1], v71, v136
	s_and_b64 s[0:1], vcc, s[0:1]
	v_add_u32_e32 v71, 37, v0
	v_cndmask_b32_e64 v38, v166, v38, s[0:1]
	v_cmp_le_u32_e64 s[0:1], v71, v136
	s_and_b64 s[0:1], vcc, s[0:1]
	v_add_u32_e32 v71, 38, v0
	v_cndmask_b32_e64 v39, v166, v39, s[0:1]
	v_cmp_le_u32_e64 s[0:1], v71, v136
	s_and_b64 s[0:1], vcc, s[0:1]
	v_or_b32_e32 v71, 39, v70
	v_cndmask_b32_e64 v40, v166, v40, s[0:1]
	v_cmp_le_u32_e64 s[0:1], v71, v136
	s_and_b64 s[0:1], vcc, s[0:1]
	v_add_u32_e32 v71, 48, v0
	v_cndmask_b32_e64 v41, v166, v41, s[0:1]
	v_cmp_le_u32_e64 s[0:1], v71, v136
	s_and_b64 s[0:1], vcc, s[0:1]
	v_add_u32_e32 v71, 49, v0
	v_cndmask_b32_e64 v42, v166, v42, s[0:1]
	v_cmp_le_u32_e64 s[0:1], v71, v136
	s_and_b64 s[0:1], vcc, s[0:1]
	s_nop 0
	v_cndmask_b32_e64 v189, v166, v43, s[0:1]
	v_add_u32_e32 v43, 50, v0
	v_cmp_le_u32_e64 s[0:1], v43, v136
	s_and_b64 s[0:1], vcc, s[0:1]
	v_add_u32_e32 v43, 51, v0
	v_cndmask_b32_e64 v190, v166, v44, s[0:1]
	v_cmp_le_u32_e64 s[0:1], v43, v136
	s_and_b64 s[0:1], vcc, s[0:1]
	v_add_u32_e32 v43, 52, v0
	v_cndmask_b32_e64 v191, v166, v45, s[0:1]
	v_cmp_le_u32_e64 s[0:1], v43, v136
	s_and_b64 s[0:1], vcc, s[0:1]
	v_add_u32_e32 v43, 53, v0
	v_cndmask_b32_e64 v194, v166, v46, s[0:1]
	v_cmp_le_u32_e64 s[0:1], v43, v136
	s_and_b64 s[0:1], vcc, s[0:1]
	v_add_u32_e32 v0, 54, v0
	v_cndmask_b32_e64 v195, v166, v47, s[0:1]
	v_cmp_le_u32_e64 s[0:1], v0, v136
	s_and_b64 s[0:1], vcc, s[0:1]
	v_or_b32_e32 v0, 55, v70
	v_cndmask_b32_e64 v196, v166, v48, s[0:1]
	v_cmp_le_u32_e64 s[0:1], v0, v136
	v_max3_f32 v0, v50, s8, v51
	v_max3_f32 v0, v0, v52, v53
	v_max3_f32 v0, v0, v54, v55
	v_max3_f32 v0, v0, v56, v57
	v_max3_f32 v0, v0, v58, v59
	v_max3_f32 v0, v0, v60, v61
	v_max3_f32 v0, v0, v62, v63
	v_max3_f32 v0, v0, v64, v65
	v_max3_f32 v0, v0, v34, v35
	v_max3_f32 v0, v0, v36, v37
	v_max3_f32 v0, v0, v38, v39
	v_max3_f32 v0, v0, v40, v41
	v_max3_f32 v0, v0, v42, v189
	s_and_b64 vcc, vcc, s[0:1]
	v_max3_f32 v0, v0, v190, v191
	v_cndmask_b32_e32 v197, v166, v49, vcc
	v_max3_f32 v0, v0, v194, v195
	v_max3_f32 v0, v0, v196, v197
	v_mul_f32_e32 v0, 0x3e38aa3b, v0
	v_max_f32_e32 v0, v188, v0
	ds_bpermute_b32 v43, v173, v0
	s_waitcnt lgkmcnt(0)
; #define MFMA(a, b, c) __builtin_amdgcn_mfma_f32_32x32x16_bf16((a), (b), (c), 0, 0, 0)
; DI unsigned pack2(float a, float b) { f32x2_t v = {a, b}; bf16x2_t r = __builtin_convertvector(v, bf16x2_t); return __builtin_bit_cast(unsigned, r); }
; DI float fexp2(float x) { return __builtin_amdgcn_exp2f(x); }
; DI float shx(float v, int m) { return __shfl_xor(v, m, 64); }
; template <int DQK, bool MASKED, int MODE, class MF>
; DI void attn_step(const bf16_t* sK, const bf16_t* sVt, const bf16x8 (&qf)[DQK / 16], f32x16& o0, f32x16& o1, float& m, float& l,
;                   float sc, const MF& mf, int lane, f32x16 (&s)[2], float invl, bool lanevalid = true) {
;     ...
;   float alpha = 1.f;
;   if (MODE != 2) {
;     float mx = fmaxf(m, mxr * sc);
;     mx = fmaxf(mx, shx(mx, 32));
;     if (!MASKED) mx = lanevalid ? mx : m;
;     alpha = fexp2(m - mx);
;     m = mx;
;   }
;   const float moff = (!MASKED && !lanevalid) ? 1.0e30f : m;
;   float ps = 0.f;
; #pragma unroll
;   for (int sub = 0; sub < 2; ++sub)
; #pragma unroll
;     for (int q = 0; q < 16; ++q) {
;       float pv = fexp2(__builtin_fmaf(s[sub][q], sc, -moff));
;       if (MASKED && MODE != 0) pv = (s[sub][q] > -1.0e38f) ? pv : 0.f;
;       if (MODE == 2) pv *= invl;
;       s[sub][q] = pv;
;       ps += pv;
;     }
;   if (MODE != 2) {
;     ps += shx(ps, 32);
;     l = l * alpha + ps;
;   }
;   if (MODE == 1) return;
;   if (MODE == 0) {
; #pragma unroll
;     for (int q = 0; q < 16; ++q) { o0[q] *= alpha; o1[q] *= alpha; }
;   }
; #pragma unroll
;   for (int sub = 0; sub < 2; ++sub)
; #pragma unroll
;     for (int s2 = 0; s2 < 2; ++s2) {
;       union { bf16x8 v; unsigned u[4]; } pb;
; #pragma unroll
;       for (int e = 0; e < 4; ++e) pb.u[e] = pack2(s[sub][8 * s2 + 2 * e], s[sub][8 * s2 + 2 * e + 1]);
;       o0 = MFMA(vf[sub][s2][0], pb.v, o0);
;       o1 = MFMA(vf[sub][s2][1], pb.v, o1);
;     }
	v_max_f32_e32 v43, v43, v43
	v_max_f32_e32 v0, v0, v43
	v_fma_f32 v43, v50, s33, -v0
	v_exp_f32_e32 v50, v43
	v_fma_f32 v43, v51, s33, -v0
	v_exp_f32_e32 v51, v43
	v_pk_fma_f32 v[224:225], v[52:53], s[32:33], v[0:1] op_sel:[0,1,0] op_sel_hi:[1,1,0] neg_lo:[0,0,1] neg_hi:[0,0,1]
	v_exp_f32_e32 v70, v224
	v_exp_f32_e32 v53, v225
	v_fma_f32 v45, v54, s33, -v0
	v_add_f32_e32 v44, 0, v50
	v_exp_f32_e32 v54, v45
	v_fma_f32 v45, v55, s33, -v0
	v_add_f32_e32 v44, v51, v44
	v_exp_f32_e32 v55, v45
	v_fma_f32 v45, v56, s33, -v0
	v_add_f32_e32 v44, v70, v44
	v_exp_f32_e32 v56, v45
	v_fma_f32 v45, v57, s33, -v0
	v_add_f32_e32 v44, v53, v44
	v_exp_f32_e32 v57, v45
	v_pk_fma_f32 v[224:225], v[58:59], s[32:33], v[0:1] op_sel:[0,1,0] op_sel_hi:[1,1,0] neg_lo:[0,0,1] neg_hi:[0,0,1]
	v_sub_f32_e32 v43, v141, v0
	v_add_f32_e32 v44, v54, v44
	v_exp_f32_e32 v141, v224
	v_add_f32_e32 v44, v55, v44
	v_exp_f32_e32 v188, v225
	v_pk_fma_f32 v[224:225], v[60:61], s[32:33], v[0:1] op_sel:[0,1,0] op_sel_hi:[1,1,0] neg_lo:[0,0,1] neg_hi:[0,0,1]
	v_add_f32_e32 v44, v56, v44
	v_exp_f32_e32 v198, v224
	v_add_f32_e32 v44, v57, v44
	v_exp_f32_e32 v199, v225
	v_pk_fma_f32 v[224:225], v[62:63], s[32:33], v[0:1] op_sel:[0,1,0] op_sel_hi:[1,1,0] neg_lo:[0,0,1] neg_hi:[0,0,1]
	v_add_f32_e32 v44, v141, v44
	v_exp_f32_e32 v200, v224
	v_add_f32_e32 v44, v188, v44
	v_exp_f32_e32 v201, v225
	v_pk_fma_f32 v[224:225], v[64:65], s[32:33], v[0:1] op_sel:[0,1,0] op_sel_hi:[1,1,0] neg_lo:[0,0,1] neg_hi:[0,0,1]
	v_add_f32_e32 v44, v198, v44
	v_exp_f32_e32 v202, v224
	v_add_f32_e32 v44, v199, v44
	v_exp_f32_e32 v203, v225
	v_pk_fma_f32 v[222:223], v[34:35], s[32:33], v[0:1] op_sel:[0,1,0] op_sel_hi:[1,1,0] neg_lo:[0,0,1] neg_hi:[0,0,1]
	v_add_f32_e32 v44, v200, v44
	v_exp_f32_e32 v204, v222
	v_add_f32_e32 v44, v201, v44
	v_exp_f32_e32 v205, v223
	v_pk_fma_f32 v[222:223], v[36:37], s[32:33], v[0:1] op_sel:[0,1,0] op_sel_hi:[1,1,0] neg_lo:[0,0,1] neg_hi:[0,0,1]
	v_add_f32_e32 v44, v202, v44
	v_exp_f32_e32 v206, v222
	v_add_f32_e32 v34, v203, v44
	v_exp_f32_e32 v207, v223
	v_pk_fma_f32 v[222:223], v[38:39], s[32:33], v[0:1] op_sel:[0,1,0] op_sel_hi:[1,1,0] neg_lo:[0,0,1] neg_hi:[0,0,1]
	v_add_f32_e32 v34, v204, v34
	v_exp_f32_e32 v208, v222
	v_add_f32_e32 v34, v205, v34
	v_exp_f32_e32 v209, v223
	v_pk_fma_f32 v[222:223], v[40:41], s[32:33], v[0:1] op_sel:[0,1,0] op_sel_hi:[1,1,0] neg_lo:[0,0,1] neg_hi:[0,0,1]
	v_add_f32_e32 v34, v206, v34
	v_exp_f32_e32 v210, v222
	v_add_f32_e32 v34, v207, v34
	v_add_f32_e32 v34, v208, v34
	v_exp_f32_e32 v52, v43
	v_add_f32_e32 v34, v209, v34
	v_add_f32_e32 v211, v210, v34
	v_exp_f32_e32 v212, v223
	v_fma_f32 v34, v42, s33, -v0
	v_exp_f32_e32 v213, v34
	v_pk_mul_f32 v[48:49], v[32:33], v[52:53] op_sel_hi:[1,0]
	v_pk_mul_f32 v[46:47], v[30:31], v[52:53] op_sel_hi:[1,0]
	v_pk_mul_f32 v[44:45], v[28:29], v[52:53] op_sel_hi:[1,0]
	v_pk_mul_f32 v[42:43], v[26:27], v[52:53] op_sel_hi:[1,0]
	v_pk_mul_f32 v[40:41], v[24:25], v[52:53] op_sel_hi:[1,0]
	v_pk_mul_f32 v[38:39], v[22:23], v[52:53] op_sel_hi:[1,0]
	v_pk_mul_f32 v[36:37], v[20:21], v[52:53] op_sel_hi:[1,0]
	v_pk_mul_f32 v[34:35], v[18:19], v[52:53] op_sel_hi:[1,0]
	v_pk_mul_f32 v[72:73], v[16:17], v[52:53] op_sel_hi:[1,0]
	v_cvt_pk_bf16_f32 v16, v50, v51
	v_cvt_pk_bf16_f32 v17, v70, v53
	v_cvt_pk_bf16_f32 v18, v54, v55
	v_cvt_pk_bf16_f32 v19, v56, v57
	v_pk_mul_f32 v[70:71], v[14:15], v[52:53] op_sel_hi:[1,0]
	v_pk_mul_f32 v[64:65], v[8:9], v[52:53] op_sel_hi:[1,0]
	v_mfma_f32_32x32x16_bf16 v[34:49], v[66:69], v[16:19], v[34:49]
	v_mul_f32_e64 v68, v12, v52
	v_mul_f32_e64 v69, v13, v52
	v_mul_f32_e64 v66, v10, v52
	v_mul_f32_e64 v67, v11, v52
	v_mul_f32_e64 v62, v6, v52
	v_mul_f32_e64 v63, v7, v52
	v_pk_mul_f32 v[60:61], v[4:5], v[52:53] op_sel_hi:[1,0]
	v_pk_mul_f32 v[58:59], v[2:3], v[52:53] op_sel_hi:[1,0]
	v_add_f32_e32 v2, v212, v211
	v_add_f32_e32 v6, v213, v2
	v_mfma_f32_32x32x16_bf16 v[58:73], v[130:133], v[16:19], v[58:73]
	v_cvt_pk_bf16_f32 v2, v141, v188
	v_cvt_pk_bf16_f32 v3, v198, v199
	v_cvt_pk_bf16_f32 v4, v200, v201
	v_cvt_pk_bf16_f32 v5, v202, v203
	v_fma_f32 v7, v189, s33, -v0
	v_exp_f32_e32 v7, v7
	v_pk_fma_f32 v[222:223], v[190:191], s[32:33], v[0:1] op_sel:[0,1,0] op_sel_hi:[1,1,0] neg_lo:[0,0,1] neg_hi:[0,0,1]
	v_mfma_f32_32x32x16_bf16 v[34:49], v[126:129], v[2:5], v[34:49]
	v_exp_f32_e32 v8, v222
	v_exp_f32_e32 v9, v223
	v_pk_fma_f32 v[222:223], v[194:195], s[32:33], v[0:1] op_sel:[0,1,0] op_sel_hi:[1,1,0] neg_lo:[0,0,1] neg_hi:[0,0,1]
	v_add_f32_e32 v6, v7, v6
	v_exp_f32_e32 v11, v223
	v_pk_fma_f32 v[224:225], v[196:197], s[32:33], v[0:1] op_sel:[0,1,0] op_sel_hi:[1,1,0] neg_lo:[0,0,1] neg_hi:[0,0,1]
	v_mfma_f32_32x32x16_bf16 v[58:73], v[122:125], v[2:5], v[58:73]
	v_exp_f32_e32 v10, v222
	v_cvt_pk_bf16_f32 v2, v204, v205
	v_cvt_pk_bf16_f32 v3, v206, v207
	v_cvt_pk_bf16_f32 v4, v208, v209
	v_cvt_pk_bf16_f32 v5, v210, v212
	v_add_f32_e32 v6, v8, v6
	v_exp_f32_e32 v12, v224
	v_mfma_f32_32x32x16_bf16 v[34:49], v[118:121], v[2:5], v[34:49]
	v_add_f32_e32 v6, v9, v6
	v_exp_f32_e32 v13, v225
	v_add_f32_e32 v6, v10, v6
	v_mfma_f32_32x32x16_bf16 v[58:73], v[114:117], v[2:5], v[58:73]
	v_add_f32_e32 v2, v11, v6
	v_add_f32_e32 v2, v12, v2
	v_add_f32_e32 v6, v13, v2
	v_cvt_pk_bf16_f32 v2, v213, v7
	v_cvt_pk_bf16_f32 v3, v8, v9
	v_cvt_pk_bf16_f32 v4, v10, v11
	v_cvt_pk_bf16_f32 v5, v12, v13
	ds_bpermute_b32 v7, v173, v6
	s_waitcnt lgkmcnt(0)
	v_add_f32_e32 v50, v6, v7
	v_mfma_f32_32x32x16_bf16 v[34:49], v[110:113], v[2:5], v[34:49]
	v_fmac_f32_e32 v50, v185, v52
	v_mfma_f32_32x32x16_bf16 v[58:73], v[106:109], v[2:5], v[58:73]

; #define MFMA(a, b, c) __builtin_amdgcn_mfma_f32_32x32x16_bf16((a), (b), (c), 0, 0, 0)
; template <int DQK, bool MASKED, int MODE, class MF>
; DI void attn_step(const bf16_t* sK, const bf16_t* sVt, const bf16x8 (&qf)[DQK / 16], f32x16& o0, f32x16& o1, float& m, float& l,
;                   float sc, const MF& mf, int lane, f32x16 (&s)[2], float invl, bool lanevalid = true) {
;     ...
;   bf16x8 kf[2][DQK / 16];
; #pragma unroll
;   for (int sub = 0; sub < 2; ++sub)
; #pragma unroll
;     for (int ks = 0; ks < DQK / 16; ++ks) kf[sub][ks] = *(const bf16x8*)(sK + (sub * 32 + pr) * KST + ks * 16 + 8 * h);
;   __builtin_amdgcn_sched_barrier(0);
; #pragma unroll
;   for (int q = 0; q < 16; ++q) { s[0][q] = 0.f; s[1][q] = 0.f; }
; #pragma unroll
;   for (int ks = 0; ks < DQK / 16; ++ks) {
;     s[0] = MFMA(kf[0][ks], qf[ks], s[0]);
;     s[1] = MFMA(kf[1][ks], qf[ks], s[1]);
;   }
;   bf16x8 vf[2][2][2];
;   if (MODE != 1) {
; #pragma unroll
;     for (int sub = 0; sub < 2; ++sub)
; #pragma unroll
;       for (int s2 = 0; s2 < 2; ++s2) {
;         vf[sub][s2][0] = *(const bf16x8*)(sVt + r * 72 + sub * 32 + s2 * 16 + 8 * h);
;         vf[sub][s2][1] = *(const bf16x8*)(sVt + (32 + r) * 72 + sub * 32 + s2 * 16 + 8 * h);
;       }
;     __builtin_amdgcn_sched_barrier(0);
;   }
;   float mxr = -3.0e38f;
; #pragma unroll
;   for (int sub = 0; sub < 2; ++sub)
; #pragma unroll
;     for (int q = 0; q < 16; ++q) {
;       if (MASKED) { const int kk = sub * 32 + 16 * (q >> 3) + 8 * h + (q & 7); s[sub][q] = mf(kk) ? s[sub][q] : -3.0e38f; }
; DI void phase_attn_nsa(const Params& P, bf16_t* og, unsigned char* smem, int L, int G) {
;     ...
;       for (int j = jlo; j <= jhi; ++j) {
;         const int key0 = j * 64, cb = (j - jlo) & 1;
;         __syncthreads();
;         if (j < jhi) kv64_store(R, sK + (cb ^ 1) * KVB64, sVt + (cb ^ 1) * KVB64, tid);
;         if (j + 1 < jhi) kv64_fetch(R, kb, 256, vb, SEQ, key0 + 128, true, tid);
;         __builtin_amdgcn_sched_barrier(0);
;         auto mf = [&](int kk) { const int key = key0 + kk; return key <= t && key > t - 512; };
;         if (key0 + 63 > t0 || key0 <= t0 + 31 - 512) attn_step<64, true, 0>(sK + cb * KVB64, sVt + cb * KVB64, qf, o0, o1, m, l, sc, mf, lane, s, 0.f);
;         else attn_step<64, false, 0>(sK + cb * KVB64, sVt + cb * KVB64, qf, o0, o1, m, l, sc, mf, lane, s, 0.f);
.LBB0_1365:
	s_add_i32 s0, s44, 63
	s_cmp_le_u32 s0, s46
	s_cselect_b64 s[0:1], -1, 0
	s_cmp_gt_i32 s44, s3
	s_cselect_b64 s[6:7], -1, 0
	s_and_b64 s[6:7], s[0:1], s[6:7]
	s_mulk_i32 s5, 0x2400
	v_lshl_add_u32 v98, s5, 1, v153
	s_mov_b64 s[0:1], -1
	s_and_b64 vcc, exec, s[6:7]
	v_max_f32_e32 v149, v148, v148
	s_cbranch_vccnz .LBB0_1367
	v_lshl_add_u32 v0, s5, 1, v172
	ds_read_b128 v[2:5], v0
	ds_read_b128 v[34:37], v0 offset:32
	ds_read_b128 v[38:41], v0 offset:64
	ds_read_b128 v[58:61], v0 offset:96
	ds_read_b128 v[6:9], v0 offset:4608
	ds_read_b128 v[62:65], v0 offset:4640
	ds_read_b128 v[66:69], v0 offset:4672
	ds_read_b128 v[184:187], v0 offset:4704
	s_waitcnt lgkmcnt(7)
	v_mfma_f32_32x32x16_bf16 v[18:33], v[2:5], v[74:77], 0
	v_lshlrev_b32_e32 v0, 1, v171
	s_waitcnt lgkmcnt(3)
	v_mfma_f32_32x32x16_bf16 v[2:17], v[6:9], v[74:77], 0
	v_mfma_f32_32x32x16_bf16 v[18:33], v[34:37], v[78:81], v[18:33]
	v_add3_u32 v34, v98, v175, v0
	v_add3_u32 v0, v98, v177, v0
	s_waitcnt lgkmcnt(2)
	v_mfma_f32_32x32x16_bf16 v[2:17], v[62:65], v[78:81], v[2:17]
	v_mfma_f32_32x32x16_bf16 v[18:33], v[38:41], v[82:85], v[18:33]
	s_waitcnt lgkmcnt(1)
	v_mfma_f32_32x32x16_bf16 v[2:17], v[66:69], v[82:85], v[2:17]
	v_mfma_f32_32x32x16_bf16 v[18:33], v[58:61], v[86:89], v[18:33]
	ds_read_b128 v[94:97], v34 offset:9216
	ds_read_b128 v[70:73], v34 offset:9248
	ds_read_b128 v[90:93], v0 offset:9216
	ds_read_b128 v[66:69], v0 offset:9248
	ds_read_b128 v[62:65], v34 offset:9280
	ds_read_b128 v[38:41], v34 offset:9312
	ds_read_b128 v[58:61], v0 offset:9280
	ds_read_b128 v[34:37], v0 offset:9312
	s_waitcnt lgkmcnt(8)
	v_mfma_f32_32x32x16_bf16 v[2:17], v[184:187], v[86:89], v[2:17]
	v_add_u32_e32 v0, s44, v171
	v_cmp_le_u32_e32 vcc, v0, v136
	v_cmp_gt_i32_e64 s[0:1], v0, v146
	s_and_b64 vcc, vcc, s[0:1]
	v_cndmask_b32_e32 v18, v166, v18, vcc
	v_cmp_lt_u32_e32 vcc, v0, v136
	v_cmp_ge_i32_e64 s[0:1], v0, v146
	s_and_b64 vcc, vcc, s[0:1]
	v_add_u32_e32 v99, 2, v0
	v_cndmask_b32_e32 v19, v166, v19, vcc
	v_cmp_le_u32_e32 vcc, v99, v136
	v_cmp_gt_i32_e64 s[0:1], v99, v146
	s_and_b64 vcc, vcc, s[0:1]
	v_add_u32_e32 v99, 3, v0
	v_cndmask_b32_e32 v20, v166, v20, vcc
	v_cmp_le_u32_e32 vcc, v99, v136
	v_cmp_gt_i32_e64 s[0:1], v99, v146
	s_and_b64 vcc, vcc, s[0:1]
	v_add_u32_e32 v99, 4, v0
	v_cndmask_b32_e32 v21, v166, v21, vcc
	v_cmp_le_u32_e32 vcc, v99, v136
	v_cmp_gt_i32_e64 s[0:1], v99, v146
	s_and_b64 vcc, vcc, s[0:1]
	v_add_u32_e32 v99, 5, v0
	v_cndmask_b32_e32 v22, v166, v22, vcc
	v_cmp_le_u32_e32 vcc, v99, v136
	v_cmp_gt_i32_e64 s[0:1], v99, v146
	s_and_b64 vcc, vcc, s[0:1]
	v_add_u32_e32 v99, 6, v0
	v_cndmask_b32_e32 v23, v166, v23, vcc
	v_cmp_le_u32_e32 vcc, v99, v136
	v_cmp_gt_i32_e64 s[0:1], v99, v146
	v_add_u32_e32 v99, s44, v139
	s_and_b64 vcc, vcc, s[0:1]
	v_or_b32_e32 v100, 7, v99
	v_cndmask_b32_e32 v24, v166, v24, vcc
	v_cmp_le_u32_e32 vcc, v100, v136
	v_cmp_gt_i32_e64 s[0:1], v100, v146
	s_and_b64 vcc, vcc, s[0:1]
	v_add_u32_e32 v100, 16, v0
	v_cndmask_b32_e32 v25, v166, v25, vcc
	v_cmp_le_u32_e32 vcc, v100, v136
	v_cmp_gt_i32_e64 s[0:1], v100, v146
	s_and_b64 vcc, vcc, s[0:1]
	v_add_u32_e32 v100, 17, v0
	v_cndmask_b32_e32 v26, v166, v26, vcc
	v_cmp_le_u32_e32 vcc, v100, v136
	v_cmp_gt_i32_e64 s[0:1], v100, v146
	s_and_b64 vcc, vcc, s[0:1]
	v_add_u32_e32 v100, 18, v0
	v_cndmask_b32_e32 v27, v166, v27, vcc
	v_cmp_le_u32_e32 vcc, v100, v136
	v_cmp_gt_i32_e64 s[0:1], v100, v146
	s_and_b64 vcc, vcc, s[0:1]
	v_add_u32_e32 v100, 19, v0
	v_cndmask_b32_e32 v28, v166, v28, vcc
	v_cmp_le_u32_e32 vcc, v100, v136
	v_cmp_gt_i32_e64 s[0:1], v100, v146
	s_and_b64 vcc, vcc, s[0:1]
	v_add_u32_e32 v100, 20, v0
	v_cndmask_b32_e32 v29, v166, v29, vcc
	v_cmp_le_u32_e32 vcc, v100, v136
	v_cmp_gt_i32_e64 s[0:1], v100, v146
	s_and_b64 vcc, vcc, s[0:1]
	v_add_u32_e32 v100, 21, v0
	v_cndmask_b32_e32 v30, v166, v30, vcc
	v_cmp_le_u32_e32 vcc, v100, v136
	v_cmp_gt_i32_e64 s[0:1], v100, v146
	s_and_b64 vcc, vcc, s[0:1]
	v_add_u32_e32 v100, 22, v0
	v_cndmask_b32_e32 v31, v166, v31, vcc
	v_cmp_le_u32_e32 vcc, v100, v136
	v_cmp_gt_i32_e64 s[0:1], v100, v146
	s_and_b64 vcc, vcc, s[0:1]
	v_or_b32_e32 v100, 23, v99
	v_cndmask_b32_e32 v32, v166, v32, vcc
	v_cmp_le_u32_e32 vcc, v100, v136
	v_cmp_gt_i32_e64 s[0:1], v100, v146
	s_and_b64 vcc, vcc, s[0:1]
	v_add_u32_e32 v100, 32, v0
	v_cndmask_b32_e32 v33, v166, v33, vcc
	v_cmp_le_u32_e32 vcc, v100, v136
	v_cmp_gt_i32_e64 s[0:1], v100, v146
	s_and_b64 vcc, vcc, s[0:1]
	v_add_u32_e32 v100, 33, v0
	v_cndmask_b32_e32 v2, v166, v2, vcc
	v_cmp_le_u32_e32 vcc, v100, v136
	v_cmp_gt_i32_e64 s[0:1], v100, v146
	s_and_b64 vcc, vcc, s[0:1]
	v_add_u32_e32 v100, 34, v0
	v_cndmask_b32_e32 v3, v166, v3, vcc
	v_cmp_le_u32_e32 vcc, v100, v136
	v_cmp_gt_i32_e64 s[0:1], v100, v146
	s_and_b64 vcc, vcc, s[0:1]
	v_add_u32_e32 v100, 35, v0
	v_cndmask_b32_e32 v4, v166, v4, vcc
	v_cmp_le_u32_e32 vcc, v100, v136
	v_cmp_gt_i32_e64 s[0:1], v100, v146
	s_and_b64 vcc, vcc, s[0:1]
	v_add_u32_e32 v100, 36, v0
	v_cndmask_b32_e32 v5, v166, v5, vcc
	v_cmp_le_u32_e32 vcc, v100, v136
	v_cmp_gt_i32_e64 s[0:1], v100, v146
	s_and_b64 vcc, vcc, s[0:1]
	v_add_u32_e32 v100, 37, v0
	v_cndmask_b32_e32 v6, v166, v6, vcc
	v_cmp_le_u32_e32 vcc, v100, v136
	v_cmp_gt_i32_e64 s[0:1], v100, v146
	s_and_b64 vcc, vcc, s[0:1]
	v_add_u32_e32 v100, 38, v0
	v_cndmask_b32_e32 v7, v166, v7, vcc
	v_cmp_le_u32_e32 vcc, v100, v136
	v_cmp_gt_i32_e64 s[0:1], v100, v146
	s_and_b64 vcc, vcc, s[0:1]
	v_or_b32_e32 v100, 39, v99
	v_cndmask_b32_e32 v8, v166, v8, vcc
	v_cmp_le_u32_e32 vcc, v100, v136
	v_cmp_gt_i32_e64 s[0:1], v100, v146
	s_and_b64 vcc, vcc, s[0:1]
	v_add_u32_e32 v100, 48, v0
	v_cndmask_b32_e32 v9, v166, v9, vcc
; DI float fexp2(float x) { return __builtin_amdgcn_exp2f(x); }
; DI float shx(float v, int m) { return __shfl_xor(v, m, 64); }
; template <int DQK, bool MASKED, int MODE, class MF>
; DI void attn_step(const bf16_t* sK, const bf16_t* sVt, const bf16x8 (&qf)[DQK / 16], f32x16& o0, f32x16& o1, float& m, float& l,
;                   float sc, const MF& mf, int lane, f32x16 (&s)[2], float invl, bool lanevalid = true) {
;     ...
;   float mxr = -3.0e38f;
; #pragma unroll
;   for (int sub = 0; sub < 2; ++sub)
; #pragma unroll
;     for (int q = 0; q < 16; ++q) {
;       if (MASKED) { const int kk = sub * 32 + 16 * (q >> 3) + 8 * h + (q & 7); s[sub][q] = mf(kk) ? s[sub][q] : -3.0e38f; }
;       if (MODE != 2) mxr = fmaxf(mxr, s[sub][q]);
;     }
;   float alpha = 1.f;
;   if (MODE != 2) {
;     float mx = fmaxf(m, mxr * sc);
;     mx = fmaxf(mx, shx(mx, 32));
;     if (!MASKED) mx = lanevalid ? mx : m;
;     alpha = fexp2(m - mx);
;     m = mx;
;   }
;   const float moff = (!MASKED && !lanevalid) ? 1.0e30f : m;
;   float ps = 0.f;
; #pragma unroll
;   for (int sub = 0; sub < 2; ++sub)
; #pragma unroll
;     for (int q = 0; q < 16; ++q) {
;       float pv = fexp2(__builtin_fmaf(s[sub][q], sc, -moff));
;       if (MASKED && MODE != 0) pv = (s[sub][q] > -1.0e38f) ? pv : 0.f;
;       if (MODE == 2) pv *= invl;
;       s[sub][q] = pv;
;       ps += pv;
;     }
;   if (MODE != 2) {
;     ps += shx(ps, 32);
;     l = l * alpha + ps;
;   }
;   if (MODE == 1) return;
;   if (MODE == 0) {
; #pragma unroll
;     for (int q = 0; q < 16; ++q) { o0[q] *= alpha; o1[q] *= alpha; }
	v_cmp_le_u32_e32 vcc, v100, v136
	v_cmp_gt_i32_e64 s[0:1], v100, v146
	s_and_b64 vcc, vcc, s[0:1]
	v_add_u32_e32 v100, 49, v0
	v_cndmask_b32_e32 v10, v166, v10, vcc
	v_cmp_le_u32_e32 vcc, v100, v136
	v_cmp_gt_i32_e64 s[0:1], v100, v146
	s_and_b64 vcc, vcc, s[0:1]
	v_cndmask_b32_e32 v101, v166, v11, vcc
	v_add_u32_e32 v11, 50, v0
	v_cmp_le_u32_e32 vcc, v11, v136
	v_cmp_gt_i32_e64 s[0:1], v11, v146
	s_and_b64 vcc, vcc, s[0:1]
	v_add_u32_e32 v11, 51, v0
	v_cndmask_b32_e32 v150, v166, v12, vcc
	v_cmp_le_u32_e32 vcc, v11, v136
	v_cmp_gt_i32_e64 s[0:1], v11, v146
	s_and_b64 vcc, vcc, s[0:1]
	v_add_u32_e32 v11, 52, v0
	v_cndmask_b32_e32 v151, v166, v13, vcc
	v_cmp_le_u32_e32 vcc, v11, v136
	v_cmp_gt_i32_e64 s[0:1], v11, v146
	s_and_b64 vcc, vcc, s[0:1]
	v_add_u32_e32 v11, 53, v0
	v_cndmask_b32_e32 v174, v166, v14, vcc
	v_cmp_le_u32_e32 vcc, v11, v136
	v_cmp_gt_i32_e64 s[0:1], v11, v146
	s_and_b64 vcc, vcc, s[0:1]
	v_add_u32_e32 v0, 54, v0
	v_cndmask_b32_e32 v178, v166, v15, vcc
	v_cmp_le_u32_e32 vcc, v0, v136
	v_cmp_gt_i32_e64 s[0:1], v0, v146
	s_and_b64 vcc, vcc, s[0:1]
	v_or_b32_e32 v0, 55, v99
	v_cndmask_b32_e32 v183, v166, v16, vcc
	v_cmp_le_u32_e32 vcc, v0, v136
	v_cmp_gt_i32_e64 s[0:1], v0, v146
	v_max3_f32 v0, v18, s8, v19
	v_max3_f32 v0, v0, v20, v21
	v_max3_f32 v0, v0, v22, v23
	v_max3_f32 v0, v0, v24, v25
	v_max3_f32 v0, v0, v26, v27
	v_max3_f32 v0, v0, v28, v29
	v_max3_f32 v0, v0, v30, v31
	v_max3_f32 v0, v0, v32, v33
	v_max3_f32 v0, v0, v2, v3
	v_max3_f32 v0, v0, v4, v5
	v_max3_f32 v0, v0, v6, v7
	v_max3_f32 v0, v0, v8, v9
	v_max3_f32 v0, v0, v10, v101
	s_and_b64 vcc, vcc, s[0:1]
	v_max3_f32 v0, v0, v150, v151
	v_cndmask_b32_e32 v99, v166, v17, vcc
	v_max3_f32 v0, v0, v174, v178
	v_max3_f32 v0, v0, v183, v99
	v_mul_f32_e32 v0, 0x3e38aa3b, v0
	v_max_f32_e32 v0, v149, v0
	ds_bpermute_b32 v11, v173, v0
	s_mov_b64 s[0:1], 0
	s_waitcnt lgkmcnt(0)
	v_max_f32_e32 v11, v11, v11
	v_max_f32_e32 v0, v0, v11
	v_fma_f32 v11, v18, s33, -v0
	v_exp_f32_e32 v18, v11
	v_fma_f32 v11, v19, s33, -v0
	v_exp_f32_e32 v19, v11
	v_fma_f32 v11, v20, s33, -v0
	v_exp_f32_e32 v20, v11
	v_fma_f32 v13, v21, s33, -v0
	v_exp_f32_e32 v21, v13
	v_fma_f32 v13, v22, s33, -v0
	v_add_f32_e32 v12, 0, v18
	v_exp_f32_e32 v22, v13
	v_fma_f32 v13, v23, s33, -v0
	v_add_f32_e32 v12, v19, v12
	v_exp_f32_e32 v23, v13
	v_fma_f32 v13, v24, s33, -v0
	v_add_f32_e32 v12, v20, v12
	v_exp_f32_e32 v24, v13
	v_fma_f32 v13, v25, s33, -v0
	v_add_f32_e32 v12, v21, v12
	v_exp_f32_e32 v25, v13
	v_pk_fma_f32 v[224:225], v[26:27], s[32:33], v[0:1] op_sel:[0,1,0] op_sel_hi:[1,1,0] neg_lo:[0,0,1] neg_hi:[0,0,1]
	v_add_f32_e32 v12, v22, v12
	v_exp_f32_e32 v188, v224
	v_add_f32_e32 v12, v23, v12
	v_exp_f32_e32 v189, v225
	v_pk_fma_f32 v[224:225], v[28:29], s[32:33], v[0:1] op_sel:[0,1,0] op_sel_hi:[1,1,0] neg_lo:[0,0,1] neg_hi:[0,0,1]
	v_add_f32_e32 v12, v24, v12
	v_exp_f32_e32 v190, v224
	v_add_f32_e32 v12, v25, v12
	v_exp_f32_e32 v191, v225
	v_pk_fma_f32 v[224:225], v[30:31], s[32:33], v[0:1] op_sel:[0,1,0] op_sel_hi:[1,1,0] neg_lo:[0,0,1] neg_hi:[0,0,1]
	v_add_f32_e32 v12, v188, v12
	v_exp_f32_e32 v194, v224
	v_add_f32_e32 v12, v189, v12
	v_exp_f32_e32 v195, v225
	v_pk_fma_f32 v[224:225], v[32:33], s[32:33], v[0:1] op_sel:[0,1,0] op_sel_hi:[1,1,0] neg_lo:[0,0,1] neg_hi:[0,0,1]
	v_add_f32_e32 v12, v190, v12
	v_exp_f32_e32 v196, v224
	v_add_f32_e32 v12, v191, v12
	v_exp_f32_e32 v197, v225
	v_pk_fma_f32 v[222:223], v[2:3], s[32:33], v[0:1] op_sel:[0,1,0] op_sel_hi:[1,1,0] neg_lo:[0,0,1] neg_hi:[0,0,1]
	v_add_f32_e32 v12, v194, v12
	v_exp_f32_e32 v198, v222
	v_add_f32_e32 v12, v195, v12
	v_exp_f32_e32 v199, v223
	v_pk_fma_f32 v[222:223], v[4:5], s[32:33], v[0:1] op_sel:[0,1,0] op_sel_hi:[1,1,0] neg_lo:[0,0,1] neg_hi:[0,0,1]
	v_add_f32_e32 v12, v196, v12
	v_exp_f32_e32 v200, v222
	v_add_f32_e32 v2, v197, v12
	v_exp_f32_e32 v201, v223
	v_pk_fma_f32 v[222:223], v[6:7], s[32:33], v[0:1] op_sel:[0,1,0] op_sel_hi:[1,1,0] neg_lo:[0,0,1] neg_hi:[0,0,1]
	v_add_f32_e32 v2, v198, v2
	v_exp_f32_e32 v202, v222
	v_add_f32_e32 v2, v199, v2
	v_exp_f32_e32 v203, v223
	v_pk_fma_f32 v[222:223], v[8:9], s[32:33], v[0:1] op_sel:[0,1,0] op_sel_hi:[1,1,0] neg_lo:[0,0,1] neg_hi:[0,0,1]
	v_add_f32_e32 v2, v200, v2
	v_exp_f32_e32 v204, v222
	v_sub_f32_e32 v11, v148, v0
	v_add_f32_e32 v2, v201, v2
	v_add_f32_e32 v2, v202, v2
	v_exp_f32_e32 v100, v11
	v_add_f32_e32 v2, v203, v2
	v_add_f32_e32 v205, v204, v2
	v_exp_f32_e32 v206, v223
	v_fma_f32 v2, v10, s33, -v0
	v_exp_f32_e32 v207, v2
	v_pk_mul_f32 v[16:17], v[144:145], v[100:101] op_sel_hi:[1,0]
	v_pk_mul_f32 v[14:15], v[140:141], v[100:101] op_sel_hi:[1,0]
	v_pk_mul_f32 v[12:13], v[132:133], v[100:101] op_sel_hi:[1,0]
	v_pk_mul_f32 v[10:11], v[130:131], v[100:101] op_sel_hi:[1,0]
	v_pk_mul_f32 v[8:9], v[128:129], v[100:101] op_sel_hi:[1,0]
	v_pk_mul_f32 v[6:7], v[126:127], v[100:101] op_sel_hi:[1,0]
	v_pk_mul_f32 v[4:5], v[124:125], v[100:101] op_sel_hi:[1,0]
	v_pk_mul_f32 v[2:3], v[122:123], v[100:101] op_sel_hi:[1,0]
	v_pk_mul_f32 v[32:33], v[142:143], v[100:101] op_sel_hi:[1,0]
	v_cvt_pk_bf16_f32 v184, v18, v19
	v_cvt_pk_bf16_f32 v185, v20, v21
	v_cvt_pk_bf16_f32 v186, v22, v23
	v_cvt_pk_bf16_f32 v187, v24, v25
	v_pk_mul_f32 v[30:31], v[120:121], v[100:101] op_sel_hi:[1,0]
	v_pk_mul_f32 v[28:29], v[118:119], v[100:101] op_sel_hi:[1,0]
	v_pk_mul_f32 v[26:27], v[116:117], v[100:101] op_sel_hi:[1,0]
	v_pk_mul_f32 v[24:25], v[114:115], v[100:101] op_sel_hi:[1,0]
	v_pk_mul_f32 v[22:23], v[112:113], v[100:101] op_sel_hi:[1,0]
	v_pk_mul_f32 v[20:21], v[110:111], v[100:101] op_sel_hi:[1,0]
	v_pk_mul_f32 v[18:19], v[108:109], v[100:101] op_sel_hi:[1,0]
; template <int DQK, bool MASKED, int MODE, class MF>
; DI void attn_step(const bf16_t* sK, const bf16_t* sVt, const bf16x8 (&qf)[DQK / 16], f32x16& o0, f32x16& o1, float& m, float& l,
;                   float sc, const MF& mf, int lane, f32x16 (&s)[2], float invl, bool lanevalid = true) {
;     ...
;   bf16x8 kf[2][DQK / 16];
; #pragma unroll
;   for (int sub = 0; sub < 2; ++sub)
; #pragma unroll
;     for (int ks = 0; ks < DQK / 16; ++ks) kf[sub][ks] = *(const bf16x8*)(sK + (sub * 32 + pr) * KST + ks * 16 + 8 * h);
;   __builtin_amdgcn_sched_barrier(0);
; #pragma unroll
;   for (int q = 0; q < 16; ++q) { s[0][q] = 0.f; s[1][q] = 0.f; }
; #pragma unroll
;   for (int ks = 0; ks < DQK / 16; ++ks) {
;     s[0] = MFMA(kf[0][ks], qf[ks], s[0]);
;     s[1] = MFMA(kf[1][ks], qf[ks], s[1]);
;   }
;   bf16x8 vf[2][2][2];
;   if (MODE != 1) {
; #pragma unroll
;     for (int sub = 0; sub < 2; ++sub)
; #pragma unroll
;       for (int s2 = 0; s2 < 2; ++s2) {
;         vf[sub][s2][0] = *(const bf16x8*)(sVt + r * 72 + sub * 32 + s2 * 16 + 8 * h);
;         vf[sub][s2][1] = *(const bf16x8*)(sVt + (32 + r) * 72 + sub * 32 + s2 * 16 + 8 * h);
;       }
;     __builtin_amdgcn_sched_barrier(0);
;   }
;   float mxr = -3.0e38f;
; #pragma unroll
;   for (int sub = 0; sub < 2; ++sub)
; #pragma unroll
;     for (int q = 0; q < 16; ++q) {
;       if (MASKED) { const int kk = sub * 32 + 16 * (q >> 3) + 8 * h + (q & 7); s[sub][q] = mf(kk) ? s[sub][q] : -3.0e38f; }
;       if (MODE != 2) mxr = fmaxf(mxr, s[sub][q]);
;     }
;   float alpha = 1.f;
;   if (MODE != 2) {
;     float mx = fmaxf(m, mxr * sc);
;     mx = fmaxf(mx, shx(mx, 32));
;     ...
;       float pv = fexp2(__builtin_fmaf(s[sub][q], sc, -moff));
;       if (MASKED && MODE != 0) pv = (s[sub][q] > -1.0e38f) ? pv : 0.f;
;       if (MODE == 2) pv *= invl;
;       s[sub][q] = pv;
;       ps += pv;
;     }
;   if (MODE != 2) {
;     ps += shx(ps, 32);
;     l = l * alpha + ps;
;   }
;   if (MODE == 1) return;
;   if (MODE == 0) {
; #pragma unroll
;     for (int q = 0; q < 16; ++q) { o0[q] *= alpha; o1[q] *= alpha; }
;   }
; #pragma unroll
;   for (int sub = 0; sub < 2; ++sub)
; #pragma unroll
;     for (int s2 = 0; s2 < 2; ++s2) {
;       union { bf16x8 v; unsigned u[4]; } pb;
; #pragma unroll
;       for (int e = 0; e < 4; ++e) pb.u[e] = pack2(s[sub][8 * s2 + 2 * e], s[sub][8 * s2 + 2 * e + 1]);
;       o0 = MFMA(vf[sub][s2][0], pb.v, o0);
	v_mfma_f32_32x32x16_bf16 v[2:17], v[94:97], v[184:187], v[2:17]
	v_fma_f32 v95, v101, s33, -v0
	v_mfma_f32_32x32x16_bf16 v[18:33], v[90:93], v[184:187], v[18:33]
	v_add_f32_e32 v90, v206, v205
	v_add_f32_e32 v94, v207, v90
	v_cvt_pk_bf16_f32 v90, v188, v189
	v_cvt_pk_bf16_f32 v91, v190, v191
	v_cvt_pk_bf16_f32 v92, v194, v195
	v_cvt_pk_bf16_f32 v93, v196, v197
	s_nop 1
	v_mfma_f32_32x32x16_bf16 v[2:17], v[70:73], v[90:93], v[2:17]
	v_exp_f32_e32 v70, v95
	v_pk_fma_f32 v[222:223], v[150:151], s[32:33], v[0:1] op_sel:[0,1,0] op_sel_hi:[1,1,0] neg_lo:[0,0,1] neg_hi:[0,0,1]
	v_exp_f32_e32 v71, v222
	v_exp_f32_e32 v72, v223
	v_add_f32_e32 v73, v70, v94
	v_add_f32_e32 v73, v71, v73
	v_mfma_f32_32x32x16_bf16 v[18:33], v[66:69], v[90:93], v[18:33]
	v_fma_f32 v66, v174, s33, -v0
	v_exp_f32_e32 v90, v66
	v_cvt_pk_bf16_f32 v66, v198, v199
	v_cvt_pk_bf16_f32 v67, v200, v201
	v_cvt_pk_bf16_f32 v68, v202, v203
	v_cvt_pk_bf16_f32 v69, v204, v206
	v_add_f32_e32 v73, v72, v73
	s_nop 0
	v_mfma_f32_32x32x16_bf16 v[2:17], v[62:65], v[66:69], v[2:17]
	v_fma_f32 v63, v178, s33, -v0
	v_exp_f32_e32 v63, v63
	v_fma_f32 v64, v183, s33, -v0
	v_exp_f32_e32 v64, v64
	v_fma_f32 v65, v99, s33, -v0
	v_exp_f32_e32 v65, v65
	v_add_f32_e32 v62, v90, v73
	v_mfma_f32_32x32x16_bf16 v[18:33], v[58:61], v[66:69], v[18:33]
	v_add_f32_e32 v58, v63, v62
	v_add_f32_e32 v58, v64, v58
	v_add_f32_e32 v62, v65, v58
	v_cvt_pk_bf16_f32 v58, v207, v70
	v_cvt_pk_bf16_f32 v59, v71, v72
	v_cvt_pk_bf16_f32 v60, v90, v63
	v_cvt_pk_bf16_f32 v61, v64, v65
	s_nop 1
	v_mfma_f32_32x32x16_bf16 v[2:17], v[38:41], v[58:61], v[2:17]
	ds_bpermute_b32 v38, v173, v62
	s_waitcnt lgkmcnt(0)
	v_add_f32_e32 v40, v62, v38
	v_fmac_f32_e32 v40, v147, v100
	v_mfma_f32_32x32x16_bf16 v[18:33], v[34:37], v[58:61], v[18:33]
.LBB0_1367:
	s_andn2_b64 vcc, exec, s[0:1]
	s_cbranch_vccnz .LBB0_1369
	v_lshl_add_u32 v0, s5, 1, v182
	s_nop 3
	ds_read_b128 v[2:5], v0
	s_nop 3
	ds_read_b128 v[18:21], v0 offset:32
	ds_read_b128 v[22:25], v0 offset:64
	ds_read_b128 v[58:61], v0 offset:96
	ds_read_b128 v[26:29], v0 offset:4608
	ds_read_b128 v[62:65], v0 offset:4640
	ds_read_b128 v[66:69], v0 offset:4672
	ds_read_b128 v[184:187], v0 offset:4704
	s_waitcnt lgkmcnt(7)
	v_mfma_f32_32x32x16_bf16 v[2:17], v[2:5], v[74:77], 0
	v_add3_u32 v0, v98, v175, v138
	s_waitcnt lgkmcnt(3)
	v_mfma_f32_32x32x16_bf16 v[26:41], v[26:29], v[74:77], 0
	v_mfma_f32_32x32x16_bf16 v[2:17], v[18:21], v[78:81], v[2:17]
	s_waitcnt lgkmcnt(2)
	v_mfma_f32_32x32x16_bf16 v[26:41], v[62:65], v[78:81], v[26:41]
	v_mfma_f32_32x32x16_bf16 v[2:17], v[22:25], v[82:85], v[2:17]
	v_add3_u32 v22, v98, v177, v138
	s_waitcnt lgkmcnt(1)
	v_mfma_f32_32x32x16_bf16 v[26:41], v[66:69], v[82:85], v[26:41]
	v_mfma_f32_32x32x16_bf16 v[2:17], v[58:61], v[86:89], v[2:17]
	ds_read_b128 v[18:21], v0 offset:9216
	ds_read_b128 v[94:97], v0 offset:9248
	ds_read_b128 v[98:101], v22 offset:9216
	ds_read_b128 v[90:93], v22 offset:9248
	ds_read_b128 v[70:73], v0 offset:9280
	ds_read_b128 v[62:65], v0 offset:9312
	ds_read_b128 v[66:69], v22 offset:9280
	ds_read_b128 v[58:61], v22 offset:9312
	s_waitcnt lgkmcnt(8)
	v_mfma_f32_32x32x16_bf16 v[26:41], v[184:187], v[86:89], v[26:41]
	s_nop 1
	v_max3_f32 v0, v2, s8, v3
	v_max3_f32 v0, v0, v4, v5
	v_max3_f32 v0, v0, v6, v7
	v_max3_f32 v0, v0, v8, v9
	v_max3_f32 v0, v0, v10, v11
	v_max3_f32 v0, v0, v12, v13
	v_max3_f32 v0, v0, v14, v15
	v_max3_f32 v0, v0, v16, v17
	s_nop 1
	v_max3_f32 v0, v0, v26, v27
	v_max3_f32 v0, v0, v28, v29
	v_max3_f32 v0, v0, v30, v31
	v_max3_f32 v0, v0, v32, v33
	v_max3_f32 v0, v0, v34, v35
	v_max3_f32 v0, v0, v36, v37
	v_max3_f32 v0, v0, v38, v39
	v_max3_f32 v0, v0, v40, v41
	v_mul_f32_e32 v0, 0x3e38aa3b, v0
	v_max_f32_e32 v0, v149, v0
	ds_bpermute_b32 v22, v173, v0
	s_waitcnt lgkmcnt(0)
; #define MFMA(a, b, c) __builtin_amdgcn_mfma_f32_32x32x16_bf16((a), (b), (c), 0, 0, 0)
; DI unsigned pack2(float a, float b) { f32x2_t v = {a, b}; bf16x2_t r = __builtin_convertvector(v, bf16x2_t); return __builtin_bit_cast(unsigned, r); }
; DI float fexp2(float x) { return __builtin_amdgcn_exp2f(x); }
; DI float shx(float v, int m) { return __shfl_xor(v, m, 64); }
; template <int DQK, bool MASKED, int MODE, class MF>
; DI void attn_step(const bf16_t* sK, const bf16_t* sVt, const bf16x8 (&qf)[DQK / 16], f32x16& o0, f32x16& o1, float& m, float& l,
;                   float sc, const MF& mf, int lane, f32x16 (&s)[2], float invl, bool lanevalid = true) {
;     ...
;   float alpha = 1.f;
;   if (MODE != 2) {
;     float mx = fmaxf(m, mxr * sc);
;     mx = fmaxf(mx, shx(mx, 32));
;     if (!MASKED) mx = lanevalid ? mx : m;
;     alpha = fexp2(m - mx);
;     m = mx;
;   }
;   const float moff = (!MASKED && !lanevalid) ? 1.0e30f : m;
;   float ps = 0.f;
; #pragma unroll
;   for (int sub = 0; sub < 2; ++sub)
; #pragma unroll
;     for (int q = 0; q < 16; ++q) {
;       float pv = fexp2(__builtin_fmaf(s[sub][q], sc, -moff));
;       if (MASKED && MODE != 0) pv = (s[sub][q] > -1.0e38f) ? pv : 0.f;
;       if (MODE == 2) pv *= invl;
;       s[sub][q] = pv;
;       ps += pv;
;     }
;   if (MODE != 2) {
;     ps += shx(ps, 32);
;     l = l * alpha + ps;
;   }
;   if (MODE == 1) return;
;   if (MODE == 0) {
; #pragma unroll
;     for (int q = 0; q < 16; ++q) { o0[q] *= alpha; o1[q] *= alpha; }
;   }
; #pragma unroll
;   for (int sub = 0; sub < 2; ++sub)
; #pragma unroll
;     for (int s2 = 0; s2 < 2; ++s2) {
;       union { bf16x8 v; unsigned u[4]; } pb;
; #pragma unroll
;       for (int e = 0; e < 4; ++e) pb.u[e] = pack2(s[sub][8 * s2 + 2 * e], s[sub][8 * s2 + 2 * e + 1]);
;       o0 = MFMA(vf[sub][s2][0], pb.v, o0);
;       o1 = MFMA(vf[sub][s2][1], pb.v, o1);
;     }
	v_max_f32_e32 v22, v22, v22
	v_max_f32_e32 v0, v0, v22
	v_pk_fma_f32 v[222:223], v[2:3], s[32:33], v[0:1] op_sel:[0,1,0] op_sel_hi:[1,1,0] neg_lo:[0,0,1] neg_hi:[0,0,1]
	v_exp_f32_e32 v23, v222
	v_pk_fma_f32 v[224:225], v[4:5], s[32:33], v[0:1] op_sel:[0,1,0] op_sel_hi:[1,1,0] neg_lo:[0,0,1] neg_hi:[0,0,1]
	v_exp_f32_e32 v24, v223
	v_exp_f32_e32 v25, v224
	v_exp_f32_e32 v149, v225
	v_pk_fma_f32 v[222:223], v[6:7], s[32:33], v[0:1] op_sel:[0,1,0] op_sel_hi:[1,1,0] neg_lo:[0,0,1] neg_hi:[0,0,1]
	v_add_f32_e32 v2, 0, v23
	v_exp_f32_e32 v150, v222
	v_add_f32_e32 v2, v24, v2
	v_exp_f32_e32 v151, v223
	v_pk_fma_f32 v[222:223], v[8:9], s[32:33], v[0:1] op_sel:[0,1,0] op_sel_hi:[1,1,0] neg_lo:[0,0,1] neg_hi:[0,0,1]
	v_add_f32_e32 v2, v25, v2
	v_exp_f32_e32 v174, v222
	v_add_f32_e32 v2, v149, v2
	v_exp_f32_e32 v178, v223
	v_pk_fma_f32 v[222:223], v[10:11], s[32:33], v[0:1] op_sel:[0,1,0] op_sel_hi:[1,1,0] neg_lo:[0,0,1] neg_hi:[0,0,1]
	v_add_f32_e32 v2, v150, v2
	v_exp_f32_e32 v183, v222
	v_add_f32_e32 v2, v151, v2
	v_exp_f32_e32 v184, v223
	v_pk_fma_f32 v[222:223], v[12:13], s[32:33], v[0:1] op_sel:[0,1,0] op_sel_hi:[1,1,0] neg_lo:[0,0,1] neg_hi:[0,0,1]
	v_add_f32_e32 v2, v174, v2
	v_exp_f32_e32 v185, v222
	v_add_f32_e32 v2, v178, v2
	v_exp_f32_e32 v186, v223
	v_pk_fma_f32 v[222:223], v[14:15], s[32:33], v[0:1] op_sel:[0,1,0] op_sel_hi:[1,1,0] neg_lo:[0,0,1] neg_hi:[0,0,1]
	v_add_f32_e32 v2, v183, v2
	v_exp_f32_e32 v187, v222
	v_add_f32_e32 v2, v184, v2
	v_exp_f32_e32 v188, v223
	v_pk_fma_f32 v[222:223], v[16:17], s[32:33], v[0:1] op_sel:[0,1,0] op_sel_hi:[1,1,0] neg_lo:[0,0,1] neg_hi:[0,0,1]
	v_add_f32_e32 v2, v185, v2
	v_exp_f32_e32 v189, v222
	v_add_f32_e32 v2, v186, v2
	v_exp_f32_e32 v190, v223
	v_pk_fma_f32 v[222:223], v[26:27], s[32:33], v[0:1] op_sel:[0,1,0] op_sel_hi:[1,1,0] neg_lo:[0,0,1] neg_hi:[0,0,1]
	v_add_f32_e32 v2, v187, v2
	v_exp_f32_e32 v191, v222
	v_add_f32_e32 v2, v188, v2
	v_exp_f32_e32 v194, v223
	v_pk_fma_f32 v[222:223], v[28:29], s[32:33], v[0:1] op_sel:[0,1,0] op_sel_hi:[1,1,0] neg_lo:[0,0,1] neg_hi:[0,0,1]
	v_add_f32_e32 v2, v189, v2
	v_exp_f32_e32 v195, v222
	v_add_f32_e32 v2, v190, v2
	v_exp_f32_e32 v196, v223
	v_pk_fma_f32 v[222:223], v[30:31], s[32:33], v[0:1] op_sel:[0,1,0] op_sel_hi:[1,1,0] neg_lo:[0,0,1] neg_hi:[0,0,1]
	v_add_f32_e32 v2, v191, v2
	v_exp_f32_e32 v197, v222
	v_add_f32_e32 v2, v194, v2
	v_exp_f32_e32 v198, v223
	v_pk_fma_f32 v[222:223], v[32:33], s[32:33], v[0:1] op_sel:[0,1,0] op_sel_hi:[1,1,0] neg_lo:[0,0,1] neg_hi:[0,0,1]
	v_add_f32_e32 v2, v195, v2
	v_exp_f32_e32 v199, v222
	v_sub_f32_e32 v22, v148, v0
	v_add_f32_e32 v2, v196, v2
	v_add_f32_e32 v2, v197, v2
	v_exp_f32_e32 v148, v22
	v_add_f32_e32 v2, v198, v2
	v_add_f32_e32 v200, v199, v2
	v_exp_f32_e32 v201, v223
	v_pk_fma_f32 v[222:223], v[34:35], s[32:33], v[0:1] op_sel:[0,1,0] op_sel_hi:[1,1,0] neg_lo:[0,0,1] neg_hi:[0,0,1]
	v_exp_f32_e32 v202, v222
	v_pk_mul_f32 v[16:17], v[144:145], v[148:149] op_sel_hi:[1,0]
	v_pk_mul_f32 v[14:15], v[140:141], v[148:149] op_sel_hi:[1,0]
	v_pk_mul_f32 v[12:13], v[132:133], v[148:149] op_sel_hi:[1,0]
	v_pk_mul_f32 v[10:11], v[130:131], v[148:149] op_sel_hi:[1,0]
	v_pk_mul_f32 v[8:9], v[128:129], v[148:149] op_sel_hi:[1,0]
	v_pk_mul_f32 v[6:7], v[126:127], v[148:149] op_sel_hi:[1,0]
	v_pk_mul_f32 v[4:5], v[124:125], v[148:149] op_sel_hi:[1,0]
	v_pk_mul_f32 v[2:3], v[122:123], v[148:149] op_sel_hi:[1,0]
	v_cvt_pk_bf16_f32 v122, v23, v24
	v_cvt_pk_bf16_f32 v123, v25, v149
	v_cvt_pk_bf16_f32 v124, v150, v151
	v_cvt_pk_bf16_f32 v125, v174, v178
	v_pk_mul_f32 v[32:33], v[142:143], v[148:149] op_sel_hi:[1,0]
	v_pk_mul_f32 v[30:31], v[120:121], v[148:149] op_sel_hi:[1,0]
	v_mfma_f32_32x32x16_bf16 v[2:17], v[18:21], v[122:125], v[2:17]
	v_mul_f32_e64 v28, v118, v148
	v_mul_f32_e64 v29, v119, v148
	v_mul_f32_e64 v26, v116, v148
	v_mul_f32_e64 v27, v117, v148
	v_mul_f32_e64 v24, v114, v148
	v_mul_f32_e64 v25, v115, v148
	v_pk_mul_f32 v[22:23], v[112:113], v[148:149] op_sel_hi:[1,0]
	v_pk_mul_f32 v[20:21], v[110:111], v[148:149] op_sel_hi:[1,0]
	v_pk_mul_f32 v[18:19], v[108:109], v[148:149] op_sel_hi:[1,0]
	v_add_f32_e32 v34, v201, v200
	s_nop 0
	v_mfma_f32_32x32x16_bf16 v[18:33], v[98:101], v[122:125], v[18:33]
	v_cvt_pk_bf16_f32 v98, v183, v184
	v_cvt_pk_bf16_f32 v99, v185, v186
	v_cvt_pk_bf16_f32 v100, v187, v188
	v_cvt_pk_bf16_f32 v101, v189, v190
	v_add_f32_e32 v34, v202, v34
	v_fma_f32 v39, v39, s33, -v0
	v_exp_f32_e32 v39, v39
	v_mfma_f32_32x32x16_bf16 v[2:17], v[94:97], v[98:101], v[2:17]
	v_exp_f32_e32 v94, v223
	v_pk_fma_f32 v[222:223], v[36:37], s[32:33], v[0:1] op_sel:[0,1,0] op_sel_hi:[1,1,0] neg_lo:[0,0,1] neg_hi:[0,0,1]
	v_exp_f32_e32 v95, v222
	v_exp_f32_e32 v96, v223
	v_add_f32_e32 v34, v94, v34
	v_add_f32_e32 v34, v95, v34
	v_mfma_f32_32x32x16_bf16 v[18:33], v[90:93], v[98:101], v[18:33]
	v_add_f32_e32 v90, v96, v34
	v_fma_f32 v34, v38, s33, -v0
	v_exp_f32_e32 v38, v34
	v_cvt_pk_bf16_f32 v34, v191, v194
	v_cvt_pk_bf16_f32 v35, v195, v196
	v_cvt_pk_bf16_f32 v36, v197, v198
	v_cvt_pk_bf16_f32 v37, v199, v201
	v_fma_f32 v40, v40, s33, -v0
	v_exp_f32_e32 v40, v40
	v_mfma_f32_32x32x16_bf16 v[2:17], v[70:73], v[34:37], v[2:17]
	v_fma_f32 v41, v41, s33, -v0
	v_exp_f32_e32 v41, v41
	v_add_f32_e32 v70, v38, v90
	v_mfma_f32_32x32x16_bf16 v[18:33], v[66:69], v[34:37], v[18:33]
	v_add_f32_e32 v34, v39, v70
	v_add_f32_e32 v34, v40, v34
	v_add_f32_e32 v66, v41, v34
	v_cvt_pk_bf16_f32 v34, v202, v94
	v_cvt_pk_bf16_f32 v35, v95, v96
	v_cvt_pk_bf16_f32 v36, v38, v39
	v_cvt_pk_bf16_f32 v37, v40, v41
	ds_bpermute_b32 v38, v173, v66
	s_waitcnt lgkmcnt(0)
	v_add_f32_e32 v40, v66, v38
	v_mfma_f32_32x32x16_bf16 v[2:17], v[62:65], v[34:37], v[2:17]
	v_fmac_f32_e32 v40, v147, v148
	v_mfma_f32_32x32x16_bf16 v[18:33], v[58:61], v[34:37], v[18:33]

; #define MFMA(a, b, c) __builtin_amdgcn_mfma_f32_32x32x16_bf16((a), (b), (c), 0, 0, 0)
; template <int DQK, bool MASKED, int MODE, class MF>
; DI void attn_step(const bf16_t* sK, const bf16_t* sVt, const bf16x8 (&qf)[DQK / 16], f32x16& o0, f32x16& o1, float& m, float& l,
;                   float sc, const MF& mf, int lane, f32x16 (&s)[2], float invl, bool lanevalid = true) {
;     ...
;   bf16x8 kf[2][DQK / 16];
; #pragma unroll
;   for (int sub = 0; sub < 2; ++sub)
; #pragma unroll
;     for (int ks = 0; ks < DQK / 16; ++ks) kf[sub][ks] = *(const bf16x8*)(sK + (sub * 32 + pr) * KST + ks * 16 + 8 * h);
;   __builtin_amdgcn_sched_barrier(0);
; #pragma unroll
;   for (int q = 0; q < 16; ++q) { s[0][q] = 0.f; s[1][q] = 0.f; }
; #pragma unroll
;   for (int ks = 0; ks < DQK / 16; ++ks) {
;     s[0] = MFMA(kf[0][ks], qf[ks], s[0]);
;     s[1] = MFMA(kf[1][ks], qf[ks], s[1]);
;   }
;   bf16x8 vf[2][2][2];
;   if (MODE != 1) {
; #pragma unroll
;     for (int sub = 0; sub < 2; ++sub)
; #pragma unroll
;       for (int s2 = 0; s2 < 2; ++s2) {
;         vf[sub][s2][0] = *(const bf16x8*)(sVt + r * 72 + sub * 32 + s2 * 16 + 8 * h);
;         vf[sub][s2][1] = *(const bf16x8*)(sVt + (32 + r) * 72 + sub * 32 + s2 * 16 + 8 * h);
;       }
;     __builtin_amdgcn_sched_barrier(0);
;   }
;   float mxr = -3.0e38f;
; #pragma unroll
;   for (int sub = 0; sub < 2; ++sub)
; #pragma unroll
;     for (int q = 0; q < 16; ++q) {
;       if (MASKED) { const int kk = sub * 32 + 16 * (q >> 3) + 8 * h + (q & 7); s[sub][q] = mf(kk) ? s[sub][q] : -3.0e38f; }
; DI void phase_attn_swa(const Params& P, const float* sinks, bf16_t* og, unsigned char* smem, int L, int G) {
;     ...
;     for (int j = jlo; j <= jhi; ++j) {
;       const int key0 = j * 64, cb = (j - jlo) & 1;
;       __syncthreads();
;       if (j < jhi) kv64_store(R, sK + (cb ^ 1) * KVB64, sVt + (cb ^ 1) * KVB64, tid);
;       if (j + 1 < jhi) kv64_fetch(R, kb, 256, vb, SEQ, key0 + 128, true, tid);
;       __builtin_amdgcn_sched_barrier(0);
;       auto mf = [&](int kk) { const int key = key0 + kk; return key <= t && key > t - 128; };
;       attn_step<64, true, 0>(sK + cb * KVB64, sVt + cb * KVB64, qf, o0, o1, m, l, sc, mf, lane, s, 0.f);
.LBB0_1672:
	s_mulk_i32 s0, 0x4800
	v_add_u32_e32 v40, s0, v163
	ds_read_b128 v[32:35], v40
	ds_read_b128 v[96:99], v40 offset:32
	ds_read_b128 v[100:103], v40 offset:64
	ds_read_b128 v[104:107], v40 offset:96
	ds_read_b128 v[36:39], v40 offset:4608
	ds_read_b128 v[108:111], v40 offset:4640
	ds_read_b128 v[112:115], v40 offset:4672
	ds_read_b128 v[178:181], v40 offset:4704
	v_add_u32_e32 v116, s0, v137
	s_waitcnt lgkmcnt(7)
	v_mfma_f32_32x32x16_bf16 v[48:63], v[32:35], v[64:67], 0
	s_waitcnt lgkmcnt(3)
	v_mfma_f32_32x32x16_bf16 v[32:47], v[36:39], v[64:67], 0
	v_mfma_f32_32x32x16_bf16 v[48:63], v[96:99], v[68:71], v[48:63]
	v_add3_u32 v96, v116, v164, v171
	v_add3_u32 v97, v116, v165, v171
	s_waitcnt lgkmcnt(2)
	v_mfma_f32_32x32x16_bf16 v[32:47], v[108:111], v[68:71], v[32:47]
	v_mfma_f32_32x32x16_bf16 v[48:63], v[100:103], v[72:75], v[48:63]
	s_waitcnt lgkmcnt(1)
	v_mfma_f32_32x32x16_bf16 v[32:47], v[112:115], v[72:75], v[32:47]
	v_mfma_f32_32x32x16_bf16 v[48:63], v[104:107], v[76:79], v[48:63]
	ds_read_b128 v[124:127], v96 offset:9216
	ds_read_b128 v[116:119], v96 offset:9248
	ds_read_b128 v[120:123], v97 offset:9216
	ds_read_b128 v[112:115], v97 offset:9248
	ds_read_b128 v[108:111], v96 offset:9280
	ds_read_b128 v[100:103], v96 offset:9312
	ds_read_b128 v[104:107], v97 offset:9280
	ds_read_b128 v[96:99], v97 offset:9312
	s_waitcnt lgkmcnt(8)
	v_mfma_f32_32x32x16_bf16 v[32:47], v[178:181], v[76:79], v[32:47]
	v_add_u32_e32 v128, s8, v162
	v_cmp_le_u32_e32 vcc, v128, v150
	v_cmp_gt_i32_e64 s[0:1], v128, v151
	s_and_b64 vcc, vcc, s[0:1]
	v_cndmask_b32_e32 v48, v172, v48, vcc
	v_cmp_lt_u32_e32 vcc, v128, v150
	v_cmp_ge_i32_e64 s[0:1], v128, v151
	s_and_b64 vcc, vcc, s[0:1]
	v_add_u32_e32 v177, 2, v128
	v_cndmask_b32_e32 v49, v172, v49, vcc
	v_cmp_le_u32_e32 vcc, v177, v150
	v_cmp_gt_i32_e64 s[0:1], v177, v151
	s_and_b64 vcc, vcc, s[0:1]
	v_add_u32_e32 v177, 3, v128
	v_cndmask_b32_e32 v50, v172, v50, vcc
	v_cmp_le_u32_e32 vcc, v177, v150
	v_cmp_gt_i32_e64 s[0:1], v177, v151
	s_and_b64 vcc, vcc, s[0:1]
	v_add_u32_e32 v177, 4, v128
	v_cndmask_b32_e32 v51, v172, v51, vcc
	v_cmp_le_u32_e32 vcc, v177, v150
	v_cmp_gt_i32_e64 s[0:1], v177, v151
	s_and_b64 vcc, vcc, s[0:1]
	v_add_u32_e32 v177, 5, v128
	v_cndmask_b32_e32 v52, v172, v52, vcc
	v_cmp_le_u32_e32 vcc, v177, v150
	v_cmp_gt_i32_e64 s[0:1], v177, v151
	s_and_b64 vcc, vcc, s[0:1]
	v_add_u32_e32 v177, 6, v128
	v_cndmask_b32_e32 v53, v172, v53, vcc
	v_cmp_le_u32_e32 vcc, v177, v150
	v_cmp_gt_i32_e64 s[0:1], v177, v151
	v_add_u32_e32 v177, s8, v161
	s_and_b64 vcc, vcc, s[0:1]
	v_or_b32_e32 v178, 7, v177
	v_cndmask_b32_e32 v54, v172, v54, vcc
	v_cmp_le_u32_e32 vcc, v178, v150
	v_cmp_gt_i32_e64 s[0:1], v178, v151
	s_and_b64 vcc, vcc, s[0:1]
	v_add_u32_e32 v178, 16, v128
	v_cndmask_b32_e32 v55, v172, v55, vcc
	v_cmp_le_u32_e32 vcc, v178, v150
	v_cmp_gt_i32_e64 s[0:1], v178, v151
	s_and_b64 vcc, vcc, s[0:1]
	v_add_u32_e32 v178, 17, v128
	v_cndmask_b32_e32 v56, v172, v56, vcc
	v_cmp_le_u32_e32 vcc, v178, v150
	v_cmp_gt_i32_e64 s[0:1], v178, v151
	s_and_b64 vcc, vcc, s[0:1]
	v_add_u32_e32 v178, 18, v128
	v_cndmask_b32_e32 v57, v172, v57, vcc
	v_cmp_le_u32_e32 vcc, v178, v150
	v_cmp_gt_i32_e64 s[0:1], v178, v151
	s_and_b64 vcc, vcc, s[0:1]
	v_add_u32_e32 v178, 19, v128
	v_cndmask_b32_e32 v58, v172, v58, vcc
	v_cmp_le_u32_e32 vcc, v178, v150
	v_cmp_gt_i32_e64 s[0:1], v178, v151
	s_and_b64 vcc, vcc, s[0:1]
	v_add_u32_e32 v178, 20, v128
	v_cndmask_b32_e32 v59, v172, v59, vcc
	v_cmp_le_u32_e32 vcc, v178, v150
	v_cmp_gt_i32_e64 s[0:1], v178, v151
	s_and_b64 vcc, vcc, s[0:1]
	v_add_u32_e32 v178, 21, v128
	v_cndmask_b32_e32 v60, v172, v60, vcc
	v_cmp_le_u32_e32 vcc, v178, v150
	v_cmp_gt_i32_e64 s[0:1], v178, v151
	s_and_b64 vcc, vcc, s[0:1]
	v_add_u32_e32 v178, 22, v128
	v_cndmask_b32_e32 v61, v172, v61, vcc
	v_cmp_le_u32_e32 vcc, v178, v150
	v_cmp_gt_i32_e64 s[0:1], v178, v151
	s_and_b64 vcc, vcc, s[0:1]
	v_or_b32_e32 v178, 23, v177
	v_cndmask_b32_e32 v62, v172, v62, vcc
	v_cmp_le_u32_e32 vcc, v178, v150
	v_cmp_gt_i32_e64 s[0:1], v178, v151
	s_and_b64 vcc, vcc, s[0:1]
	v_add_u32_e32 v178, 32, v128
	v_cndmask_b32_e32 v63, v172, v63, vcc
	v_cmp_le_u32_e32 vcc, v178, v150
	v_cmp_gt_i32_e64 s[0:1], v178, v151
	s_and_b64 vcc, vcc, s[0:1]
	v_cndmask_b32_e32 v178, v172, v32, vcc
	v_add_u32_e32 v32, 33, v128
	v_cmp_le_u32_e32 vcc, v32, v150
	v_cmp_gt_i32_e64 s[0:1], v32, v151
	s_and_b64 vcc, vcc, s[0:1]
	v_add_u32_e32 v32, 34, v128
	v_cndmask_b32_e32 v33, v172, v33, vcc
	v_cmp_le_u32_e32 vcc, v32, v150
	v_cmp_gt_i32_e64 s[0:1], v32, v151
	s_and_b64 vcc, vcc, s[0:1]
	v_add_u32_e32 v32, 35, v128
	v_cndmask_b32_e32 v34, v172, v34, vcc
	v_cmp_le_u32_e32 vcc, v32, v150
	v_cmp_gt_i32_e64 s[0:1], v32, v151
	s_and_b64 vcc, vcc, s[0:1]
	v_add_u32_e32 v32, 36, v128
	v_cndmask_b32_e32 v35, v172, v35, vcc
	v_cmp_le_u32_e32 vcc, v32, v150
	v_cmp_gt_i32_e64 s[0:1], v32, v151
	s_and_b64 vcc, vcc, s[0:1]
	v_add_u32_e32 v32, 37, v128
	v_cndmask_b32_e32 v36, v172, v36, vcc
	v_cmp_le_u32_e32 vcc, v32, v150
	v_cmp_gt_i32_e64 s[0:1], v32, v151
	s_and_b64 vcc, vcc, s[0:1]
	v_add_u32_e32 v32, 38, v128
	v_cndmask_b32_e32 v37, v172, v37, vcc
	v_cmp_le_u32_e32 vcc, v32, v150
	v_cmp_gt_i32_e64 s[0:1], v32, v151
	s_and_b64 vcc, vcc, s[0:1]
	v_or_b32_e32 v32, 39, v177
	v_cndmask_b32_e32 v38, v172, v38, vcc
	v_cmp_le_u32_e32 vcc, v32, v150
	v_cmp_gt_i32_e64 s[0:1], v32, v151
	s_and_b64 vcc, vcc, s[0:1]
	v_add_u32_e32 v32, 48, v128
	v_cndmask_b32_e32 v39, v172, v39, vcc
	v_cmp_le_u32_e32 vcc, v32, v150
	v_cmp_gt_i32_e64 s[0:1], v32, v151
	s_and_b64 vcc, vcc, s[0:1]
	v_add_u32_e32 v32, 49, v128
	v_cndmask_b32_e32 v179, v172, v40, vcc
; #define MFMA(a, b, c) __builtin_amdgcn_mfma_f32_32x32x16_bf16((a), (b), (c), 0, 0, 0)
; DI unsigned pack2(float a, float b) { f32x2_t v = {a, b}; bf16x2_t r = __builtin_convertvector(v, bf16x2_t); return __builtin_bit_cast(unsigned, r); }
; DI float fexp2(float x) { return __builtin_amdgcn_exp2f(x); }
; DI float shx(float v, int m) { return __shfl_xor(v, m, 64); }
; template <int DQK, bool MASKED, int MODE, class MF>
; DI void attn_step(const bf16_t* sK, const bf16_t* sVt, const bf16x8 (&qf)[DQK / 16], f32x16& o0, f32x16& o1, float& m, float& l,
;                   float sc, const MF& mf, int lane, f32x16 (&s)[2], float invl, bool lanevalid = true) {
;     ...
;   float mxr = -3.0e38f;
; #pragma unroll
;   for (int sub = 0; sub < 2; ++sub)
; #pragma unroll
;     for (int q = 0; q < 16; ++q) {
;       if (MASKED) { const int kk = sub * 32 + 16 * (q >> 3) + 8 * h + (q & 7); s[sub][q] = mf(kk) ? s[sub][q] : -3.0e38f; }
;       if (MODE != 2) mxr = fmaxf(mxr, s[sub][q]);
;     }
;   float alpha = 1.f;
;   if (MODE != 2) {
;     float mx = fmaxf(m, mxr * sc);
;     mx = fmaxf(mx, shx(mx, 32));
;     if (!MASKED) mx = lanevalid ? mx : m;
;     alpha = fexp2(m - mx);
;     m = mx;
;   }
;   const float moff = (!MASKED && !lanevalid) ? 1.0e30f : m;
;   float ps = 0.f;
; #pragma unroll
;   for (int sub = 0; sub < 2; ++sub)
; #pragma unroll
;     for (int q = 0; q < 16; ++q) {
;       float pv = fexp2(__builtin_fmaf(s[sub][q], sc, -moff));
;       if (MASKED && MODE != 0) pv = (s[sub][q] > -1.0e38f) ? pv : 0.f;
;       if (MODE == 2) pv *= invl;
;       s[sub][q] = pv;
;       ps += pv;
;     }
;   if (MODE != 2) {
;     ps += shx(ps, 32);
;     l = l * alpha + ps;
;   }
;   if (MODE == 1) return;
;   if (MODE == 0) {
; #pragma unroll
;     for (int q = 0; q < 16; ++q) { o0[q] *= alpha; o1[q] *= alpha; }
;   }
; #pragma unroll
;   for (int sub = 0; sub < 2; ++sub)
; #pragma unroll
;     for (int s2 = 0; s2 < 2; ++s2) {
;       union { bf16x8 v; unsigned u[4]; } pb;
; #pragma unroll
;       for (int e = 0; e < 4; ++e) pb.u[e] = pack2(s[sub][8 * s2 + 2 * e], s[sub][8 * s2 + 2 * e + 1]);
;       o0 = MFMA(vf[sub][s2][0], pb.v, o0);
;       o1 = MFMA(vf[sub][s2][1], pb.v, o1);
;     }
	v_cmp_le_u32_e32 vcc, v32, v150
	v_cmp_gt_i32_e64 s[0:1], v32, v151
	s_and_b64 vcc, vcc, s[0:1]
	v_add_u32_e32 v32, 50, v128
	v_cndmask_b32_e32 v41, v172, v41, vcc
	v_cmp_le_u32_e32 vcc, v32, v150
	v_cmp_gt_i32_e64 s[0:1], v32, v151
	s_and_b64 vcc, vcc, s[0:1]
	v_add_u32_e32 v32, 51, v128
	v_cndmask_b32_e32 v42, v172, v42, vcc
	v_cmp_le_u32_e32 vcc, v32, v150
	v_cmp_gt_i32_e64 s[0:1], v32, v151
	s_and_b64 vcc, vcc, s[0:1]
	v_add_u32_e32 v32, 52, v128
	v_cndmask_b32_e32 v43, v172, v43, vcc
	v_cmp_le_u32_e32 vcc, v32, v150
	v_cmp_gt_i32_e64 s[0:1], v32, v151
	s_and_b64 vcc, vcc, s[0:1]
	v_add_u32_e32 v32, 53, v128
	v_cndmask_b32_e32 v44, v172, v44, vcc
	v_cmp_le_u32_e32 vcc, v32, v150
	v_cmp_gt_i32_e64 s[0:1], v32, v151
	s_and_b64 vcc, vcc, s[0:1]
	v_add_u32_e32 v32, 54, v128
	v_cndmask_b32_e32 v45, v172, v45, vcc
	v_cmp_le_u32_e32 vcc, v32, v150
	v_cmp_gt_i32_e64 s[0:1], v32, v151
	s_and_b64 vcc, vcc, s[0:1]
	v_or_b32_e32 v32, 55, v177
	v_cndmask_b32_e32 v46, v172, v46, vcc
	v_cmp_le_u32_e32 vcc, v32, v150
	v_cmp_gt_i32_e64 s[0:1], v32, v151
	v_max3_f32 v32, v48, s14, v49
	v_max3_f32 v32, v32, v50, v51
	v_max3_f32 v32, v32, v52, v53
	v_max3_f32 v32, v32, v54, v55
	v_max3_f32 v32, v32, v56, v57
	v_max3_f32 v32, v32, v58, v59
	v_max3_f32 v32, v32, v60, v61
	v_max3_f32 v32, v32, v62, v63
	v_max3_f32 v32, v32, v178, v33
	v_max3_f32 v32, v32, v34, v35
	v_max3_f32 v32, v32, v36, v37
	v_max3_f32 v32, v32, v38, v39
	v_max3_f32 v32, v32, v179, v41
	s_and_b64 vcc, vcc, s[0:1]
	v_max3_f32 v32, v32, v42, v43
	v_cndmask_b32_e32 v47, v172, v47, vcc
	v_max3_f32 v32, v32, v44, v45
	v_max3_f32 v32, v32, v46, v47
	v_mul_f32_e32 v32, 0x3e38aa3b, v32
	v_max_f32_e32 v40, v176, v176
	v_max_f32_e32 v32, v40, v32
	ds_bpermute_b32 v40, v174, v32
	s_add_i32 s18, s18, 1
	s_add_i32 s0, s17, s18
	s_add_i32 s8, s8, 64
	s_add_i32 s0, s0, -1
	s_waitcnt lgkmcnt(0)
	v_max_f32_e32 v40, v40, v40
	v_max_f32_e32 v32, v32, v40
	v_fma_f32 v40, v48, s15, -v32
	v_exp_f32_e32 v48, v40
	v_fma_f32 v49, v49, s15, -v32
	v_exp_f32_e32 v49, v49
	v_fma_f32 v50, v50, s15, -v32
	v_exp_f32_e32 v50, v50
	v_fma_f32 v51, v51, s15, -v32
	v_exp_f32_e32 v51, v51
	v_fma_f32 v52, v52, s15, -v32
	v_add_f32_e32 v128, 0, v48
	v_exp_f32_e32 v52, v52
	v_fma_f32 v53, v53, s15, -v32
	v_add_f32_e32 v128, v49, v128
	v_exp_f32_e32 v53, v53
	v_fma_f32 v54, v54, s15, -v32
	v_add_f32_e32 v128, v50, v128
	v_exp_f32_e32 v54, v54
	v_fma_f32 v55, v55, s15, -v32
	v_add_f32_e32 v128, v51, v128
	v_exp_f32_e32 v55, v55
	v_fma_f32 v56, v56, s15, -v32
	v_add_f32_e32 v128, v52, v128
	v_exp_f32_e32 v56, v56
	v_fma_f32 v57, v57, s15, -v32
	v_add_f32_e32 v128, v53, v128
	v_exp_f32_e32 v57, v57
	v_fma_f32 v58, v58, s15, -v32
	v_add_f32_e32 v128, v54, v128
	v_exp_f32_e32 v58, v58
	v_fma_f32 v59, v59, s15, -v32
	v_add_f32_e32 v128, v55, v128
	v_exp_f32_e32 v59, v59
	v_fma_f32 v60, v60, s15, -v32
	v_add_f32_e32 v128, v56, v128
	v_exp_f32_e32 v60, v60
	v_fma_f32 v61, v61, s15, -v32
	v_add_f32_e32 v128, v57, v128
	v_exp_f32_e32 v61, v61
	v_fma_f32 v62, v62, s15, -v32
	v_add_f32_e32 v128, v58, v128
	v_exp_f32_e32 v62, v62
	v_fma_f32 v63, v63, s15, -v32
	v_sub_f32_e32 v40, v176, v32
	v_add_f32_e32 v128, v59, v128
	v_exp_f32_e32 v63, v63
	v_fma_f32 v176, v178, s15, -v32
	v_add_f32_e32 v128, v60, v128
	v_exp_f32_e32 v176, v176
	v_fma_f32 v33, v33, s15, -v32
	v_add_f32_e32 v128, v61, v128
	v_exp_f32_e32 v33, v33
	s_nop 0
	v_pk_fma_f32 v[184:185], v[34:35], s[14:15], v[32:33] op_sel:[0,1,0] op_sel_hi:[1,1,0] neg_lo:[0,0,1] neg_hi:[0,0,1]
	v_add_f32_e32 v128, v62, v128
	v_exp_f32_e32 v177, v184
	v_add_f32_e32 v128, v63, v128
	v_exp_f32_e32 v178, v185
	v_pk_fma_f32 v[184:185], v[36:37], s[14:15], v[32:33] op_sel:[0,1,0] op_sel_hi:[1,1,0] neg_lo:[0,0,1] neg_hi:[0,0,1]
	v_add_f32_e32 v128, v176, v128
	v_exp_f32_e32 v180, v184
	v_add_f32_e32 v34, v33, v128
	v_exp_f32_e32 v128, v185
	v_fma_f32 v35, v38, s15, -v32
	v_add_f32_e32 v34, v177, v34
	v_exp_f32_e32 v38, v35
	v_fma_f32 v35, v39, s15, -v32
	v_add_f32_e32 v34, v178, v34
	v_exp_f32_e32 v39, v35
	v_add_f32_e32 v34, v180, v34
	v_exp_f32_e32 v40, v40
	v_add_f32_e32 v34, v128, v34
	v_add_f32_e32 v34, v38, v34
	v_add_f32_e32 v181, v39, v34
	v_fma_f32 v34, v179, s15, -v32
	v_exp_f32_e32 v179, v34
	v_pk_mul_f32 v[14:15], v[14:15], v[40:41] op_sel_hi:[1,0]
	v_pk_mul_f32 v[12:13], v[12:13], v[40:41] op_sel_hi:[1,0]
	v_pk_mul_f32 v[10:11], v[10:11], v[40:41] op_sel_hi:[1,0]
	v_pk_mul_f32 v[8:9], v[8:9], v[40:41] op_sel_hi:[1,0]
	v_pk_mul_f32 v[6:7], v[6:7], v[40:41] op_sel_hi:[1,0]
	v_pk_mul_f32 v[4:5], v[4:5], v[40:41] op_sel_hi:[1,0]
	v_pk_mul_f32 v[2:3], v[2:3], v[40:41] op_sel_hi:[1,0]
	v_pk_mul_f32 v[0:1], v[0:1], v[40:41] op_sel_hi:[1,0]
	v_pk_mul_f32 v[30:31], v[30:31], v[40:41] op_sel_hi:[1,0]
	v_cvt_pk_bf16_f32 v34, v48, v49
	v_cvt_pk_bf16_f32 v35, v50, v51
	v_cvt_pk_bf16_f32 v36, v52, v53
	v_cvt_pk_bf16_f32 v37, v54, v55
	v_pk_mul_f32 v[28:29], v[28:29], v[40:41] op_sel_hi:[1,0]
	v_pk_mul_f32 v[26:27], v[26:27], v[40:41] op_sel_hi:[1,0]
	v_pk_mul_f32 v[24:25], v[24:25], v[40:41] op_sel_hi:[1,0]
	v_pk_mul_f32 v[22:23], v[22:23], v[40:41] op_sel_hi:[1,0]
	v_pk_mul_f32 v[20:21], v[20:21], v[40:41] op_sel_hi:[1,0]
	v_pk_mul_f32 v[18:19], v[18:19], v[40:41] op_sel_hi:[1,0]
	v_pk_mul_f32 v[16:17], v[16:17], v[40:41] op_sel_hi:[1,0]
	v_mfma_f32_32x32x16_bf16 v[0:15], v[124:127], v[34:37], v[0:15]
	v_fma_f32 v42, v42, s15, -v32
	v_exp_f32_e32 v42, v42
	v_fma_f32 v43, v43, s15, -v32
	v_exp_f32_e32 v43, v43
	v_fma_f32 v44, v44, s15, -v32
	v_add_f32_e32 v48, v179, v181
	v_exp_f32_e32 v44, v44
	v_mfma_f32_32x32x16_bf16 v[16:31], v[120:123], v[34:37], v[16:31]
	v_fma_f32 v34, v41, s15, -v32
	v_exp_f32_e32 v41, v34
	v_cvt_pk_bf16_f32 v34, v56, v57
	v_cvt_pk_bf16_f32 v35, v58, v59
	v_cvt_pk_bf16_f32 v36, v60, v61
	v_cvt_pk_bf16_f32 v37, v62, v63
	v_add_f32_e32 v48, v41, v48
	s_cmp_ge_u32 s0, s11
	v_mfma_f32_32x32x16_bf16 v[0:15], v[116:119], v[34:37], v[0:15]
	v_mfma_f32_32x32x16_bf16 v[16:31], v[112:115], v[34:37], v[16:31]
	v_add_f32_e32 v34, v42, v48
	v_add_f32_e32 v34, v43, v34
	v_add_f32_e32 v48, v44, v34
	v_cvt_pk_bf16_f32 v34, v176, v33
	v_cvt_pk_bf16_f32 v35, v177, v178
	v_cvt_pk_bf16_f32 v36, v180, v128
	v_cvt_pk_bf16_f32 v37, v38, v39
	v_fma_f32 v33, v45, s15, -v32
	v_pk_fma_f32 v[184:185], v[46:47], s[14:15], v[32:33] op_sel:[0,1,0] op_sel_hi:[1,1,0] neg_lo:[0,0,1] neg_hi:[0,0,1]
	v_mfma_f32_32x32x16_bf16 v[0:15], v[108:111], v[34:37], v[0:15]
	v_exp_f32_e32 v33, v33
	v_exp_f32_e32 v39, v184
	v_exp_f32_e32 v45, v185
	v_add_f32_e32 v38, v33, v48
	v_mfma_f32_32x32x16_bf16 v[16:31], v[104:107], v[34:37], v[16:31]
	v_add_f32_e32 v34, v39, v38
	v_cvt_pk_bf16_f32 v36, v179, v41
	v_cvt_pk_bf16_f32 v37, v42, v43
	v_cvt_pk_bf16_f32 v38, v44, v33
	v_cvt_pk_bf16_f32 v39, v39, v45
	v_add_f32_e32 v34, v45, v34
	ds_bpermute_b32 v35, v174, v34
	v_mfma_f32_32x32x16_bf16 v[0:15], v[100:103], v[36:39], v[0:15]
	s_waitcnt lgkmcnt(0)
	v_add_f32_e32 v34, v34, v35
	v_fmac_f32_e32 v34, v175, v40
	v_mfma_f32_32x32x16_bf16 v[16:31], v[96:99], v[36:39], v[16:31]
	s_cbranch_scc1 .LBB0_1659
; DI void phase_attn_swa(const Params& P, const float* sinks, bf16_t* og, unsigned char* smem, int L, int G) {
;     ...
;     for (int j = jlo; j <= jhi; ++j) {
;       const int key0 = j * 64, cb = (j - jlo) & 1;
;       __syncthreads();
;       if (j < jhi) kv64_store(R, sK + (cb ^ 1) * KVB64, sVt + (cb ^ 1) * KVB64, tid);
;       if (j + 1 < jhi) kv64_fetch(R, kb, 256, vb, SEQ, key0 + 128, true, tid);
;       __builtin_amdgcn_sched_barrier(0);
;       auto mf = [&](int kk) { const int key = key0 + kk; return key <= t && key > t - 128; };
;       attn_step<64, true, 0>(sK + cb * KVB64, sVt + cb * KVB64, qf, o0, o1, m, l, sc, mf, lane, s, 0.f);
;     }
	v_mov_b32_e32 v175, v34
	v_mov_b32_e32 v176, v32
	s_branch .LBB0_1668
